# all 16-byte stores before grid syncs made write-through (sc0 sc1) so the barrier L2 writeback has little left to flush
# baseline (speedup 1.0000x reference)
; __device__ __forceinline__ void phase_prologue(const Ctx& C) {
;     ...
; #pragma unroll 8
;         for (int k = kbeg; k < kbeg + 128; ++k) { const f32x4 w = *(const f32x4*)(wa + (size_t)k * NMOD);
; #pragma unroll
;             for (int b = 0; b < 8; ++b) acc[b] += w * sc[b * DM + k]; }
.LBB0_12:
	v_lshl_add_u64 v[40:41], v[38:39], 0, s[0:1]
	v_add_co_u32_e32 v42, vcc, s3, v40
	global_load_dwordx4 v[46:49], v[40:41], off
	s_nop 0
	v_addc_co_u32_e32 v43, vcc, 0, v41, vcc
	v_add_co_u32_e32 v114, vcc, s11, v40
	v_mov_b32_e32 v35, s10
	s_nop 0
	v_addc_co_u32_e32 v115, vcc, 0, v41, vcc
	v_add_co_u32_e32 v118, vcc, s12, v40
	ds_read_b128 v[50:53], v35
	ds_read_b128 v[54:57], v35 offset:16
	ds_read_b128 v[58:61], v35 offset:4096
	ds_read_b128 v[62:65], v35 offset:4112
	ds_read_b128 v[66:69], v35 offset:8192
	ds_read_b128 v[70:73], v35 offset:8208
	ds_read_b128 v[74:77], v35 offset:12288
	ds_read_b128 v[78:81], v35 offset:12304
	ds_read_b128 v[82:85], v35 offset:16384
	ds_read_b128 v[86:89], v35 offset:16400
	ds_read_b128 v[90:93], v35 offset:20480
	ds_read_b128 v[94:97], v35 offset:20496
	ds_read_b128 v[98:101], v35 offset:24576
	ds_read_b128 v[102:105], v35 offset:24592
	ds_read_b128 v[106:109], v35 offset:28672
	ds_read_b128 v[110:113], v35 offset:28688
	v_addc_co_u32_e32 v119, vcc, 0, v41, vcc
	v_add_co_u32_e32 v122, vcc, s13, v40
	s_waitcnt lgkmcnt(14)
	v_mov_b32_e32 v138, v53
	v_addc_co_u32_e32 v123, vcc, 0, v41, vcc
	v_add_co_u32_e32 v126, vcc, s14, v40
	s_waitcnt lgkmcnt(13)
	v_mov_b32_e32 v140, v61
	v_addc_co_u32_e32 v127, vcc, 0, v41, vcc
	v_add_co_u32_e32 v130, vcc, s15, v40
	s_waitcnt lgkmcnt(11)
	v_mov_b32_e32 v142, v69
	v_addc_co_u32_e32 v131, vcc, 0, v41, vcc
	v_add_co_u32_e32 v134, vcc, s16, v40
	s_waitcnt lgkmcnt(9)
	v_mov_b32_e32 v144, v77
	v_addc_co_u32_e32 v135, vcc, 0, v41, vcc
	global_load_dwordx4 v[40:43], v[42:43], off
	s_nop 0
	global_load_dwordx4 v[114:117], v[114:115], off
	s_nop 0
	global_load_dwordx4 v[118:121], v[118:119], off
	s_nop 0
	global_load_dwordx4 v[122:125], v[122:123], off
	s_nop 0
	global_load_dwordx4 v[126:129], v[126:127], off
	s_nop 0
	global_load_dwordx4 v[130:133], v[130:131], off
	s_nop 0
	global_load_dwordx4 v[134:137], v[134:135], off
	s_waitcnt lgkmcnt(7)
	v_mov_b32_e32 v146, v85
	s_waitcnt lgkmcnt(5)
	v_mov_b32_e32 v148, v93
	s_waitcnt lgkmcnt(3)
	v_mov_b32_e32 v150, v101
	s_waitcnt lgkmcnt(1)
	v_mov_b32_e32 v152, v109
	s_add_u32 s0, s0, 0x30000
	s_addc_u32 s1, s1, 0
	s_add_i32 s10, s10, 32
	v_mov_b32_e32 v154, v57
	v_mov_b32_e32 v156, v65
	v_mov_b32_e32 v158, v73
	v_mov_b32_e32 v160, v81
	v_mov_b32_e32 v164, v89
	v_mov_b32_e32 v166, v97
	v_mov_b32_e32 v168, v105
	s_waitcnt lgkmcnt(0)
	v_mov_b32_e32 v170, v113
	s_cmp_eq_u32 s0, 0x300000
	s_waitcnt vmcnt(7)
	v_pk_fma_f32 v[8:9], v[48:49], v[50:51], v[8:9] op_sel_hi:[1,0,1]
	v_pk_fma_f32 v[6:7], v[46:47], v[50:51], v[6:7] op_sel_hi:[1,0,1]
	v_pk_fma_f32 v[12:13], v[48:49], v[58:59], v[12:13] op_sel_hi:[1,0,1]
	v_pk_fma_f32 v[10:11], v[46:47], v[58:59], v[10:11] op_sel_hi:[1,0,1]
	v_pk_fma_f32 v[16:17], v[48:49], v[66:67], v[16:17] op_sel_hi:[1,0,1]
	v_pk_fma_f32 v[14:15], v[46:47], v[66:67], v[14:15] op_sel_hi:[1,0,1]
	v_pk_fma_f32 v[20:21], v[48:49], v[74:75], v[20:21] op_sel_hi:[1,0,1]
	v_pk_fma_f32 v[18:19], v[46:47], v[74:75], v[18:19] op_sel_hi:[1,0,1]
	v_pk_fma_f32 v[24:25], v[48:49], v[82:83], v[24:25] op_sel_hi:[1,0,1]
	v_pk_fma_f32 v[22:23], v[46:47], v[82:83], v[22:23] op_sel_hi:[1,0,1]
	v_pk_fma_f32 v[28:29], v[48:49], v[90:91], v[28:29] op_sel_hi:[1,0,1]
	v_pk_fma_f32 v[26:27], v[46:47], v[90:91], v[26:27] op_sel_hi:[1,0,1]
	v_pk_fma_f32 v[32:33], v[48:49], v[98:99], v[32:33] op_sel_hi:[1,0,1]
	v_pk_fma_f32 v[30:31], v[46:47], v[98:99], v[30:31] op_sel_hi:[1,0,1]
	v_pk_fma_f32 v[4:5], v[48:49], v[106:107], v[4:5] op_sel_hi:[1,0,1]
	v_pk_fma_f32 v[2:3], v[46:47], v[106:107], v[2:3] op_sel_hi:[1,0,1]
	s_waitcnt vmcnt(6)
	v_pk_fma_f32 v[6:7], v[40:41], v[50:51], v[6:7] op_sel:[0,1,0]
	v_pk_fma_f32 v[8:9], v[42:43], v[50:51], v[8:9] op_sel:[0,1,0]
	v_pk_fma_f32 v[10:11], v[40:41], v[58:59], v[10:11] op_sel:[0,1,0]
	v_pk_fma_f32 v[12:13], v[42:43], v[58:59], v[12:13] op_sel:[0,1,0]
	v_pk_fma_f32 v[14:15], v[40:41], v[66:67], v[14:15] op_sel:[0,1,0]
	v_pk_fma_f32 v[16:17], v[42:43], v[66:67], v[16:17] op_sel:[0,1,0]
	v_pk_fma_f32 v[18:19], v[40:41], v[74:75], v[18:19] op_sel:[0,1,0]
	v_pk_fma_f32 v[20:21], v[42:43], v[74:75], v[20:21] op_sel:[0,1,0]
	v_pk_fma_f32 v[22:23], v[40:41], v[82:83], v[22:23] op_sel:[0,1,0]
	v_pk_fma_f32 v[24:25], v[42:43], v[82:83], v[24:25] op_sel:[0,1,0]
	v_pk_fma_f32 v[26:27], v[40:41], v[90:91], v[26:27] op_sel:[0,1,0]
	v_pk_fma_f32 v[28:29], v[42:43], v[90:91], v[28:29] op_sel:[0,1,0]
	v_pk_fma_f32 v[30:31], v[40:41], v[98:99], v[30:31] op_sel:[0,1,0]
	v_pk_fma_f32 v[32:33], v[42:43], v[98:99], v[32:33] op_sel:[0,1,0]
	v_pk_fma_f32 v[2:3], v[40:41], v[106:107], v[2:3] op_sel:[0,1,0]
	v_pk_fma_f32 v[4:5], v[42:43], v[106:107], v[4:5] op_sel:[0,1,0]
	s_waitcnt vmcnt(5)
	v_pk_fma_f32 v[8:9], v[116:117], v[52:53], v[8:9] op_sel_hi:[1,0,1]
	v_pk_fma_f32 v[6:7], v[114:115], v[52:53], v[6:7] op_sel_hi:[1,0,1]
	v_pk_fma_f32 v[12:13], v[116:117], v[60:61], v[12:13] op_sel_hi:[1,0,1]
	v_pk_fma_f32 v[10:11], v[114:115], v[60:61], v[10:11] op_sel_hi:[1,0,1]
	v_pk_fma_f32 v[16:17], v[116:117], v[68:69], v[16:17] op_sel_hi:[1,0,1]
	v_pk_fma_f32 v[14:15], v[114:115], v[68:69], v[14:15] op_sel_hi:[1,0,1]
	v_pk_fma_f32 v[20:21], v[116:117], v[76:77], v[20:21] op_sel_hi:[1,0,1]
	v_pk_fma_f32 v[18:19], v[114:115], v[76:77], v[18:19] op_sel_hi:[1,0,1]
	v_pk_fma_f32 v[24:25], v[116:117], v[84:85], v[24:25] op_sel_hi:[1,0,1]
	v_pk_fma_f32 v[22:23], v[114:115], v[84:85], v[22:23] op_sel_hi:[1,0,1]
	v_pk_fma_f32 v[28:29], v[116:117], v[92:93], v[28:29] op_sel_hi:[1,0,1]
	v_pk_fma_f32 v[26:27], v[114:115], v[92:93], v[26:27] op_sel_hi:[1,0,1]
	v_pk_fma_f32 v[32:33], v[116:117], v[100:101], v[32:33] op_sel_hi:[1,0,1]
	v_pk_fma_f32 v[30:31], v[114:115], v[100:101], v[30:31] op_sel_hi:[1,0,1]
	v_pk_fma_f32 v[4:5], v[116:117], v[108:109], v[4:5] op_sel_hi:[1,0,1]
	v_pk_fma_f32 v[2:3], v[114:115], v[108:109], v[2:3] op_sel_hi:[1,0,1]
	s_waitcnt vmcnt(4)
; __device__ __forceinline__ void phase_prologue(const Ctx& C) {
;     ...
; #pragma unroll 8
;         for (int k = kbeg; k < kbeg + 128; ++k) { const f32x4 w = *(const f32x4*)(wa + (size_t)k * NMOD);
; #pragma unroll
;             for (int b = 0; b < 8; ++b) acc[b] += w * sc[b * DM + k]; }
	v_pk_fma_f32 v[8:9], v[120:121], v[138:139], v[8:9] op_sel_hi:[1,0,1]
	v_pk_fma_f32 v[6:7], v[118:119], v[138:139], v[6:7] op_sel_hi:[1,0,1]
	v_pk_fma_f32 v[12:13], v[120:121], v[140:141], v[12:13] op_sel_hi:[1,0,1]
	v_pk_fma_f32 v[10:11], v[118:119], v[140:141], v[10:11] op_sel_hi:[1,0,1]
	v_pk_fma_f32 v[16:17], v[120:121], v[142:143], v[16:17] op_sel_hi:[1,0,1]
	v_pk_fma_f32 v[14:15], v[118:119], v[142:143], v[14:15] op_sel_hi:[1,0,1]
	v_pk_fma_f32 v[20:21], v[120:121], v[144:145], v[20:21] op_sel_hi:[1,0,1]
	v_pk_fma_f32 v[18:19], v[118:119], v[144:145], v[18:19] op_sel_hi:[1,0,1]
	v_pk_fma_f32 v[24:25], v[120:121], v[146:147], v[24:25] op_sel_hi:[1,0,1]
	v_pk_fma_f32 v[22:23], v[118:119], v[146:147], v[22:23] op_sel_hi:[1,0,1]
	v_pk_fma_f32 v[28:29], v[120:121], v[148:149], v[28:29] op_sel_hi:[1,0,1]
	v_pk_fma_f32 v[26:27], v[118:119], v[148:149], v[26:27] op_sel_hi:[1,0,1]
	v_pk_fma_f32 v[32:33], v[120:121], v[150:151], v[32:33] op_sel_hi:[1,0,1]
	v_pk_fma_f32 v[30:31], v[118:119], v[150:151], v[30:31] op_sel_hi:[1,0,1]
	v_pk_fma_f32 v[4:5], v[120:121], v[152:153], v[4:5] op_sel_hi:[1,0,1]
	v_pk_fma_f32 v[2:3], v[118:119], v[152:153], v[2:3] op_sel_hi:[1,0,1]
	s_waitcnt vmcnt(3)
	v_pk_fma_f32 v[8:9], v[124:125], v[54:55], v[8:9] op_sel_hi:[1,0,1]
	v_pk_fma_f32 v[6:7], v[122:123], v[54:55], v[6:7] op_sel_hi:[1,0,1]
	v_pk_fma_f32 v[12:13], v[124:125], v[62:63], v[12:13] op_sel_hi:[1,0,1]
	v_pk_fma_f32 v[10:11], v[122:123], v[62:63], v[10:11] op_sel_hi:[1,0,1]
	v_pk_fma_f32 v[16:17], v[124:125], v[70:71], v[16:17] op_sel_hi:[1,0,1]
	v_pk_fma_f32 v[14:15], v[122:123], v[70:71], v[14:15] op_sel_hi:[1,0,1]
	v_pk_fma_f32 v[20:21], v[124:125], v[78:79], v[20:21] op_sel_hi:[1,0,1]
	v_pk_fma_f32 v[18:19], v[122:123], v[78:79], v[18:19] op_sel_hi:[1,0,1]
	v_pk_fma_f32 v[24:25], v[124:125], v[86:87], v[24:25] op_sel_hi:[1,0,1]
	v_pk_fma_f32 v[22:23], v[122:123], v[86:87], v[22:23] op_sel_hi:[1,0,1]
	v_pk_fma_f32 v[28:29], v[124:125], v[94:95], v[28:29] op_sel_hi:[1,0,1]
	v_pk_fma_f32 v[26:27], v[122:123], v[94:95], v[26:27] op_sel_hi:[1,0,1]
	v_pk_fma_f32 v[32:33], v[124:125], v[102:103], v[32:33] op_sel_hi:[1,0,1]
	v_pk_fma_f32 v[30:31], v[122:123], v[102:103], v[30:31] op_sel_hi:[1,0,1]
	v_pk_fma_f32 v[4:5], v[124:125], v[110:111], v[4:5] op_sel_hi:[1,0,1]
	v_pk_fma_f32 v[2:3], v[122:123], v[110:111], v[2:3] op_sel_hi:[1,0,1]
	s_waitcnt vmcnt(2)
	v_pk_fma_f32 v[8:9], v[128:129], v[54:55], v[8:9] op_sel:[0,1,0]
	v_pk_fma_f32 v[6:7], v[126:127], v[54:55], v[6:7] op_sel:[0,1,0]
	v_pk_fma_f32 v[12:13], v[128:129], v[62:63], v[12:13] op_sel:[0,1,0]
	v_pk_fma_f32 v[10:11], v[126:127], v[62:63], v[10:11] op_sel:[0,1,0]
	v_pk_fma_f32 v[16:17], v[128:129], v[70:71], v[16:17] op_sel:[0,1,0]
	v_pk_fma_f32 v[14:15], v[126:127], v[70:71], v[14:15] op_sel:[0,1,0]
	v_pk_fma_f32 v[20:21], v[128:129], v[78:79], v[20:21] op_sel:[0,1,0]
	v_pk_fma_f32 v[18:19], v[126:127], v[78:79], v[18:19] op_sel:[0,1,0]
	v_pk_fma_f32 v[24:25], v[128:129], v[86:87], v[24:25] op_sel:[0,1,0]
	v_pk_fma_f32 v[22:23], v[126:127], v[86:87], v[22:23] op_sel:[0,1,0]
	v_pk_fma_f32 v[28:29], v[128:129], v[94:95], v[28:29] op_sel:[0,1,0]
	v_pk_fma_f32 v[26:27], v[126:127], v[94:95], v[26:27] op_sel:[0,1,0]
	v_pk_fma_f32 v[32:33], v[128:129], v[102:103], v[32:33] op_sel:[0,1,0]
	v_pk_fma_f32 v[30:31], v[126:127], v[102:103], v[30:31] op_sel:[0,1,0]
	v_pk_fma_f32 v[4:5], v[128:129], v[110:111], v[4:5] op_sel:[0,1,0]
	v_pk_fma_f32 v[2:3], v[126:127], v[110:111], v[2:3] op_sel:[0,1,0]
	s_waitcnt vmcnt(1)
	v_pk_fma_f32 v[8:9], v[132:133], v[56:57], v[8:9] op_sel_hi:[1,0,1]
	v_pk_fma_f32 v[6:7], v[130:131], v[56:57], v[6:7] op_sel_hi:[1,0,1]
	v_pk_fma_f32 v[12:13], v[132:133], v[64:65], v[12:13] op_sel_hi:[1,0,1]
	v_pk_fma_f32 v[10:11], v[130:131], v[64:65], v[10:11] op_sel_hi:[1,0,1]
	v_pk_fma_f32 v[16:17], v[132:133], v[72:73], v[16:17] op_sel_hi:[1,0,1]
	v_pk_fma_f32 v[14:15], v[130:131], v[72:73], v[14:15] op_sel_hi:[1,0,1]
	v_pk_fma_f32 v[20:21], v[132:133], v[80:81], v[20:21] op_sel_hi:[1,0,1]
	v_pk_fma_f32 v[18:19], v[130:131], v[80:81], v[18:19] op_sel_hi:[1,0,1]
	v_pk_fma_f32 v[24:25], v[132:133], v[88:89], v[24:25] op_sel_hi:[1,0,1]
	v_pk_fma_f32 v[22:23], v[130:131], v[88:89], v[22:23] op_sel_hi:[1,0,1]
	v_pk_fma_f32 v[28:29], v[132:133], v[96:97], v[28:29] op_sel_hi:[1,0,1]
	v_pk_fma_f32 v[26:27], v[130:131], v[96:97], v[26:27] op_sel_hi:[1,0,1]
	v_pk_fma_f32 v[32:33], v[132:133], v[104:105], v[32:33] op_sel_hi:[1,0,1]
	v_pk_fma_f32 v[30:31], v[130:131], v[104:105], v[30:31] op_sel_hi:[1,0,1]
	v_pk_fma_f32 v[4:5], v[132:133], v[112:113], v[4:5] op_sel_hi:[1,0,1]
	v_pk_fma_f32 v[2:3], v[130:131], v[112:113], v[2:3] op_sel_hi:[1,0,1]
	s_waitcnt vmcnt(0)
	v_pk_fma_f32 v[8:9], v[136:137], v[154:155], v[8:9] op_sel_hi:[1,0,1]
	v_pk_fma_f32 v[6:7], v[134:135], v[154:155], v[6:7] op_sel_hi:[1,0,1]
	v_pk_fma_f32 v[12:13], v[136:137], v[156:157], v[12:13] op_sel_hi:[1,0,1]
	v_pk_fma_f32 v[10:11], v[134:135], v[156:157], v[10:11] op_sel_hi:[1,0,1]
	v_pk_fma_f32 v[16:17], v[136:137], v[158:159], v[16:17] op_sel_hi:[1,0,1]
	v_pk_fma_f32 v[14:15], v[134:135], v[158:159], v[14:15] op_sel_hi:[1,0,1]
	v_pk_fma_f32 v[20:21], v[136:137], v[160:161], v[20:21] op_sel_hi:[1,0,1]
	v_pk_fma_f32 v[18:19], v[134:135], v[160:161], v[18:19] op_sel_hi:[1,0,1]
	v_pk_fma_f32 v[24:25], v[136:137], v[164:165], v[24:25] op_sel_hi:[1,0,1]
	v_pk_fma_f32 v[22:23], v[134:135], v[164:165], v[22:23] op_sel_hi:[1,0,1]
	v_pk_fma_f32 v[28:29], v[136:137], v[166:167], v[28:29] op_sel_hi:[1,0,1]
	v_pk_fma_f32 v[26:27], v[134:135], v[166:167], v[26:27] op_sel_hi:[1,0,1]
	v_pk_fma_f32 v[32:33], v[136:137], v[168:169], v[32:33] op_sel_hi:[1,0,1]
	v_pk_fma_f32 v[30:31], v[134:135], v[168:169], v[30:31] op_sel_hi:[1,0,1]
	v_pk_fma_f32 v[4:5], v[136:137], v[170:171], v[4:5] op_sel_hi:[1,0,1]
	v_pk_fma_f32 v[2:3], v[134:135], v[170:171], v[2:3] op_sel_hi:[1,0,1]
	s_cbranch_scc0 .LBB0_12
; #define LAS __attribute__((address_space(3)))
; __device__ __forceinline__ void phase_prologue(const Ctx& C) {
;     ...
;         for (int b = 0; b < 8; ++b) *(LAS f32x4*)(red + (C.wave * 8 + b) * 256 + lane * 4) = acc[b];
;         __syncthreads();
;         { const int b = C.wave; f32x4 s = *(const f32x4*)(C.in[3] + (size_t)l * NMOD + n0);
; #pragma unroll
;           for (int w = 0; w < 8; ++w) s += *(LAS f32x4*)(red + (w * 8 + b) * 256 + lane * 4);
;           *(f32x4*)((float*)(ws_ + WS_MOD) + ((size_t)l * BATCH + b) * NMOD + n0) = s; }
;         __syncthreads();
	v_readlane_b32 s3, v254, 20
	s_lshl_b32 s0, s3, 13
	s_add_i32 s0, s0, 0
	v_lshlrev_b32_e32 v1, 2, v1
	v_readlane_b32 s64, v254, 4
	v_add_u32_e32 v35, s0, v1
	s_mul_i32 s0, s2, 0x6000
	v_readlane_b32 s70, v254, 10
	s_mul_hi_u32 s1, s2, 0x6000
	v_readlane_b32 s71, v254, 11
	s_add_u32 s0, s70, s0
	s_addc_u32 s1, s71, s1
	v_lshlrev_b64 v[40:41], 2, v[36:37]
	ds_write_b128 v35, v[6:9] offset:32768
	ds_write_b128 v35, v[10:13] offset:33792
	ds_write_b128 v35, v[14:17] offset:34816
	ds_write_b128 v35, v[18:21] offset:35840
	ds_write_b128 v35, v[22:25] offset:36864
	ds_write_b128 v35, v[26:29] offset:37888
	ds_write_b128 v35, v[30:33] offset:38912
	ds_write_b128 v35, v[2:5] offset:39936
	v_lshl_add_u64 v[2:3], s[0:1], 0, v[40:41]
	s_waitcnt lgkmcnt(0)
	s_barrier
	global_load_dwordx4 v[2:5], v[2:3], off
	s_lshl_b32 s0, s3, 10
	s_add_i32 s0, s0, 0
	v_add_u32_e32 v1, s0, v1
	ds_read_b128 v[6:9], v1 offset:32768
	ds_read_b128 v[10:13], v1 offset:40960
	ds_read_b128 v[14:17], v1 offset:49152
	ds_read_b128 v[18:21], v1 offset:57344
	s_lshl_b32 s1, s2, 3
	s_add_i32 s1, s1, s3
	v_add_u32_e32 v35, 0x8000, v1
	s_mul_hi_u32 s2, s1, 0x6000
	s_mulk_i32 s1, 0x6000
	ds_read_b128 v[22:25], v35 offset:32768
	ds_read_b128 v[26:29], v35 offset:40960
	ds_read_b128 v[30:33], v35 offset:49152
	ds_read_b128 v[36:39], v35 offset:57344
	s_add_u32 s0, s4, s1
	s_addc_u32 s1, s5, s2
	v_lshl_add_u64 v[40:41], s[0:1], 0, v[40:41]
	v_add_co_u32_e32 v40, vcc, 0x10000, v40
	v_readlane_b32 s65, v254, 5
	s_nop 0
	v_addc_co_u32_e32 v41, vcc, 0, v41, vcc
	v_readlane_b32 s66, v254, 6
	v_readlane_b32 s67, v254, 7
	v_readlane_b32 s68, v254, 8
	v_readlane_b32 s69, v254, 9
	v_readlane_b32 s72, v254, 12
	v_readlane_b32 s73, v254, 13
	v_readlane_b32 s74, v254, 14
	v_readlane_b32 s75, v254, 15
	v_readlane_b32 s76, v254, 16
	v_readlane_b32 s77, v254, 17
	v_readlane_b32 s78, v254, 18
	v_readlane_b32 s79, v254, 19
	s_waitcnt vmcnt(0) lgkmcnt(7)
	v_pk_add_f32 v[4:5], v[4:5], v[8:9]
	v_pk_add_f32 v[2:3], v[2:3], v[6:7]
	s_waitcnt lgkmcnt(6)
	v_pk_add_f32 v[4:5], v[4:5], v[12:13]
	v_pk_add_f32 v[2:3], v[2:3], v[10:11]
	s_waitcnt lgkmcnt(5)
	v_pk_add_f32 v[4:5], v[4:5], v[16:17]
	v_pk_add_f32 v[2:3], v[2:3], v[14:15]
	s_waitcnt lgkmcnt(4)
	v_pk_add_f32 v[4:5], v[4:5], v[20:21]
	v_pk_add_f32 v[2:3], v[2:3], v[18:19]
	s_waitcnt lgkmcnt(3)
	v_pk_add_f32 v[4:5], v[4:5], v[24:25]
	v_pk_add_f32 v[2:3], v[2:3], v[22:23]
	s_waitcnt lgkmcnt(2)
	v_pk_add_f32 v[4:5], v[4:5], v[28:29]
	v_pk_add_f32 v[2:3], v[2:3], v[26:27]
	s_waitcnt lgkmcnt(1)
	v_pk_add_f32 v[4:5], v[4:5], v[32:33]
	v_pk_add_f32 v[2:3], v[2:3], v[30:31]
	s_waitcnt lgkmcnt(0)
	v_pk_add_f32 v[4:5], v[4:5], v[38:39]
	v_pk_add_f32 v[2:3], v[2:3], v[36:37]
	flat_store_dwordx4 v[40:41], v[2:5] sc0 sc1
	s_waitcnt lgkmcnt(0)
	s_barrier

; #define LAS __attribute__((address_space(3)))
; __device__ __forceinline__ unsigned pk2(float lo, float hi) { return pg8::cvt_pk_bf16(lo, hi); }
; __device__ __forceinline__ void transpose_item(const float* W, int K, int N, bf16* WT, int row_off, LAS float* scr, int kb, int nb, int lane, const float* kscale = nullptr) {
;     const int k0 = 64 * kb, n0 = 32 * nb;
;     f32x4 v[8];
; #pragma unroll
;     for (int i = 0; i < 8; ++i) { v[i] = *(const f32x4*)(W + (size_t)(k0 + 8 * i + (lane >> 3)) * N + n0 + 4 * (lane & 7)); if (kscale) v[i] = v[i] * kscale[8 * i + (lane >> 3)]; }
; #pragma unroll
;     for (int i = 0; i < 8; ++i) { LAS float* d = scr + (8 * i + (lane >> 3)) * 33 + 4 * (lane & 7); d[0] = v[i].x; d[1] = v[i].y; d[2] = v[i].z; d[3] = v[i].w; }
;     asm volatile("s_waitcnt lgkmcnt(0)" ::: "memory");
;     const int c = lane & 7;
; #pragma unroll
;     for (int j = 0; j < 4; ++j) { const int n = (lane >> 3) + 8 * j; const LAS float* s = scr + (8 * c) * 33 + n;
;         u32x4 o; o.x = pk2(s[0 * 33], s[1 * 33]); o.y = pk2(s[2 * 33], s[3 * 33]); o.z = pk2(s[4 * 33], s[5 * 33]); o.w = pk2(s[6 * 33], s[7 * 33]);
;         *(u32x4*)(WT + (size_t)(row_off + n0 + n) * K + k0 + 8 * c) = o; }
;     asm volatile("s_waitcnt lgkmcnt(0)" ::: "memory");
; }
; __device__ __forceinline__ void phase_prologue(const Ctx& C) {
;     ...
;         if (r < I_IN) { const int kb = r / 96, nb = r % 96, seg = nb >> 4;
;             const int nseg = (seg == 2) ? 4 : (seg == 3) ? 2 : (seg == 4) ? 3 : seg;
;             transpose_item(C.in[4] + (size_t)l * DM * W_IN, DM, W_IN, (bf16*)((unsigned char*)wl + WO_IN), (nseg - seg) * 512, scr, kb, nb, lane); continue; }
.LBB0_19:
	v_readlane_b32 s64, v254, 4
	s_mul_i32 s4, s26, 0xc00000
	v_readlane_b32 s72, v254, 12
	s_sext_i32_i16 s2, s42
	s_mul_hi_i32 s3, s26, 0xc00000
	v_readlane_b32 s73, v254, 13
	s_add_u32 s42, s72, s4
	s_addc_u32 s3, s73, s3
	s_sub_i32 s4, s41, s27
	s_lshl_b32 s41, s4, 9
	s_lshl_b32 s4, s0, 5
	s_ashr_i32 s5, s4, 31
	s_lshl_b32 s2, s2, 6
	s_lshl_b64 s[26:27], s[4:5], 2
	s_add_u32 s26, s42, s26
	v_add_u32_e32 v32, s2, v34
	s_addc_u32 s27, s3, s27
	v_lshl_add_u64 v[30:31], s[26:27], 0, v[36:37]
	v_add_u32_e32 v4, 8, v32
	v_add_u32_e32 v10, 16, v32
	v_add_u32_e32 v12, 24, v32
	v_add_u32_e32 v18, 32, v32
	v_add_u32_e32 v20, 40, v32
	v_mad_i64_i32 v[2:3], s[26:27], v32, s38, v[30:31]
	v_mad_i64_i32 v[6:7], s[26:27], v4, s38, v[30:31]
	v_mad_i64_i32 v[10:11], s[26:27], v10, s38, v[30:31]
	v_mad_i64_i32 v[14:15], s[26:27], v12, s38, v[30:31]
	v_mad_i64_i32 v[18:19], s[26:27], v18, s38, v[30:31]
	v_mad_i64_i32 v[22:23], s[26:27], v20, s38, v[30:31]
	global_load_dwordx4 v[2:5], v[2:3], off
	s_nop 0
	global_load_dwordx4 v[6:9], v[6:7], off
	s_nop 0
	global_load_dwordx4 v[10:13], v[10:11], off
	s_nop 0
	global_load_dwordx4 v[14:17], v[14:15], off
	s_nop 0
	global_load_dwordx4 v[18:21], v[18:19], off
	s_nop 0
	global_load_dwordx4 v[22:25], v[22:23], off
	v_add_u32_e32 v26, 48, v32
	v_mad_i64_i32 v[26:27], s[26:27], v26, s38, v[30:31]
	global_load_dwordx4 v[26:29], v[26:27], off
	v_add_u32_e32 v32, 56, v32
	v_mad_i64_i32 v[30:31], s[26:27], v32, s38, v[30:31]
	global_load_dwordx4 v[30:33], v[30:31], off
	s_ashr_i32 s3, s2, 31
	s_add_i32 s41, s41, s4
	s_lshl_b64 s[2:3], s[2:3], 1
	v_add_u32_e32 v40, s41, v34
	s_add_u32 s2, s40, s2
	v_mov_b32_e32 v39, v37
	v_ashrrev_i32_e32 v41, 31, v40
	s_addc_u32 s3, s39, s3
	v_lshlrev_b64 v[40:41], 11, v[40:41]
	v_lshl_add_u64 v[64:65], s[2:3], 0, v[38:39]
	v_add_u32_e32 v62, s41, v1
	v_ashrrev_i32_e32 v63, 31, v62
	v_lshlrev_b64 v[62:63], 11, v[62:63]
	v_readlane_b32 s65, v254, 5
	v_readlane_b32 s66, v254, 6
	v_readlane_b32 s67, v254, 7
	v_readlane_b32 s68, v254, 8
	v_readlane_b32 s69, v254, 9
	v_readlane_b32 s70, v254, 10
	v_readlane_b32 s71, v254, 11
	v_readlane_b32 s74, v254, 14
	v_readlane_b32 s75, v254, 15
	v_readlane_b32 s76, v254, 16
	v_readlane_b32 s77, v254, 17
	v_readlane_b32 s78, v254, 18
	v_readlane_b32 s79, v254, 19
	s_waitcnt vmcnt(0)
	ds_write2_b32 v45, v2, v3 offset1:1
	ds_write2_b32 v45, v4, v5 offset0:2 offset1:3
	ds_write2_b32 v46, v6, v7 offset1:1
	ds_write2_b32 v47, v8, v9 offset1:1
	ds_write2_b32 v48, v10, v11 offset1:1
	ds_write2_b32 v49, v12, v13 offset1:1
	ds_write2_b32 v50, v14, v15 offset1:1
	ds_write2_b32 v51, v16, v17 offset1:1
	ds_write2_b32 v52, v18, v19 offset1:1
	ds_write2_b32 v53, v20, v21 offset1:1
	ds_write2_b32 v54, v22, v23 offset1:1
	ds_write2_b32 v55, v24, v25 offset1:1
	ds_write2_b32 v56, v26, v27 offset1:1
	ds_write2_b32 v57, v28, v29 offset1:1
	ds_write2_b32 v58, v30, v31 offset1:1
	ds_write2_b32 v59, v32, v33 offset1:1
	s_waitcnt lgkmcnt(0)
	ds_read_b32 v2, v44
	ds_read_b32 v3, v44 offset:132
	ds_read_b32 v4, v44 offset:264
	ds_read_b32 v5, v44 offset:396
	ds_read_b32 v8, v44 offset:528
	ds_read_b32 v9, v44 offset:660
	ds_read_b32 v10, v44 offset:792
	ds_read_b32 v11, v44 offset:924
	v_lshl_add_u64 v[6:7], v[64:65], 0, v[40:41]
	s_waitcnt lgkmcnt(0)
	v_cvt_pk_bf16_f32 v2, v2, v3
	v_cvt_pk_bf16_f32 v3, v4, v5
	v_cvt_pk_bf16_f32 v4, v8, v9
	v_cvt_pk_bf16_f32 v5, v10, v11
	flat_store_dwordx4 v[6:7], v[2:5] sc0 sc1
	ds_read_b32 v2, v44 offset:32
	ds_read_b32 v3, v44 offset:164
	ds_read_b32 v4, v44 offset:296
	ds_read_b32 v5, v44 offset:428
	ds_read_b32 v8, v44 offset:560
	ds_read_b32 v9, v44 offset:692
	ds_read_b32 v10, v44 offset:824
	ds_read_b32 v11, v44 offset:956
	v_lshl_add_u64 v[6:7], v[64:65], 0, v[62:63]
	s_waitcnt lgkmcnt(0)
	v_cvt_pk_bf16_f32 v2, v2, v3
	v_cvt_pk_bf16_f32 v3, v4, v5
	v_cvt_pk_bf16_f32 v4, v8, v9
	v_cvt_pk_bf16_f32 v5, v10, v11
	flat_store_dwordx4 v[6:7], v[2:5] sc0 sc1
	ds_read_b32 v2, v44 offset:64
	ds_read_b32 v3, v44 offset:196
	ds_read_b32 v4, v44 offset:328
	ds_read_b32 v5, v44 offset:460
	ds_read_b32 v6, v44 offset:592
	ds_read_b32 v7, v44 offset:724
	ds_read_b32 v8, v44 offset:856
	ds_read_b32 v9, v44 offset:988
	s_waitcnt lgkmcnt(0)
	v_cvt_pk_bf16_f32 v2, v2, v3
	v_cvt_pk_bf16_f32 v3, v4, v5
	v_cvt_pk_bf16_f32 v4, v6, v7
	v_add_u32_e32 v6, s41, v42
	v_ashrrev_i32_e32 v7, 31, v6
	v_lshlrev_b64 v[6:7], 11, v[6:7]
	v_cvt_pk_bf16_f32 v5, v8, v9
	v_lshl_add_u64 v[6:7], v[64:65], 0, v[6:7]
	flat_store_dwordx4 v[6:7], v[2:5] sc0 sc1
	ds_read_b32 v2, v44 offset:96
	ds_read_b32 v3, v44 offset:228
	ds_read_b32 v4, v44 offset:360
	ds_read_b32 v5, v44 offset:492
	ds_read_b32 v6, v44 offset:624
	ds_read_b32 v7, v44 offset:756
	ds_read_b32 v8, v44 offset:888
	ds_read_b32 v9, v44 offset:1020
	s_waitcnt lgkmcnt(0)
	v_cvt_pk_bf16_f32 v2, v2, v3
	v_cvt_pk_bf16_f32 v3, v4, v5
	v_cvt_pk_bf16_f32 v4, v6, v7
	v_add_u32_e32 v6, s41, v43
	v_ashrrev_i32_e32 v7, 31, v6
	v_lshlrev_b64 v[6:7], 11, v[6:7]
	v_cvt_pk_bf16_f32 v5, v8, v9
	v_lshl_add_u64 v[6:7], v[64:65], 0, v[6:7]
	flat_store_dwordx4 v[6:7], v[2:5] sc0 sc1
	s_waitcnt lgkmcnt(0)

; __device__ __forceinline__ void phase_prologue(const Ctx& C) {
;     ...
;     for (int it = gw; it < DEPTH * I_L; it += NGW) {
;         const int l = it / I_L; int r = it % I_L;
;         bf16* wl = (bf16*)(ws_ + WS_W + (size_t)l * WS_WL);
;         if (r < I_IN) { const int kb = r / 96, nb = r % 96, seg = nb >> 4;
;             const int nseg = (seg == 2) ? 4 : (seg == 3) ? 2 : (seg == 4) ? 3 : seg;
;             transpose_item(C.in[4] + (size_t)l * DM * W_IN, DM, W_IN, (bf16*)((unsigned char*)wl + WO_IN), (nseg - seg) * 512, scr, kb, nb, lane); continue; }
;         r -= I_IN;
;         if (r < I_OUT) { const int kb = r / 32, k0 = 64 * kb;
;             transpose_item(C.in[8] + (size_t)l * DM * DM, DM, DM, (bf16*)((unsigned char*)wl + WO_OUT), 0, scr, kb, r % 32, lane, k0 < 512 ? C.in[6] + (size_t)l * 512 + k0 : C.in[7] + (size_t)l * 512 + (k0 - 512)); continue; }
;         r -= I_OUT;
;         if (r < I_UP) { const int kb = r / 176, nb = r % 176, n0 = 32 * nb, isv = n0 >= DFF ? 1 : 0, j0 = n0 - DFF * isv;
;             transpose_item(C.in[9] + (size_t)l * DM * NUP, DM, NUP, (bf16*)((unsigned char*)wl + WO_UP), 256 * (j0 >> 7) + 128 * isv + (j0 & 127) - n0, scr, kb, nb, lane); continue; }
;         r -= I_UP;
;         transpose_item(C.in[12] + (size_t)l * DFF * DM, DFF, DM, (bf16*)((unsigned char*)wl + WO_DOWN), 0, scr, r / 32, r % 32, lane);
.LBB0_21:
	s_mul_hi_i32 s0, s16, 0x5397829d
	s_lshr_b32 s2, s0, 31
	s_ashr_i32 s0, s0, 11
	s_add_i32 s26, s0, s2
	s_mul_i32 s0, s26, 0xffffe780
	s_add_i32 s41, s16, s0
	s_ashr_i32 s27, s26, 31
	s_mul_i32 s2, s26, 0x1900000
	s_mul_hi_i32 s0, s26, 0x1900000
	s_add_u32 s40, s18, s2
	s_addc_u32 s39, s19, s0
	s_cmpk_gt_i32 s41, 0x5ff
	s_mov_b64 s[2:3], -1
	s_cbranch_scc0 .LBB0_47
	s_cmpk_gt_u32 s41, 0x7ff
	s_cbranch_scc0 .LBB0_28
	s_cmpk_gt_u32 s41, 0x12ff
	s_cbranch_scc0 .LBB0_25
	s_mul_i32 s2, s26, 0xb00000
	s_mul_hi_i32 s0, s26, 0xb00000
	s_add_u32 s3, s56, s2
	s_addc_u32 s5, s57, s0
	s_mul_i32 s0, s26, 0xffffcf00
	s_add_i32 s0, s22, s0
	s_and_b32 s0, s0, 0x7fffffc0
	s_and_b32 s2, s20, 0x3e0
	s_addk_i32 s0, 0xda00
	s_lshl_b32 s4, s2, 2
	v_add_u32_e32 v2, s0, v34
	s_add_u32 s4, s3, s4
	s_addc_u32 s5, s5, 0
	v_ashrrev_i32_e32 v3, 31, v2
	v_lshl_add_u64 v[4:5], s[4:5], 0, v[36:37]
	v_lshlrev_b64 v[2:3], 12, v[2:3]
	v_lshl_add_u64 v[30:31], v[4:5], 0, v[2:3]
	v_add_co_u32_e32 v6, vcc, s28, v30
	s_lshl_b64 s[4:5], s[0:1], 1
	s_nop 0
	v_addc_co_u32_e32 v7, vcc, 0, v31, vcc
	v_add_co_u32_e32 v10, vcc, s29, v30
	global_load_dwordx4 v[2:5], v[30:31], off
	s_nop 0
	global_load_dwordx4 v[6:9], v[6:7], off
	v_addc_co_u32_e32 v11, vcc, 0, v31, vcc
	v_add_co_u32_e32 v14, vcc, s30, v30
	s_add_u32 s4, s40, s4
	s_nop 0
	v_addc_co_u32_e32 v15, vcc, 0, v31, vcc
	v_add_co_u32_e32 v18, vcc, s31, v30
	global_load_dwordx4 v[10:13], v[10:11], off
	s_nop 0
	global_load_dwordx4 v[14:17], v[14:15], off
	v_addc_co_u32_e32 v19, vcc, 0, v31, vcc
	v_add_co_u32_e32 v22, vcc, s33, v30
	v_mov_b32_e32 v39, v37
	s_nop 0
	v_addc_co_u32_e32 v23, vcc, 0, v31, vcc
	global_load_dwordx4 v[18:21], v[18:19], off
	s_nop 0
	global_load_dwordx4 v[22:25], v[22:23], off
	v_add_co_u32_e32 v26, vcc, s34, v30
	s_addc_u32 s5, s39, s5
	s_nop 0
	v_addc_co_u32_e32 v27, vcc, 0, v31, vcc
	global_load_dwordx4 v[26:29], v[26:27], off
	v_add_co_u32_e32 v30, vcc, s35, v30
	v_lshl_add_u64 v[40:41], s[4:5], 0, v[38:39]
	s_nop 0
	v_addc_co_u32_e32 v31, vcc, 0, v31, vcc
	global_load_dwordx4 v[30:33], v[30:31], off
	v_add_u32_e32 v61, s2, v34
	v_lshl_add_u64 v[40:41], v[40:41], 0, s[10:11]
	s_waitcnt vmcnt(0)
	ds_write2_b32 v45, v2, v3 offset1:1
	ds_write2_b32 v45, v4, v5 offset0:2 offset1:3
	ds_write2_b32 v46, v6, v7 offset1:1
	ds_write2_b32 v47, v8, v9 offset1:1
	ds_write2_b32 v48, v10, v11 offset1:1
	ds_write2_b32 v49, v12, v13 offset1:1
	ds_write2_b32 v50, v14, v15 offset1:1
	ds_write2_b32 v51, v16, v17 offset1:1
	ds_write2_b32 v52, v18, v19 offset1:1
	ds_write2_b32 v53, v20, v21 offset1:1
	ds_write2_b32 v54, v22, v23 offset1:1
	ds_write2_b32 v55, v24, v25 offset1:1
	ds_write2_b32 v56, v26, v27 offset1:1
	ds_write2_b32 v57, v28, v29 offset1:1
	ds_write2_b32 v58, v30, v31 offset1:1
	ds_write2_b32 v59, v32, v33 offset1:1
	s_waitcnt lgkmcnt(0)
	ds_read_b32 v2, v44
	ds_read_b32 v3, v44 offset:132
	ds_read_b32 v4, v44 offset:264
	ds_read_b32 v5, v44 offset:396
	ds_read_b32 v8, v44 offset:528
	ds_read_b32 v9, v44 offset:660
	ds_read_b32 v10, v44 offset:792
	ds_read_b32 v11, v44 offset:924
	v_mad_i64_i32 v[6:7], s[4:5], v61, s36, v[40:41]
	s_waitcnt lgkmcnt(0)
	v_cvt_pk_bf16_f32 v2, v2, v3
	v_cvt_pk_bf16_f32 v3, v4, v5
	v_cvt_pk_bf16_f32 v4, v8, v9
	v_cvt_pk_bf16_f32 v5, v10, v11
	flat_store_dwordx4 v[6:7], v[2:5] sc0 sc1
	ds_read_b32 v2, v44 offset:32
	ds_read_b32 v3, v44 offset:164
	ds_read_b32 v4, v44 offset:296
	ds_read_b32 v5, v44 offset:428
	ds_read_b32 v6, v44 offset:560
	ds_read_b32 v7, v44 offset:692
	ds_read_b32 v8, v44 offset:824
	ds_read_b32 v9, v44 offset:956
	v_add_u32_e32 v10, s2, v1
	s_waitcnt lgkmcnt(0)
	v_cvt_pk_bf16_f32 v2, v2, v3
	v_cvt_pk_bf16_f32 v3, v4, v5
	v_cvt_pk_bf16_f32 v4, v6, v7
	v_cvt_pk_bf16_f32 v5, v8, v9
	v_mad_i64_i32 v[6:7], s[4:5], v10, s36, v[40:41]
	flat_store_dwordx4 v[6:7], v[2:5] sc0 sc1
	ds_read_b32 v2, v44 offset:64
	ds_read_b32 v3, v44 offset:196
	ds_read_b32 v4, v44 offset:328
	ds_read_b32 v5, v44 offset:460
	ds_read_b32 v6, v44 offset:592
	ds_read_b32 v7, v44 offset:724
	ds_read_b32 v8, v44 offset:856
	ds_read_b32 v9, v44 offset:988
	s_waitcnt lgkmcnt(0)
	v_cvt_pk_bf16_f32 v2, v2, v3
	v_cvt_pk_bf16_f32 v3, v4, v5
	v_cvt_pk_bf16_f32 v4, v6, v7
	v_add_u32_e32 v6, s2, v42
	v_cvt_pk_bf16_f32 v5, v8, v9
	v_mad_i64_i32 v[6:7], s[4:5], v6, s36, v[40:41]
	flat_store_dwordx4 v[6:7], v[2:5] sc0 sc1
	ds_read_b32 v2, v44 offset:96
	ds_read_b32 v3, v44 offset:228
	ds_read_b32 v4, v44 offset:360
	ds_read_b32 v5, v44 offset:492
	ds_read_b32 v6, v44 offset:624
	ds_read_b32 v7, v44 offset:756
	ds_read_b32 v8, v44 offset:888
	ds_read_b32 v9, v44 offset:1020
	s_waitcnt lgkmcnt(0)
	v_cvt_pk_bf16_f32 v2, v2, v3
	v_cvt_pk_bf16_f32 v3, v4, v5
	v_cvt_pk_bf16_f32 v4, v6, v7
	v_add_u32_e32 v6, s2, v43
	v_cvt_pk_bf16_f32 v5, v8, v9
	v_mad_i64_i32 v[6:7], s[2:3], v6, s36, v[40:41]
	flat_store_dwordx4 v[6:7], v[2:5] sc0 sc1
	s_waitcnt lgkmcnt(0)
	s_mov_b64 s[2:3], 0
; #define LAS __attribute__((address_space(3)))
; __device__ __forceinline__ unsigned pk2(float lo, float hi) { return pg8::cvt_pk_bf16(lo, hi); }
; __device__ __forceinline__ void transpose_item(const float* W, int K, int N, bf16* WT, int row_off, LAS float* scr, int kb, int nb, int lane, const float* kscale = nullptr) {
;     const int k0 = 64 * kb, n0 = 32 * nb;
;     f32x4 v[8];
; #pragma unroll
;     for (int i = 0; i < 8; ++i) { v[i] = *(const f32x4*)(W + (size_t)(k0 + 8 * i + (lane >> 3)) * N + n0 + 4 * (lane & 7)); if (kscale) v[i] = v[i] * kscale[8 * i + (lane >> 3)]; }
; #pragma unroll
;     for (int i = 0; i < 8; ++i) { LAS float* d = scr + (8 * i + (lane >> 3)) * 33 + 4 * (lane & 7); d[0] = v[i].x; d[1] = v[i].y; d[2] = v[i].z; d[3] = v[i].w; }
;     asm volatile("s_waitcnt lgkmcnt(0)" ::: "memory");
;     const int c = lane & 7;
; #pragma unroll
;     for (int j = 0; j < 4; ++j) { const int n = (lane >> 3) + 8 * j; const LAS float* s = scr + (8 * c) * 33 + n;
;         u32x4 o; o.x = pk2(s[0 * 33], s[1 * 33]); o.y = pk2(s[2 * 33], s[3 * 33]); o.z = pk2(s[4 * 33], s[5 * 33]); o.w = pk2(s[6 * 33], s[7 * 33]);
;         *(u32x4*)(WT + (size_t)(row_off + n0 + n) * K + k0 + 8 * c) = o; }
;     asm volatile("s_waitcnt lgkmcnt(0)" ::: "memory");
; }
; __device__ __forceinline__ void phase_prologue(const Ctx& C) {
;     ...
;         if (r < I_UP) { const int kb = r / 176, nb = r % 176, n0 = 32 * nb, isv = n0 >= DFF ? 1 : 0, j0 = n0 - DFF * isv;
;             transpose_item(C.in[9] + (size_t)l * DM * NUP, DM, NUP, (bf16*)((unsigned char*)wl + WO_UP), 256 * (j0 >> 7) + 128 * isv + (j0 & 127) - n0, scr, kb, nb, lane); continue; }
.LBB0_25:
	s_andn2_b64 vcc, exec, s[2:3]
	s_cbranch_vccnz .LBB0_27
	s_add_i32 s0, s41, 0xf800
	s_and_b32 s2, s0, 0xffff
	s_mul_i32 s2, s2, 0xba2f
	s_lshr_b32 s4, s2, 23
	s_mul_i32 s2, s4, 0xb0
	s_sub_i32 s0, s0, s2
	s_lshl_b32 s2, s0, 5
	s_and_b32 s3, s2, 0xffe0
	s_and_b32 s0, s0, 0xffff
	s_cmpk_gt_u32 s0, 0x57
	s_cselect_b32 s0, 0xfffff500, 0
	s_mul_i32 s42, s26, 0x1600000
	s_cselect_b32 s43, 0x80, 0
	s_add_i32 s0, s0, s3
	s_mul_hi_i32 s5, s26, 0x1600000
	s_add_u32 s42, s50, s42
	s_addc_u32 s5, s51, s5
	s_lshl_b32 s0, s0, 1
	s_and_b32 s2, s2, 0x60
	s_and_b32 s0, s0, 0xffffff00
	s_or_b32 s2, s2, s43
	s_or_b32 s0, s2, s0
	s_lshl_b32 s2, s3, 2
	s_add_u32 s2, s42, s2
	v_lshl_add_u32 v32, s4, 6, v34
	s_addc_u32 s3, s5, 0
	v_lshl_add_u64 v[30:31], s[2:3], 0, v[36:37]
	v_add_u32_e32 v4, 8, v32
	v_add_u32_e32 v10, 16, v32
	v_add_u32_e32 v12, 24, v32
	v_add_u32_e32 v18, 32, v32
	v_add_u32_e32 v20, 40, v32
	v_mad_i64_i32 v[2:3], s[2:3], v32, s37, v[30:31]
	v_mad_i64_i32 v[6:7], s[2:3], v4, s37, v[30:31]
	v_mad_i64_i32 v[10:11], s[2:3], v10, s37, v[30:31]
	v_mad_i64_i32 v[14:15], s[2:3], v12, s37, v[30:31]
	v_mad_i64_i32 v[18:19], s[2:3], v18, s37, v[30:31]
	v_mad_i64_i32 v[22:23], s[2:3], v20, s37, v[30:31]
	global_load_dwordx4 v[2:5], v[2:3], off
	s_nop 0
	global_load_dwordx4 v[6:9], v[6:7], off
	s_nop 0
	global_load_dwordx4 v[10:13], v[10:11], off
	s_nop 0
	global_load_dwordx4 v[14:17], v[14:15], off
	s_nop 0
	global_load_dwordx4 v[18:21], v[18:19], off
	s_nop 0
	global_load_dwordx4 v[22:25], v[22:23], off
	v_add_u32_e32 v26, 48, v32
	v_mad_i64_i32 v[26:27], s[2:3], v26, s37, v[30:31]
	global_load_dwordx4 v[26:29], v[26:27], off
	v_add_u32_e32 v32, 56, v32
	v_mad_i64_i32 v[30:31], s[2:3], v32, s37, v[30:31]
	global_load_dwordx4 v[30:33], v[30:31], off
	s_lshl_b32 s2, s4, 7
	s_add_u32 s2, s40, s2
	v_mov_b32_e32 v39, v37
	v_add_u32_e32 v40, s0, v34
	s_addc_u32 s3, s39, 0
	v_ashrrev_i32_e32 v41, 31, v40
	v_lshl_add_u64 v[64:65], s[2:3], 0, v[38:39]
	v_lshlrev_b64 v[40:41], 11, v[40:41]
	v_lshl_add_u64 v[64:65], v[64:65], 0, s[12:13]
	v_add_u32_e32 v62, s0, v1
	v_ashrrev_i32_e32 v63, 31, v62
	v_lshlrev_b64 v[62:63], 11, v[62:63]
	s_waitcnt vmcnt(0)
	ds_write2_b32 v45, v2, v3 offset1:1
	ds_write2_b32 v45, v4, v5 offset0:2 offset1:3
	ds_write2_b32 v46, v6, v7 offset1:1
	ds_write2_b32 v47, v8, v9 offset1:1
	ds_write2_b32 v48, v10, v11 offset1:1
	ds_write2_b32 v49, v12, v13 offset1:1
	ds_write2_b32 v50, v14, v15 offset1:1
	ds_write2_b32 v51, v16, v17 offset1:1
	ds_write2_b32 v52, v18, v19 offset1:1
	ds_write2_b32 v53, v20, v21 offset1:1
	ds_write2_b32 v54, v22, v23 offset1:1
	ds_write2_b32 v55, v24, v25 offset1:1
	ds_write2_b32 v56, v26, v27 offset1:1
	ds_write2_b32 v57, v28, v29 offset1:1
	ds_write2_b32 v58, v30, v31 offset1:1
	ds_write2_b32 v59, v32, v33 offset1:1
	s_waitcnt lgkmcnt(0)
	ds_read_b32 v2, v44
	ds_read_b32 v3, v44 offset:132
	ds_read_b32 v4, v44 offset:264
	ds_read_b32 v5, v44 offset:396
	ds_read_b32 v8, v44 offset:528
	ds_read_b32 v9, v44 offset:660
	ds_read_b32 v10, v44 offset:792
	ds_read_b32 v11, v44 offset:924
	v_lshl_add_u64 v[6:7], v[64:65], 0, v[40:41]
	s_waitcnt lgkmcnt(0)
	v_cvt_pk_bf16_f32 v2, v2, v3
	v_cvt_pk_bf16_f32 v3, v4, v5
	v_cvt_pk_bf16_f32 v4, v8, v9
	v_cvt_pk_bf16_f32 v5, v10, v11
	flat_store_dwordx4 v[6:7], v[2:5] sc0 sc1
	ds_read_b32 v2, v44 offset:32
	ds_read_b32 v3, v44 offset:164
	ds_read_b32 v4, v44 offset:296
	ds_read_b32 v5, v44 offset:428
	ds_read_b32 v8, v44 offset:560
	ds_read_b32 v9, v44 offset:692
	ds_read_b32 v10, v44 offset:824
	ds_read_b32 v11, v44 offset:956
	v_lshl_add_u64 v[6:7], v[64:65], 0, v[62:63]
	s_waitcnt lgkmcnt(0)
	v_cvt_pk_bf16_f32 v2, v2, v3
	v_cvt_pk_bf16_f32 v3, v4, v5
	v_cvt_pk_bf16_f32 v4, v8, v9
	v_cvt_pk_bf16_f32 v5, v10, v11
	flat_store_dwordx4 v[6:7], v[2:5] sc0 sc1
	ds_read_b32 v2, v44 offset:64
	ds_read_b32 v3, v44 offset:196
	ds_read_b32 v4, v44 offset:328
	ds_read_b32 v5, v44 offset:460
	ds_read_b32 v6, v44 offset:592
	ds_read_b32 v7, v44 offset:724
	ds_read_b32 v8, v44 offset:856
	ds_read_b32 v9, v44 offset:988
	s_waitcnt lgkmcnt(0)
	v_cvt_pk_bf16_f32 v2, v2, v3
	v_cvt_pk_bf16_f32 v3, v4, v5
	v_cvt_pk_bf16_f32 v4, v6, v7
	v_add_u32_e32 v6, s0, v42
	v_ashrrev_i32_e32 v7, 31, v6
	v_lshlrev_b64 v[6:7], 11, v[6:7]
	v_cvt_pk_bf16_f32 v5, v8, v9
	v_lshl_add_u64 v[6:7], v[64:65], 0, v[6:7]
	flat_store_dwordx4 v[6:7], v[2:5] sc0 sc1
	ds_read_b32 v2, v44 offset:96
	ds_read_b32 v3, v44 offset:228
	ds_read_b32 v4, v44 offset:360
	ds_read_b32 v5, v44 offset:492
	ds_read_b32 v6, v44 offset:624
	ds_read_b32 v7, v44 offset:756
	ds_read_b32 v8, v44 offset:888
	ds_read_b32 v9, v44 offset:1020
	s_waitcnt lgkmcnt(0)
	v_cvt_pk_bf16_f32 v2, v2, v3
	v_cvt_pk_bf16_f32 v3, v4, v5
	v_cvt_pk_bf16_f32 v4, v6, v7
	v_add_u32_e32 v6, s0, v43
	v_ashrrev_i32_e32 v7, 31, v6
	v_lshlrev_b64 v[6:7], 11, v[6:7]
	v_cvt_pk_bf16_f32 v5, v8, v9
	v_lshl_add_u64 v[6:7], v[64:65], 0, v[6:7]
	flat_store_dwordx4 v[6:7], v[2:5] sc0 sc1
	s_waitcnt lgkmcnt(0)

; #define LAS __attribute__((address_space(3)))
; __device__ __forceinline__ unsigned pk2(float lo, float hi) { return pg8::cvt_pk_bf16(lo, hi); }
; __device__ __forceinline__ void transpose_item(const float* W, int K, int N, bf16* WT, int row_off, LAS float* scr, int kb, int nb, int lane, const float* kscale = nullptr) {
;     ...
;     for (int i = 0; i < 8; ++i) { LAS float* d = scr + (8 * i + (lane >> 3)) * 33 + 4 * (lane & 7); d[0] = v[i].x; d[1] = v[i].y; d[2] = v[i].z; d[3] = v[i].w; }
;     asm volatile("s_waitcnt lgkmcnt(0)" ::: "memory");
;     const int c = lane & 7;
; #pragma unroll
;     for (int j = 0; j < 4; ++j) { const int n = (lane >> 3) + 8 * j; const LAS float* s = scr + (8 * c) * 33 + n;
;         u32x4 o; o.x = pk2(s[0 * 33], s[1 * 33]); o.y = pk2(s[2 * 33], s[3 * 33]); o.z = pk2(s[4 * 33], s[5 * 33]); o.w = pk2(s[6 * 33], s[7 * 33]);
;         *(u32x4*)(WT + (size_t)(row_off + n0 + n) * K + k0 + 8 * c) = o; }
;     asm volatile("s_waitcnt lgkmcnt(0)" ::: "memory");
.LBB0_45:
	s_waitcnt vmcnt(0)
	ds_write2_b32 v45, v2, v3 offset1:1
	ds_write2_b32 v45, v4, v5 offset0:2 offset1:3
	ds_write2_b32 v46, v6, v7 offset1:1
	ds_write2_b32 v47, v8, v9 offset1:1
	ds_write2_b32 v48, v10, v11 offset1:1
	ds_write2_b32 v49, v12, v13 offset1:1
	ds_write2_b32 v50, v14, v15 offset1:1
	ds_write2_b32 v51, v16, v17 offset1:1
	ds_write2_b32 v52, v18, v19 offset1:1
	ds_write2_b32 v53, v20, v21 offset1:1
	ds_write2_b32 v54, v22, v23 offset1:1
	ds_write2_b32 v55, v24, v25 offset1:1
	ds_write2_b32 v56, v26, v27 offset1:1
	ds_write2_b32 v57, v28, v29 offset1:1
	ds_write2_b32 v60, v30, v31 offset1:1
	ds_write2_b32 v60, v32, v33 offset0:2 offset1:3
	s_lshl_b64 s[2:3], s[0:1], 1
	s_waitcnt lgkmcnt(0)
	s_add_u32 s2, s40, s2
	s_addc_u32 s3, s39, s3
	v_mov_b32_e32 v39, v37
	ds_read_b32 v4, v44
	ds_read_b32 v5, v44 offset:132
	ds_read_b32 v8, v44 offset:264
	ds_read_b32 v9, v44 offset:396
	ds_read_b32 v10, v44 offset:528
	ds_read_b32 v11, v44 offset:660
	ds_read_b32 v12, v44 offset:792
	ds_read_b32 v13, v44 offset:924
	v_lshl_add_u64 v[2:3], s[2:3], 0, v[38:39]
	v_lshl_add_u64 v[6:7], v[2:3], 0, s[14:15]
	s_waitcnt lgkmcnt(0)
	v_cvt_pk_bf16_f32 v3, v8, v9
	v_add_u32_e32 v8, s27, v34
	v_ashrrev_i32_e32 v9, 31, v8
	v_lshlrev_b64 v[8:9], 11, v[8:9]
	v_cvt_pk_bf16_f32 v2, v4, v5
	v_cvt_pk_bf16_f32 v4, v10, v11
	v_cvt_pk_bf16_f32 v5, v12, v13
	v_lshl_add_u64 v[8:9], v[6:7], 0, v[8:9]
	flat_store_dwordx4 v[8:9], v[2:5] sc0 sc1
	ds_read_b32 v2, v44 offset:32
	ds_read_b32 v3, v44 offset:164
	ds_read_b32 v4, v44 offset:296
	ds_read_b32 v5, v44 offset:428
	ds_read_b32 v8, v44 offset:560
	ds_read_b32 v9, v44 offset:692
	ds_read_b32 v10, v44 offset:824
	ds_read_b32 v11, v44 offset:956
	s_waitcnt lgkmcnt(0)
	v_cvt_pk_bf16_f32 v2, v2, v3
	v_cvt_pk_bf16_f32 v3, v4, v5
	v_cvt_pk_bf16_f32 v4, v8, v9
	v_add_u32_e32 v8, s27, v1
	v_ashrrev_i32_e32 v9, 31, v8
	v_lshlrev_b64 v[8:9], 11, v[8:9]
	v_cvt_pk_bf16_f32 v5, v10, v11
	v_lshl_add_u64 v[8:9], v[6:7], 0, v[8:9]
	flat_store_dwordx4 v[8:9], v[2:5] sc0 sc1
	ds_read_b32 v2, v44 offset:64
	ds_read_b32 v3, v44 offset:196
	ds_read_b32 v4, v44 offset:328
	ds_read_b32 v5, v44 offset:460
	ds_read_b32 v8, v44 offset:592
	ds_read_b32 v9, v44 offset:724
	ds_read_b32 v10, v44 offset:856
	ds_read_b32 v11, v44 offset:988
	s_waitcnt lgkmcnt(0)
	v_cvt_pk_bf16_f32 v2, v2, v3
	v_cvt_pk_bf16_f32 v3, v4, v5
	v_cvt_pk_bf16_f32 v4, v8, v9
	v_add_u32_e32 v8, s27, v42
	v_ashrrev_i32_e32 v9, 31, v8
	v_lshlrev_b64 v[8:9], 11, v[8:9]
	v_cvt_pk_bf16_f32 v5, v10, v11
	v_lshl_add_u64 v[8:9], v[6:7], 0, v[8:9]
	flat_store_dwordx4 v[8:9], v[2:5] sc0 sc1
	ds_read_b32 v2, v44 offset:96
	ds_read_b32 v3, v44 offset:228
	ds_read_b32 v4, v44 offset:360
	ds_read_b32 v5, v44 offset:492
	ds_read_b32 v8, v44 offset:624
	ds_read_b32 v9, v44 offset:756
	ds_read_b32 v10, v44 offset:888
	ds_read_b32 v11, v44 offset:1020
	s_waitcnt lgkmcnt(0)
	v_cvt_pk_bf16_f32 v2, v2, v3
	v_cvt_pk_bf16_f32 v3, v4, v5
	v_cvt_pk_bf16_f32 v4, v8, v9
	v_add_u32_e32 v8, s27, v43
	v_ashrrev_i32_e32 v9, 31, v8
	v_lshlrev_b64 v[8:9], 11, v[8:9]
	v_cvt_pk_bf16_f32 v5, v10, v11
	v_lshl_add_u64 v[6:7], v[6:7], 0, v[8:9]
	flat_store_dwordx4 v[6:7], v[2:5] sc0 sc1
	s_waitcnt lgkmcnt(0)

; __device__ __forceinline__ void unpack8(const u32x4 w, f32x4& a, f32x4& c) { a = (f32x4){bf_lo(w.x), bf_hi(w.x), bf_lo(w.y), bf_hi(w.y)}; c = (f32x4){bf_lo(w.z), bf_hi(w.z), bf_lo(w.w), bf_hi(w.w)}; }
; template <bool X_F32> __device__ __forceinline__ void phase_norm_mod(const Ctx& C, const void* xin, const float* modl, int shift_idx, int scale_idx) {
;     ...
;         for (int r0_ = (gw % (NGW >> 3)) * NR; r0_ < T / 8; r0_ += (NGW >> 3) * NR) { const int m0 = (gw / (NGW >> 3)) * (T / 8) + r0_;
;             const int b = m0 >> 12;
;             u32x4 raw[NR][2]; float s[NR];
; #pragma unroll
;             for (int r = 0; r < NR; ++r)
; #pragma unroll
;                 for (int j = 0; j < 2; ++j) raw[r][j] = ((const u32x4*)((const bf16*)xin + (size_t)(m0 + r) * DM + 512 * j))[lane];
; #pragma unroll
;             for (int r = 0; r < NR; ++r) { s[r] = 0.f;
; #pragma unroll
;                 for (int j = 0; j < 2; ++j) { f32x4 t0, t1; unpack8(raw[r][j], t0, t1);
;                     s[r] += ((t0.x * t0.x + t0.y * t0.y) + (t0.z * t0.z + t0.w * t0.w)) + ((t1.x * t1.x + t1.y * t1.y) + (t1.z * t1.z + t1.w * t1.w)); } }
.LBB0_129:
	s_add_i32 s20, s12, s50
	s_ashr_i32 s21, s20, 31
	s_lshl_b64 s[48:49], s[20:21], 11
	v_lshl_add_u64 v[4:5], v[16:17], 0, s[48:49]
	global_load_dwordx4 v[0:3], v[4:5], off
	s_nop 0
	global_load_dwordx4 v[4:7], v[4:5], off offset:1024
	s_add_i32 s2, s20, 1
	s_ashr_i32 s3, s2, 31
	s_lshl_b64 s[14:15], s[2:3], 11
	v_lshl_add_u64 v[12:13], v[16:17], 0, s[14:15]
	global_load_dwordx4 v[8:11], v[12:13], off
	s_nop 0
	global_load_dwordx4 v[12:15], v[12:13], off offset:1024
	s_add_i32 s2, s20, 2
	s_ashr_i32 s3, s2, 31
	s_lshl_b64 s[4:5], s[2:3], 11
	v_lshl_add_u64 v[26:27], v[16:17], 0, s[4:5]
	global_load_dwordx4 v[22:25], v[26:27], off
	s_nop 0
	global_load_dwordx4 v[26:29], v[26:27], off offset:1024
	s_add_i32 s2, s20, 3
	s_ashr_i32 s3, s2, 31
	s_lshl_b64 s[46:47], s[2:3], 11
	v_lshl_add_u64 v[34:35], v[16:17], 0, s[46:47]
	global_load_dwordx4 v[30:33], v[34:35], off
	s_nop 0
	global_load_dwordx4 v[34:37], v[34:35], off offset:1024
	s_add_i32 s2, s20, 4
	s_ashr_i32 s3, s2, 31
	s_lshl_b64 s[44:45], s[2:3], 11
	v_lshl_add_u64 v[42:43], v[16:17], 0, s[44:45]
	global_load_dwordx4 v[38:41], v[42:43], off
	s_nop 0
	global_load_dwordx4 v[42:45], v[42:43], off offset:1024
	s_add_i32 s2, s20, 5
	s_ashr_i32 s3, s2, 31
	s_lshl_b64 s[42:43], s[2:3], 11
	v_lshl_add_u64 v[50:51], v[16:17], 0, s[42:43]
	global_load_dwordx4 v[46:49], v[50:51], off
	s_nop 0
	global_load_dwordx4 v[50:53], v[50:51], off offset:1024
	s_add_i32 s2, s20, 6
	s_ashr_i32 s3, s2, 31
	s_lshl_b64 s[40:41], s[2:3], 11
	v_lshl_add_u64 v[54:55], v[16:17], 0, s[40:41]
	global_load_dwordx4 v[104:107], v[54:55], off
	global_load_dwordx4 v[108:111], v[54:55], off offset:1024
	s_add_i32 s2, s20, 7
	s_ashr_i32 s3, s2, 31
	s_lshl_b64 s[38:39], s[2:3], 11
	v_lshl_add_u64 v[54:55], v[16:17], 0, s[38:39]
	global_load_dwordx4 v[112:115], v[54:55], off
	global_load_dwordx4 v[116:119], v[54:55], off offset:1024
	s_ashr_i32 s2, s20, 12
	s_mul_hi_i32 s3, s2, 0x6000
	s_mulk_i32 s2, 0x6000
	s_add_u32 s2, s78, s2
	s_addc_u32 s3, s1, s3
	v_lshl_add_u64 v[198:199], v[20:21], 0, s[48:49]
	s_add_i32 s13, s13, s10
	s_add_i32 s50, s50, s10
	s_waitcnt vmcnt(0)
	v_and_b32_e32 v154, 0xffff0000, v0
	v_and_b32_e32 v155, 0xffff0000, v4
	v_and_b32_e32 v175, 0xffff0000, v5
	v_and_b32_e32 v174, 0xffff0000, v1
	v_lshlrev_b32_e32 v153, 16, v4
	v_lshlrev_b32_e32 v152, 16, v0
	v_lshlrev_b32_e32 v159, 16, v5
	v_lshlrev_b32_e32 v158, 16, v1
	v_lshlrev_b32_e32 v156, 16, v2
	v_and_b32_e32 v160, 0xffff0000, v2
	v_lshlrev_b32_e32 v176, 16, v3
	v_and_b32_e32 v178, 0xffff0000, v3
	v_pk_mul_f32 v[0:1], v[154:155], v[154:155]
	v_pk_mul_f32 v[2:3], v[174:175], v[174:175]
	v_and_b32_e32 v161, 0xffff0000, v6
	v_and_b32_e32 v179, 0xffff0000, v7
	v_pk_fma_f32 v[0:1], v[152:153], v[152:153], v[0:1]
	v_pk_fma_f32 v[2:3], v[158:159], v[158:159], v[2:3]
	v_lshlrev_b32_e32 v157, 16, v6
	v_lshlrev_b32_e32 v177, 16, v7
	v_pk_add_f32 v[0:1], v[0:1], v[2:3]
	v_pk_mul_f32 v[2:3], v[160:161], v[160:161]
	v_pk_mul_f32 v[4:5], v[178:179], v[178:179]
	v_pk_fma_f32 v[2:3], v[156:157], v[156:157], v[2:3]
	v_pk_fma_f32 v[4:5], v[176:177], v[176:177], v[4:5]
	v_and_b32_e32 v139, 0xffff0000, v12
	v_pk_add_f32 v[2:3], v[2:3], v[4:5]
	v_and_b32_e32 v138, 0xffff0000, v8
	v_and_b32_e32 v147, 0xffff0000, v13
	v_and_b32_e32 v146, 0xffff0000, v9
	v_pk_add_f32 v[0:1], v[0:1], v[2:3]
	v_lshlrev_b32_e32 v137, 16, v12
	v_lshlrev_b32_e32 v136, 16, v8
	v_lshlrev_b32_e32 v143, 16, v13
	v_lshlrev_b32_e32 v142, 16, v9
	v_pk_mul_f32 v[2:3], v[138:139], v[138:139]
	v_pk_mul_f32 v[4:5], v[146:147], v[146:147]
	v_and_b32_e32 v145, 0xffff0000, v14
	v_and_b32_e32 v144, 0xffff0000, v10
	v_and_b32_e32 v151, 0xffff0000, v15
	v_and_b32_e32 v150, 0xffff0000, v11
	v_pk_fma_f32 v[2:3], v[136:137], v[136:137], v[2:3]
	v_pk_fma_f32 v[4:5], v[142:143], v[142:143], v[4:5]
	v_lshlrev_b32_e32 v141, 16, v14
	v_lshlrev_b32_e32 v140, 16, v10
	v_lshlrev_b32_e32 v149, 16, v15
	v_lshlrev_b32_e32 v148, 16, v11
	v_pk_add_f32 v[2:3], v[2:3], v[4:5]
	v_pk_mul_f32 v[4:5], v[144:145], v[144:145]
	v_pk_mul_f32 v[6:7], v[150:151], v[150:151]
	v_pk_fma_f32 v[4:5], v[140:141], v[140:141], v[4:5]
	v_pk_fma_f32 v[6:7], v[148:149], v[148:149], v[6:7]
	v_and_b32_e32 v123, 0xffff0000, v26
	v_pk_add_f32 v[4:5], v[4:5], v[6:7]
	v_and_b32_e32 v122, 0xffff0000, v22
	v_pk_add_f32 v[2:3], v[2:3], v[4:5]
	v_and_b32_e32 v131, 0xffff0000, v27
	v_and_b32_e32 v130, 0xffff0000, v23
	v_add_f32_e32 v0, v0, v1
	v_add_f32_e32 v1, v2, v3
	v_lshlrev_b32_e32 v121, 16, v26
	v_lshlrev_b32_e32 v120, 16, v22
	v_lshlrev_b32_e32 v127, 16, v27
	v_lshlrev_b32_e32 v126, 16, v23
	v_pk_mul_f32 v[2:3], v[122:123], v[122:123]
	v_pk_mul_f32 v[4:5], v[130:131], v[130:131]
	v_and_b32_e32 v129, 0xffff0000, v28
	v_and_b32_e32 v128, 0xffff0000, v24
	v_and_b32_e32 v135, 0xffff0000, v29
	v_and_b32_e32 v134, 0xffff0000, v25
	v_pk_fma_f32 v[2:3], v[120:121], v[120:121], v[2:3]
	v_pk_fma_f32 v[4:5], v[126:127], v[126:127], v[4:5]
	v_lshlrev_b32_e32 v125, 16, v28
	v_lshlrev_b32_e32 v124, 16, v24
	v_lshlrev_b32_e32 v133, 16, v29
	v_lshlrev_b32_e32 v132, 16, v25
	v_pk_add_f32 v[2:3], v[2:3], v[4:5]
	v_pk_mul_f32 v[4:5], v[128:129], v[128:129]
	v_pk_mul_f32 v[6:7], v[134:135], v[134:135]
	v_pk_fma_f32 v[4:5], v[124:125], v[124:125], v[4:5]
	v_pk_fma_f32 v[6:7], v[132:133], v[132:133], v[6:7]
	v_and_b32_e32 v91, 0xffff0000, v34
	v_pk_add_f32 v[4:5], v[4:5], v[6:7]
	v_and_b32_e32 v90, 0xffff0000, v30
	v_and_b32_e32 v99, 0xffff0000, v35
	v_and_b32_e32 v98, 0xffff0000, v31
	v_pk_add_f32 v[2:3], v[2:3], v[4:5]
	v_lshlrev_b32_e32 v89, 16, v34
	v_lshlrev_b32_e32 v88, 16, v30
	v_lshlrev_b32_e32 v95, 16, v35
	v_lshlrev_b32_e32 v94, 16, v31
; __device__ __forceinline__ void unpack8(const u32x4 w, f32x4& a, f32x4& c) { a = (f32x4){bf_lo(w.x), bf_hi(w.x), bf_lo(w.y), bf_hi(w.y)}; c = (f32x4){bf_lo(w.z), bf_hi(w.z), bf_lo(w.w), bf_hi(w.w)}; }
; template <int NR> __device__ __forceinline__ void wave_sumN(float (&s)[NR]) {
; #pragma unroll
;     for (int o = 1; o < 64; o <<= 1) {
;         float t[NR];
; #pragma unroll
;         for (int r = 0; r < NR; ++r) t[r] = __shfl_xor(s[r], o);
; #pragma unroll
;         for (int r = 0; r < NR; ++r) s[r] += t[r];
;     }
; }
; template <bool X_F32> __device__ __forceinline__ void phase_norm_mod(const Ctx& C, const void* xin, const float* modl, int shift_idx, int scale_idx) {
;     ...
;             for (int r = 0; r < NR; ++r) { s[r] = 0.f;
; #pragma unroll
;                 for (int j = 0; j < 2; ++j) { f32x4 t0, t1; unpack8(raw[r][j], t0, t1);
;                     s[r] += ((t0.x * t0.x + t0.y * t0.y) + (t0.z * t0.z + t0.w * t0.w)) + ((t1.x * t1.x + t1.y * t1.y) + (t1.z * t1.z + t1.w * t1.w)); } }
;             wave_sumN<NR>(s);
	v_pk_mul_f32 v[4:5], v[90:91], v[90:91]
	v_pk_mul_f32 v[6:7], v[98:99], v[98:99]
	v_and_b32_e32 v97, 0xffff0000, v36
	v_and_b32_e32 v96, 0xffff0000, v32
	v_and_b32_e32 v103, 0xffff0000, v37
	v_and_b32_e32 v102, 0xffff0000, v33
	v_pk_fma_f32 v[4:5], v[88:89], v[88:89], v[4:5]
	v_pk_fma_f32 v[6:7], v[94:95], v[94:95], v[6:7]
	v_lshlrev_b32_e32 v93, 16, v36
	v_lshlrev_b32_e32 v92, 16, v32
	v_lshlrev_b32_e32 v101, 16, v37
	v_lshlrev_b32_e32 v100, 16, v33
	v_pk_add_f32 v[4:5], v[4:5], v[6:7]
	v_pk_mul_f32 v[6:7], v[96:97], v[96:97]
	v_pk_mul_f32 v[8:9], v[102:103], v[102:103]
	v_pk_fma_f32 v[6:7], v[92:93], v[92:93], v[6:7]
	v_pk_fma_f32 v[8:9], v[100:101], v[100:101], v[8:9]
	v_and_b32_e32 v73, 0xffff0000, v42
	v_pk_add_f32 v[6:7], v[6:7], v[8:9]
	v_and_b32_e32 v72, 0xffff0000, v38
	v_pk_add_f32 v[4:5], v[4:5], v[6:7]
	v_and_b32_e32 v83, 0xffff0000, v43
	v_and_b32_e32 v82, 0xffff0000, v39
	v_add_f32_e32 v2, v2, v3
	v_add_f32_e32 v3, v4, v5
	v_lshlrev_b32_e32 v71, 16, v42
	v_lshlrev_b32_e32 v70, 16, v38
	v_lshlrev_b32_e32 v77, 16, v43
	v_lshlrev_b32_e32 v76, 16, v39
	v_pk_mul_f32 v[4:5], v[72:73], v[72:73]
	v_pk_mul_f32 v[6:7], v[82:83], v[82:83]
	v_and_b32_e32 v79, 0xffff0000, v44
	v_and_b32_e32 v78, 0xffff0000, v40
	v_and_b32_e32 v87, 0xffff0000, v45
	v_and_b32_e32 v86, 0xffff0000, v41
	v_pk_fma_f32 v[4:5], v[70:71], v[70:71], v[4:5]
	v_pk_fma_f32 v[6:7], v[76:77], v[76:77], v[6:7]
	v_lshlrev_b32_e32 v75, 16, v44
	v_lshlrev_b32_e32 v74, 16, v40
	v_lshlrev_b32_e32 v85, 16, v45
	v_lshlrev_b32_e32 v84, 16, v41
	v_pk_add_f32 v[4:5], v[4:5], v[6:7]
	v_pk_mul_f32 v[6:7], v[78:79], v[78:79]
	v_pk_mul_f32 v[8:9], v[86:87], v[86:87]
	v_pk_fma_f32 v[6:7], v[74:75], v[74:75], v[6:7]
	v_pk_fma_f32 v[8:9], v[84:85], v[84:85], v[8:9]
	v_and_b32_e32 v57, 0xffff0000, v50
	v_pk_add_f32 v[6:7], v[6:7], v[8:9]
	v_and_b32_e32 v56, 0xffff0000, v46
	v_and_b32_e32 v65, 0xffff0000, v51
	v_and_b32_e32 v64, 0xffff0000, v47
	v_pk_add_f32 v[4:5], v[4:5], v[6:7]
	v_lshlrev_b32_e32 v55, 16, v50
	v_lshlrev_b32_e32 v54, 16, v46
	v_lshlrev_b32_e32 v61, 16, v51
	v_lshlrev_b32_e32 v60, 16, v47
	v_pk_mul_f32 v[6:7], v[56:57], v[56:57]
	v_pk_mul_f32 v[8:9], v[64:65], v[64:65]
	v_and_b32_e32 v63, 0xffff0000, v52
	v_and_b32_e32 v62, 0xffff0000, v48
	v_and_b32_e32 v69, 0xffff0000, v53
	v_and_b32_e32 v68, 0xffff0000, v49
	v_pk_fma_f32 v[6:7], v[54:55], v[54:55], v[6:7]
	v_pk_fma_f32 v[8:9], v[60:61], v[60:61], v[8:9]
	v_lshlrev_b32_e32 v59, 16, v52
	v_lshlrev_b32_e32 v58, 16, v48
	v_lshlrev_b32_e32 v67, 16, v53
	v_lshlrev_b32_e32 v66, 16, v49
	v_pk_add_f32 v[6:7], v[6:7], v[8:9]
	v_pk_mul_f32 v[8:9], v[62:63], v[62:63]
	v_pk_mul_f32 v[10:11], v[68:69], v[68:69]
	v_pk_fma_f32 v[8:9], v[58:59], v[58:59], v[8:9]
	v_pk_fma_f32 v[10:11], v[66:67], v[66:67], v[10:11]
	v_and_b32_e32 v41, 0xffff0000, v108
	v_pk_add_f32 v[8:9], v[8:9], v[10:11]
	v_and_b32_e32 v40, 0xffff0000, v104
	v_pk_add_f32 v[6:7], v[6:7], v[8:9]
	v_and_b32_e32 v49, 0xffff0000, v109
	v_and_b32_e32 v48, 0xffff0000, v105
	v_add_f32_e32 v4, v4, v5
	v_add_f32_e32 v5, v6, v7
	v_lshlrev_b32_e32 v39, 16, v108
	v_lshlrev_b32_e32 v38, 16, v104
	v_lshlrev_b32_e32 v45, 16, v109
	v_lshlrev_b32_e32 v44, 16, v105
	v_pk_mul_f32 v[6:7], v[40:41], v[40:41]
	v_pk_mul_f32 v[8:9], v[48:49], v[48:49]
	v_and_b32_e32 v47, 0xffff0000, v110
	v_and_b32_e32 v46, 0xffff0000, v106
	v_and_b32_e32 v53, 0xffff0000, v111
	v_and_b32_e32 v52, 0xffff0000, v107
	v_pk_fma_f32 v[6:7], v[38:39], v[38:39], v[6:7]
	v_pk_fma_f32 v[8:9], v[44:45], v[44:45], v[8:9]
	v_lshlrev_b32_e32 v43, 16, v110
	v_lshlrev_b32_e32 v42, 16, v106
	v_lshlrev_b32_e32 v51, 16, v111
	v_lshlrev_b32_e32 v50, 16, v107
	v_pk_add_f32 v[6:7], v[6:7], v[8:9]
	v_pk_mul_f32 v[8:9], v[46:47], v[46:47]
	v_pk_mul_f32 v[10:11], v[52:53], v[52:53]
	v_pk_fma_f32 v[8:9], v[42:43], v[42:43], v[8:9]
	v_pk_fma_f32 v[10:11], v[50:51], v[50:51], v[10:11]
	v_and_b32_e32 v25, 0xffff0000, v116
	v_pk_add_f32 v[8:9], v[8:9], v[10:11]
	v_and_b32_e32 v24, 0xffff0000, v112
	v_and_b32_e32 v33, 0xffff0000, v117
	v_and_b32_e32 v32, 0xffff0000, v113
	v_pk_add_f32 v[6:7], v[6:7], v[8:9]
	v_lshlrev_b32_e32 v23, 16, v116
	v_lshlrev_b32_e32 v22, 16, v112
	v_lshlrev_b32_e32 v29, 16, v117
	v_lshlrev_b32_e32 v28, 16, v113
	v_pk_mul_f32 v[8:9], v[24:25], v[24:25]
	v_pk_mul_f32 v[10:11], v[32:33], v[32:33]
	v_and_b32_e32 v31, 0xffff0000, v118
	v_and_b32_e32 v30, 0xffff0000, v114
	v_and_b32_e32 v37, 0xffff0000, v119
	v_and_b32_e32 v36, 0xffff0000, v115
	v_pk_fma_f32 v[8:9], v[22:23], v[22:23], v[8:9]
	v_pk_fma_f32 v[10:11], v[28:29], v[28:29], v[10:11]
	v_lshlrev_b32_e32 v27, 16, v118
	v_lshlrev_b32_e32 v26, 16, v114
	v_lshlrev_b32_e32 v35, 16, v119
	v_lshlrev_b32_e32 v34, 16, v115
	v_pk_add_f32 v[8:9], v[8:9], v[10:11]
	v_pk_mul_f32 v[10:11], v[30:31], v[30:31]
	v_pk_mul_f32 v[12:13], v[36:37], v[36:37]
	v_pk_fma_f32 v[10:11], v[26:27], v[26:27], v[10:11]
	v_pk_fma_f32 v[12:13], v[34:35], v[34:35], v[12:13]
	v_add_f32_e32 v6, v6, v7
	v_pk_add_f32 v[10:11], v[10:11], v[12:13]
	ds_bpermute_b32 v12, v180, v4
	v_pk_add_f32 v[8:9], v[8:9], v[10:11]
	ds_bpermute_b32 v10, v180, v2
	v_add_f32_e32 v7, v8, v9
	ds_bpermute_b32 v8, v180, v0
	ds_bpermute_b32 v9, v180, v1
	ds_bpermute_b32 v11, v180, v3
	ds_bpermute_b32 v13, v180, v5
	ds_bpermute_b32 v14, v180, v6
	ds_bpermute_b32 v15, v180, v7
	s_waitcnt lgkmcnt(0)
	v_add_f32_e32 v0, v0, v8
	s_waitcnt lgkmcnt(4)
	v_add_f32_e32 v1, v1, v9
	ds_bpermute_b32 v8, v181, v0
	v_add_f32_e32 v2, v2, v10
	s_waitcnt lgkmcnt(4)
	v_add_f32_e32 v3, v3, v11
	v_add_f32_e32 v4, v4, v12
	s_waitcnt lgkmcnt(3)
	v_add_f32_e32 v5, v5, v13
	s_waitcnt lgkmcnt(2)
	v_add_f32_e32 v6, v6, v14
	s_waitcnt lgkmcnt(1)
; template <int NR> __device__ __forceinline__ void wave_sumN(float (&s)[NR]) {
; #pragma unroll
;     for (int o = 1; o < 64; o <<= 1) {
;         float t[NR];
; #pragma unroll
;         for (int r = 0; r < NR; ++r) t[r] = __shfl_xor(s[r], o);
; #pragma unroll
;         for (int r = 0; r < NR; ++r) s[r] += t[r];
;     }
; }
; template <bool X_F32> __device__ __forceinline__ void phase_norm_mod(const Ctx& C, const void* xin, const float* modl, int shift_idx, int scale_idx) {
;     ...
;             f32x4 a[4], g[4];
; #pragma unroll
;             for (int j = 0; j < 2; ++j)
; #pragma unroll
;                 for (int q = 0; q < 2; ++q) { a[2 * j + q] = *(const f32x4*)(modl + (size_t)b * NMOD + shift_idx * DM + 512 * j + 8 * lane + 4 * q);
;                     g[2 * j + q] = *(const f32x4*)(modl + (size_t)b * NMOD + scale_idx * DM + 512 * j + 8 * lane + 4 * q) + 1.0f; }
	v_add_f32_e32 v7, v7, v15
	ds_bpermute_b32 v9, v181, v1
	ds_bpermute_b32 v10, v181, v2
	ds_bpermute_b32 v11, v181, v3
	ds_bpermute_b32 v12, v181, v4
	ds_bpermute_b32 v13, v181, v5
	ds_bpermute_b32 v14, v181, v6
	ds_bpermute_b32 v15, v181, v7
	s_waitcnt lgkmcnt(7)
	v_add_f32_e32 v0, v0, v8
	s_waitcnt lgkmcnt(6)
	v_add_f32_e32 v1, v1, v9
	ds_bpermute_b32 v8, v182, v0
	s_waitcnt lgkmcnt(6)
	v_add_f32_e32 v2, v2, v10
	s_waitcnt lgkmcnt(5)
	v_add_f32_e32 v3, v3, v11
	s_waitcnt lgkmcnt(4)
	v_add_f32_e32 v4, v4, v12
	s_waitcnt lgkmcnt(3)
	v_add_f32_e32 v5, v5, v13
	s_waitcnt lgkmcnt(2)
	v_add_f32_e32 v6, v6, v14
	s_waitcnt lgkmcnt(1)
	v_add_f32_e32 v7, v7, v15
	ds_bpermute_b32 v9, v182, v1
	ds_bpermute_b32 v10, v182, v2
	ds_bpermute_b32 v11, v182, v3
	ds_bpermute_b32 v12, v182, v4
	ds_bpermute_b32 v13, v182, v5
	ds_bpermute_b32 v14, v182, v6
	ds_bpermute_b32 v15, v182, v7
	s_waitcnt lgkmcnt(7)
	v_add_f32_e32 v0, v0, v8
	s_waitcnt lgkmcnt(6)
	v_add_f32_e32 v1, v1, v9
	ds_bpermute_b32 v8, v183, v0
	s_waitcnt lgkmcnt(6)
	v_add_f32_e32 v2, v2, v10
	s_waitcnt lgkmcnt(5)
	v_add_f32_e32 v3, v3, v11
	s_waitcnt lgkmcnt(4)
	v_add_f32_e32 v4, v4, v12
	s_waitcnt lgkmcnt(3)
	v_add_f32_e32 v5, v5, v13
	s_waitcnt lgkmcnt(2)
	v_add_f32_e32 v6, v6, v14
	s_waitcnt lgkmcnt(1)
	v_add_f32_e32 v7, v7, v15
	ds_bpermute_b32 v9, v183, v1
	ds_bpermute_b32 v10, v183, v2
	ds_bpermute_b32 v11, v183, v3
	ds_bpermute_b32 v12, v183, v4
	ds_bpermute_b32 v13, v183, v5
	ds_bpermute_b32 v14, v183, v6
	ds_bpermute_b32 v15, v183, v7
	s_waitcnt lgkmcnt(7)
	v_add_f32_e32 v0, v0, v8
	s_waitcnt lgkmcnt(6)
	v_add_f32_e32 v1, v1, v9
	ds_bpermute_b32 v8, v184, v0
	s_waitcnt lgkmcnt(6)
	v_add_f32_e32 v2, v2, v10
	s_waitcnt lgkmcnt(5)
	v_add_f32_e32 v3, v3, v11
	s_waitcnt lgkmcnt(4)
	v_add_f32_e32 v4, v4, v12
	s_waitcnt lgkmcnt(3)
	v_add_f32_e32 v5, v5, v13
	s_waitcnt lgkmcnt(2)
	v_add_f32_e32 v6, v6, v14
	s_waitcnt lgkmcnt(1)
	v_add_f32_e32 v7, v7, v15
	ds_bpermute_b32 v9, v184, v1
	ds_bpermute_b32 v10, v184, v2
	ds_bpermute_b32 v11, v184, v3
	ds_bpermute_b32 v12, v184, v4
	ds_bpermute_b32 v13, v184, v5
	ds_bpermute_b32 v14, v184, v6
	ds_bpermute_b32 v15, v184, v7
	s_waitcnt lgkmcnt(7)
	v_add_f32_e32 v0, v0, v8
	s_waitcnt lgkmcnt(6)
	v_add_f32_e32 v1, v1, v9
	ds_bpermute_b32 v8, v185, v0
	s_waitcnt lgkmcnt(6)
	v_add_f32_e32 v2, v2, v10
	s_waitcnt lgkmcnt(5)
	v_add_f32_e32 v3, v3, v11
	s_waitcnt lgkmcnt(4)
	v_add_f32_e32 v4, v4, v12
	s_waitcnt lgkmcnt(3)
	v_add_f32_e32 v5, v5, v13
	s_waitcnt lgkmcnt(2)
	v_add_f32_e32 v6, v6, v14
	s_waitcnt lgkmcnt(1)
	v_add_f32_e32 v7, v7, v15
	ds_bpermute_b32 v9, v185, v1
	ds_bpermute_b32 v10, v185, v2
	ds_bpermute_b32 v11, v185, v3
	ds_bpermute_b32 v12, v185, v4
	ds_bpermute_b32 v13, v185, v5
	ds_bpermute_b32 v14, v185, v6
	ds_bpermute_b32 v15, v185, v7
	v_lshl_add_u64 v[104:105], v[18:19], 2, s[2:3]
	s_waitcnt lgkmcnt(7)
	v_add_f32_e32 v80, v0, v8
	v_add_co_u32_e32 v0, vcc, s19, v104
	s_waitcnt lgkmcnt(6)
	v_add_f32_e32 v192, v1, v9
	v_addc_co_u32_e32 v1, vcc, 0, v105, vcc
	s_waitcnt lgkmcnt(5)
	v_add_f32_e32 v191, v2, v10
	s_waitcnt lgkmcnt(4)
	v_add_f32_e32 v190, v3, v11
	s_waitcnt lgkmcnt(3)
	v_add_f32_e32 v189, v4, v12
	s_waitcnt lgkmcnt(2)
	v_add_f32_e32 v188, v5, v13
	s_waitcnt lgkmcnt(1)
	v_add_f32_e32 v187, v6, v14
	s_waitcnt lgkmcnt(0)
	v_add_f32_e32 v186, v7, v15
	v_lshl_add_u64 v[106:107], v[104:105], 0, s[90:91]
	global_load_dwordx4 v[4:7], v[104:105], off offset:16
	global_load_dwordx4 v[12:15], v[104:105], off
	s_nop 0
	global_load_dwordx4 v[0:3], v[0:1], off
	s_nop 0
	global_load_dwordx4 v[8:11], v[106:107], off offset:16
	v_fmamk_f32 v80, v80, 0x3a800000, v214
	v_cmp_gt_f32_e32 vcc, s51, v80
	v_mul_f32_e32 v193, 0x4f800000, v80
	v_mov_b32_e32 v201, v160
	v_cndmask_b32_e32 v80, v80, v193, vcc
	v_sqrt_f32_e32 v193, v80
	v_mov_b32_e32 v203, v178
	v_mov_b32_e32 v160, v157
	v_mov_b32_e32 v178, v177
	v_mov_b32_e32 v200, v156
	v_mov_b32_e32 v202, v176
	s_waitcnt vmcnt(1)
	v_pk_add_f32 v[116:117], v[2:3], 1.0 op_sel_hi:[1,0]
	v_pk_add_f32 v[118:119], v[0:1], 1.0 op_sel_hi:[1,0]
	s_waitcnt vmcnt(0)
	v_pk_add_f32 v[112:113], v[10:11], 1.0 op_sel_hi:[1,0]
	v_pk_add_f32 v[114:115], v[8:9], 1.0 op_sel_hi:[1,0]
	global_load_dwordx4 v[0:3], v[104:105], off offset:2064
	global_load_dwordx4 v[8:11], v[104:105], off offset:2048
	global_load_dwordx4 v[194:197], v[106:107], off offset:2064
	s_nop 0
	global_load_dwordx4 v[104:107], v[106:107], off offset:2048
	s_waitcnt vmcnt(0)
; __device__ __forceinline__ unsigned pk2(float lo, float hi) { return pg8::cvt_pk_bf16(lo, hi); }
; __device__ __forceinline__ void unpack8(const u32x4 w, f32x4& a, f32x4& c) { a = (f32x4){bf_lo(w.x), bf_hi(w.x), bf_lo(w.y), bf_hi(w.y)}; c = (f32x4){bf_lo(w.z), bf_hi(w.z), bf_lo(w.w), bf_hi(w.w)}; }
; template <bool X_F32> __device__ __forceinline__ void phase_norm_mod(const Ctx& C, const void* xin, const float* modl, int shift_idx, int scale_idx) {
;     ...
;             for (int r = 0; r < NR; ++r) { const float rs = 1.0f / sqrtf(s[r] * (1.f / DM) + EPS);
; #pragma unroll
;                 for (int j = 0; j < 2; ++j) { f32x4 t0, t1; unpack8(raw[r][j], t0, t1);
;                     const f32x4 y0 = t0 * rs * g[2 * j] + a[2 * j], y1 = t1 * rs * g[2 * j + 1] + a[2 * j + 1];
;                     u32x4 w; w.x = pk2(y0.x, y0.y); w.y = pk2(y0.z, y0.w); w.z = pk2(y1.x, y1.y); w.w = pk2(y1.z, y1.w);
;                     ((u32x4*)(H + (size_t)(m0 + r) * DM + 512 * j))[lane] = w; } }
	v_pk_add_f32 v[108:109], v[106:107], 1.0 op_sel_hi:[1,0]
	v_pk_add_f32 v[106:107], v[194:195], 1.0 op_sel_hi:[1,0]
	v_add_u32_e32 v194, -1, v193
	v_fma_f32 v195, -v194, v193, v80
	v_cmp_ge_f32_e64 s[36:37], 0, v195
	v_add_u32_e32 v195, 1, v193
	v_pk_add_f32 v[110:111], v[104:105], 1.0 op_sel_hi:[1,0]
	v_cndmask_b32_e64 v194, v193, v194, s[36:37]
	v_fma_f32 v193, -v195, v193, v80
	v_cmp_lt_f32_e64 s[36:37], 0, v193
	v_pk_add_f32 v[104:105], v[196:197], 1.0 op_sel_hi:[1,0]
	s_nop 0
	v_cndmask_b32_e64 v193, v194, v195, s[36:37]
	v_mul_f32_e32 v194, 0x37800000, v193
	v_cndmask_b32_e32 v193, v193, v194, vcc
	v_cmp_class_f32_e32 vcc, v80, v215
	s_nop 1
	v_cndmask_b32_e32 v80, v193, v80, vcc
	v_div_scale_f32 v193, s[2:3], v80, v80, 1.0
	v_rcp_f32_e32 v194, v193
	s_nop 0
	v_fma_f32 v195, -v193, v194, 1.0
	v_fmac_f32_e32 v194, v195, v194
	v_div_scale_f32 v195, vcc, 1.0, v80, 1.0
	v_mul_f32_e32 v196, v195, v194
	v_fma_f32 v197, -v193, v196, v195
	v_fmac_f32_e32 v196, v197, v194
	v_fma_f32 v193, -v193, v196, v195
	v_div_fmas_f32 v193, v193, v194, v196
	v_div_fixup_f32 v80, v193, v80, 1.0
	v_mov_b32_e32 v195, v154
	v_mov_b32_e32 v197, v174
	v_mov_b32_e32 v154, v153
	v_mov_b32_e32 v174, v159
	v_mov_b32_e32 v194, v152
	v_mov_b32_e32 v196, v158
	v_pk_mul_f32 v[152:153], v[80:81], v[154:155] op_sel_hi:[0,1]
	v_pk_mul_f32 v[154:155], v[80:81], v[174:175] op_sel_hi:[0,1]
	v_pk_mul_f32 v[156:157], v[80:81], v[160:161] op_sel_hi:[0,1]
	v_pk_mul_f32 v[158:159], v[80:81], v[178:179] op_sel_hi:[0,1]
	v_pk_fma_f32 v[154:155], v[154:155], v[108:109], v[10:11]
	v_pk_fma_f32 v[152:153], v[152:153], v[110:111], v[8:9]
	v_pk_fma_f32 v[158:159], v[158:159], v[104:105], v[2:3]
	v_pk_fma_f32 v[156:157], v[156:157], v[106:107], v[0:1]
	v_pk_mul_f32 v[194:195], v[80:81], v[194:195] op_sel_hi:[0,1]
	v_pk_mul_f32 v[196:197], v[80:81], v[196:197] op_sel_hi:[0,1]
	v_pk_mul_f32 v[200:201], v[80:81], v[200:201] op_sel_hi:[0,1]
	v_pk_mul_f32 v[202:203], v[80:81], v[202:203] op_sel_hi:[0,1]
	v_cvt_pk_bf16_f32 v152, v152, v153
	v_cvt_pk_bf16_f32 v153, v154, v155
	v_cvt_pk_bf16_f32 v154, v156, v157
	v_cvt_pk_bf16_f32 v155, v158, v159
	v_fmamk_f32 v80, v192, 0x3a800000, v214
	flat_store_dwordx4 v[198:199], v[152:155] offset:1024 sc0 sc1
	v_cmp_gt_f32_e32 vcc, s51, v80
	v_mov_b32_e32 v159, v144
	v_mul_f32_e32 v152, 0x4f800000, v80
	v_cndmask_b32_e32 v80, v80, v152, vcc
	v_sqrt_f32_e32 v152, v80
	v_mov_b32_e32 v161, v150
	v_mov_b32_e32 v144, v141
	v_mov_b32_e32 v150, v149
	v_add_u32_e32 v153, -1, v152
	v_fma_f32 v154, -v153, v152, v80
	v_cmp_ge_f32_e64 s[36:37], 0, v154
	v_add_u32_e32 v154, 1, v152
	v_mov_b32_e32 v158, v140
	v_cndmask_b32_e64 v153, v152, v153, s[36:37]
	v_fma_f32 v152, -v154, v152, v80
	v_cmp_lt_f32_e64 s[36:37], 0, v152
	v_mov_b32_e32 v160, v148
	v_pk_fma_f32 v[196:197], v[196:197], v[116:117], v[14:15]
	v_cndmask_b32_e64 v152, v153, v154, s[36:37]
	v_mul_f32_e32 v153, 0x37800000, v152
	v_cndmask_b32_e32 v152, v152, v153, vcc
	v_cmp_class_f32_e32 vcc, v80, v215
	v_pk_fma_f32 v[194:195], v[194:195], v[118:119], v[12:13]
	v_pk_fma_f32 v[202:203], v[202:203], v[112:113], v[6:7]
	v_cndmask_b32_e32 v80, v152, v80, vcc
	v_div_scale_f32 v152, s[2:3], v80, v80, 1.0
	v_rcp_f32_e32 v153, v152
	v_pk_fma_f32 v[200:201], v[200:201], v[114:115], v[4:5]
	v_cvt_pk_bf16_f32 v194, v194, v195
	v_cvt_pk_bf16_f32 v195, v196, v197
	v_fma_f32 v154, -v152, v153, 1.0
	v_fmac_f32_e32 v153, v154, v153
	v_div_scale_f32 v154, vcc, 1.0, v80, 1.0
	v_mul_f32_e32 v155, v154, v153
	v_fma_f32 v156, -v152, v155, v154
	v_fmac_f32_e32 v155, v156, v153
	v_fma_f32 v152, -v152, v155, v154
	v_div_fmas_f32 v152, v152, v153, v155
	v_div_fixup_f32 v80, v152, v80, 1.0
	v_mov_b32_e32 v153, v138
	v_mov_b32_e32 v155, v146
	v_mov_b32_e32 v138, v137
	v_mov_b32_e32 v146, v143
	v_mov_b32_e32 v152, v136
	v_mov_b32_e32 v154, v142
	v_pk_mul_f32 v[136:137], v[80:81], v[138:139] op_sel_hi:[0,1]
	v_pk_mul_f32 v[138:139], v[80:81], v[146:147] op_sel_hi:[0,1]
	v_pk_mul_f32 v[140:141], v[80:81], v[144:145] op_sel_hi:[0,1]
	v_pk_mul_f32 v[142:143], v[80:81], v[150:151] op_sel_hi:[0,1]
	v_pk_fma_f32 v[138:139], v[138:139], v[108:109], v[10:11]
	v_pk_fma_f32 v[136:137], v[136:137], v[110:111], v[8:9]
	v_pk_fma_f32 v[142:143], v[142:143], v[104:105], v[2:3]
	v_pk_fma_f32 v[140:141], v[140:141], v[106:107], v[0:1]
	v_lshl_add_u64 v[156:157], v[20:21], 0, s[14:15]
	v_pk_mul_f32 v[152:153], v[80:81], v[152:153] op_sel_hi:[0,1]
	v_pk_mul_f32 v[154:155], v[80:81], v[154:155] op_sel_hi:[0,1]
	v_pk_mul_f32 v[158:159], v[80:81], v[158:159] op_sel_hi:[0,1]
	v_pk_mul_f32 v[160:161], v[80:81], v[160:161] op_sel_hi:[0,1]
	v_cvt_pk_bf16_f32 v136, v136, v137
	v_cvt_pk_bf16_f32 v137, v138, v139
	v_cvt_pk_bf16_f32 v138, v140, v141
	v_cvt_pk_bf16_f32 v139, v142, v143
	v_fmamk_f32 v80, v191, 0x3a800000, v214
	flat_store_dwordx4 v[156:157], v[136:139] offset:1024 sc0 sc1
	v_cmp_gt_f32_e32 vcc, s51, v80
	v_mov_b32_e32 v143, v128
	v_mul_f32_e32 v136, 0x4f800000, v80
	v_cndmask_b32_e32 v80, v80, v136, vcc
	v_sqrt_f32_e32 v136, v80
	v_mov_b32_e32 v145, v134
	v_mov_b32_e32 v128, v125
	v_mov_b32_e32 v134, v133
	v_add_u32_e32 v137, -1, v136
	v_fma_f32 v138, -v137, v136, v80
	v_cmp_ge_f32_e64 s[36:37], 0, v138
	v_add_u32_e32 v138, 1, v136
	v_mov_b32_e32 v142, v124
	v_cndmask_b32_e64 v137, v136, v137, s[36:37]
	v_fma_f32 v136, -v138, v136, v80
	v_cmp_lt_f32_e64 s[36:37], 0, v136
	v_mov_b32_e32 v144, v132
	v_pk_fma_f32 v[154:155], v[116:117], v[154:155], v[14:15]
	v_cndmask_b32_e64 v136, v137, v138, s[36:37]
	v_mul_f32_e32 v137, 0x37800000, v136
	v_cndmask_b32_e32 v136, v136, v137, vcc
	v_cmp_class_f32_e32 vcc, v80, v215
	v_pk_fma_f32 v[152:153], v[118:119], v[152:153], v[12:13]
; __device__ __forceinline__ unsigned pk2(float lo, float hi) { return pg8::cvt_pk_bf16(lo, hi); }
; __device__ __forceinline__ void unpack8(const u32x4 w, f32x4& a, f32x4& c) { a = (f32x4){bf_lo(w.x), bf_hi(w.x), bf_lo(w.y), bf_hi(w.y)}; c = (f32x4){bf_lo(w.z), bf_hi(w.z), bf_lo(w.w), bf_hi(w.w)}; }
; template <bool X_F32> __device__ __forceinline__ void phase_norm_mod(const Ctx& C, const void* xin, const float* modl, int shift_idx, int scale_idx) {
;     ...
;             for (int r = 0; r < NR; ++r) { const float rs = 1.0f / sqrtf(s[r] * (1.f / DM) + EPS);
; #pragma unroll
;                 for (int j = 0; j < 2; ++j) { f32x4 t0, t1; unpack8(raw[r][j], t0, t1);
;                     const f32x4 y0 = t0 * rs * g[2 * j] + a[2 * j], y1 = t1 * rs * g[2 * j + 1] + a[2 * j + 1];
;                     u32x4 w; w.x = pk2(y0.x, y0.y); w.y = pk2(y0.z, y0.w); w.z = pk2(y1.x, y1.y); w.w = pk2(y1.z, y1.w);
;                     ((u32x4*)(H + (size_t)(m0 + r) * DM + 512 * j))[lane] = w; } }
	v_pk_fma_f32 v[160:161], v[160:161], v[112:113], v[6:7]
	v_cndmask_b32_e32 v80, v136, v80, vcc
	v_div_scale_f32 v136, s[2:3], v80, v80, 1.0
	v_rcp_f32_e32 v137, v136
	v_pk_fma_f32 v[158:159], v[158:159], v[114:115], v[4:5]
	v_cvt_pk_bf16_f32 v196, v200, v201
	v_cvt_pk_bf16_f32 v197, v202, v203
	v_fma_f32 v138, -v136, v137, 1.0
	v_fmac_f32_e32 v137, v138, v137
	v_div_scale_f32 v138, vcc, 1.0, v80, 1.0
	v_mul_f32_e32 v139, v138, v137
	v_fma_f32 v140, -v136, v139, v138
	v_fmac_f32_e32 v139, v140, v137
	v_fma_f32 v136, -v136, v139, v138
	v_div_fmas_f32 v136, v136, v137, v139
	v_div_fixup_f32 v80, v136, v80, 1.0
	v_mov_b32_e32 v137, v122
	v_mov_b32_e32 v139, v130
	v_mov_b32_e32 v122, v121
	v_mov_b32_e32 v130, v127
	v_mov_b32_e32 v136, v120
	v_mov_b32_e32 v138, v126
	v_pk_mul_f32 v[120:121], v[80:81], v[122:123] op_sel_hi:[0,1]
	v_pk_mul_f32 v[122:123], v[80:81], v[130:131] op_sel_hi:[0,1]
	v_pk_mul_f32 v[124:125], v[80:81], v[128:129] op_sel_hi:[0,1]
	v_pk_mul_f32 v[126:127], v[80:81], v[134:135] op_sel_hi:[0,1]
	v_pk_fma_f32 v[122:123], v[122:123], v[108:109], v[10:11]
	v_pk_fma_f32 v[120:121], v[120:121], v[110:111], v[8:9]
	v_pk_fma_f32 v[126:127], v[126:127], v[104:105], v[2:3]
	v_pk_fma_f32 v[124:125], v[124:125], v[106:107], v[0:1]
	v_lshl_add_u64 v[140:141], v[20:21], 0, s[4:5]
	v_pk_mul_f32 v[136:137], v[80:81], v[136:137] op_sel_hi:[0,1]
	v_pk_mul_f32 v[138:139], v[80:81], v[138:139] op_sel_hi:[0,1]
	v_pk_mul_f32 v[142:143], v[80:81], v[142:143] op_sel_hi:[0,1]
	v_pk_mul_f32 v[144:145], v[80:81], v[144:145] op_sel_hi:[0,1]
	v_cvt_pk_bf16_f32 v120, v120, v121
	v_cvt_pk_bf16_f32 v121, v122, v123
	v_cvt_pk_bf16_f32 v122, v124, v125
	v_cvt_pk_bf16_f32 v123, v126, v127
	v_fmamk_f32 v80, v190, 0x3a800000, v214
	flat_store_dwordx4 v[140:141], v[120:123] offset:1024 sc0 sc1
	v_cmp_gt_f32_e32 vcc, s51, v80
	v_mov_b32_e32 v127, v96
	v_mul_f32_e32 v120, 0x4f800000, v80
	v_cndmask_b32_e32 v80, v80, v120, vcc
	v_sqrt_f32_e32 v120, v80
	v_mov_b32_e32 v129, v102
	v_mov_b32_e32 v96, v93
	v_mov_b32_e32 v102, v101
	v_add_u32_e32 v121, -1, v120
	v_fma_f32 v122, -v121, v120, v80
	v_cmp_ge_f32_e64 s[36:37], 0, v122
	v_add_u32_e32 v122, 1, v120
	v_mov_b32_e32 v126, v92
	v_cndmask_b32_e64 v121, v120, v121, s[36:37]
	v_fma_f32 v120, -v122, v120, v80
	v_cmp_lt_f32_e64 s[36:37], 0, v120
	v_mov_b32_e32 v128, v100
	v_pk_fma_f32 v[138:139], v[116:117], v[138:139], v[14:15]
	v_cndmask_b32_e64 v120, v121, v122, s[36:37]
	v_mul_f32_e32 v121, 0x37800000, v120
	v_cndmask_b32_e32 v120, v120, v121, vcc
	v_cmp_class_f32_e32 vcc, v80, v215
	v_pk_fma_f32 v[136:137], v[118:119], v[136:137], v[12:13]
	v_pk_fma_f32 v[144:145], v[144:145], v[112:113], v[6:7]
	v_cndmask_b32_e32 v80, v120, v80, vcc
	v_div_scale_f32 v120, s[2:3], v80, v80, 1.0
	v_rcp_f32_e32 v121, v120
	v_pk_fma_f32 v[142:143], v[142:143], v[114:115], v[4:5]
	v_cvt_pk_bf16_f32 v152, v152, v153
	v_cvt_pk_bf16_f32 v153, v154, v155
	v_fma_f32 v122, -v120, v121, 1.0
	v_fmac_f32_e32 v121, v122, v121
	v_div_scale_f32 v122, vcc, 1.0, v80, 1.0
	v_mul_f32_e32 v123, v122, v121
	v_fma_f32 v124, -v120, v123, v122
	v_fmac_f32_e32 v123, v124, v121
	v_fma_f32 v120, -v120, v123, v122
	v_div_fmas_f32 v120, v120, v121, v123
	v_div_fixup_f32 v80, v120, v80, 1.0
	v_mov_b32_e32 v121, v90
	v_mov_b32_e32 v123, v98
	v_mov_b32_e32 v90, v89
	v_mov_b32_e32 v98, v95
	v_mov_b32_e32 v120, v88
	v_mov_b32_e32 v122, v94
	v_pk_mul_f32 v[88:89], v[80:81], v[90:91] op_sel_hi:[0,1]
	v_pk_mul_f32 v[90:91], v[80:81], v[98:99] op_sel_hi:[0,1]
	v_pk_mul_f32 v[92:93], v[80:81], v[96:97] op_sel_hi:[0,1]
	v_pk_mul_f32 v[94:95], v[80:81], v[102:103] op_sel_hi:[0,1]
	v_pk_fma_f32 v[90:91], v[90:91], v[108:109], v[10:11]
	v_pk_fma_f32 v[88:89], v[88:89], v[110:111], v[8:9]
	v_pk_fma_f32 v[94:95], v[94:95], v[104:105], v[2:3]
	v_pk_fma_f32 v[92:93], v[92:93], v[106:107], v[0:1]
	v_lshl_add_u64 v[124:125], v[20:21], 0, s[46:47]
	v_pk_mul_f32 v[120:121], v[80:81], v[120:121] op_sel_hi:[0,1]
	v_pk_mul_f32 v[122:123], v[80:81], v[122:123] op_sel_hi:[0,1]
	v_pk_mul_f32 v[126:127], v[80:81], v[126:127] op_sel_hi:[0,1]
	v_pk_mul_f32 v[128:129], v[80:81], v[128:129] op_sel_hi:[0,1]
	v_cvt_pk_bf16_f32 v88, v88, v89
	v_cvt_pk_bf16_f32 v89, v90, v91
	v_cvt_pk_bf16_f32 v90, v92, v93
	v_cvt_pk_bf16_f32 v91, v94, v95
	v_fmamk_f32 v80, v189, 0x3a800000, v214
	flat_store_dwordx4 v[124:125], v[88:91] offset:1024 sc0 sc1
	v_cmp_gt_f32_e32 vcc, s51, v80
	v_mov_b32_e32 v95, v78
	v_mul_f32_e32 v88, 0x4f800000, v80
	v_cndmask_b32_e32 v80, v80, v88, vcc
	v_sqrt_f32_e32 v88, v80
	v_mov_b32_e32 v97, v86
	v_mov_b32_e32 v78, v75
	v_mov_b32_e32 v86, v85
	v_add_u32_e32 v89, -1, v88
	v_fma_f32 v90, -v89, v88, v80
	v_cmp_ge_f32_e64 s[36:37], 0, v90
	v_add_u32_e32 v90, 1, v88
	v_mov_b32_e32 v94, v74
	v_cndmask_b32_e64 v89, v88, v89, s[36:37]
	v_fma_f32 v88, -v90, v88, v80
	v_cmp_lt_f32_e64 s[36:37], 0, v88
	v_pk_fma_f32 v[122:123], v[116:117], v[122:123], v[14:15]
	v_pk_fma_f32 v[120:121], v[118:119], v[120:121], v[12:13]
	v_cndmask_b32_e64 v88, v89, v90, s[36:37]
	v_mul_f32_e32 v89, 0x37800000, v88
	v_cndmask_b32_e32 v88, v88, v89, vcc
	v_cmp_class_f32_e32 vcc, v80, v215
	v_mov_b32_e32 v96, v84
	v_pk_fma_f32 v[128:129], v[112:113], v[128:129], v[6:7]
	v_cndmask_b32_e32 v80, v88, v80, vcc
	v_div_scale_f32 v88, s[2:3], v80, v80, 1.0
	v_rcp_f32_e32 v89, v88
	v_pk_fma_f32 v[126:127], v[114:115], v[126:127], v[4:5]
	v_cvt_pk_bf16_f32 v154, v158, v159
	v_cvt_pk_bf16_f32 v155, v160, v161
	v_fma_f32 v90, -v88, v89, 1.0
	v_fmac_f32_e32 v89, v90, v89
	v_div_scale_f32 v90, vcc, 1.0, v80, 1.0
	v_mul_f32_e32 v91, v90, v89
	v_fma_f32 v92, -v88, v91, v90
	v_fmac_f32_e32 v91, v92, v89
	v_fma_f32 v88, -v88, v91, v90
; __device__ __forceinline__ unsigned pk2(float lo, float hi) { return pg8::cvt_pk_bf16(lo, hi); }
; __device__ __forceinline__ void unpack8(const u32x4 w, f32x4& a, f32x4& c) { a = (f32x4){bf_lo(w.x), bf_hi(w.x), bf_lo(w.y), bf_hi(w.y)}; c = (f32x4){bf_lo(w.z), bf_hi(w.z), bf_lo(w.w), bf_hi(w.w)}; }
; template <bool X_F32> __device__ __forceinline__ void phase_norm_mod(const Ctx& C, const void* xin, const float* modl, int shift_idx, int scale_idx) {
;     ...
;             for (int r = 0; r < NR; ++r) { const float rs = 1.0f / sqrtf(s[r] * (1.f / DM) + EPS);
; #pragma unroll
;                 for (int j = 0; j < 2; ++j) { f32x4 t0, t1; unpack8(raw[r][j], t0, t1);
;                     const f32x4 y0 = t0 * rs * g[2 * j] + a[2 * j], y1 = t1 * rs * g[2 * j + 1] + a[2 * j + 1];
;                     u32x4 w; w.x = pk2(y0.x, y0.y); w.y = pk2(y0.z, y0.w); w.z = pk2(y1.x, y1.y); w.w = pk2(y1.z, y1.w);
;                     ((u32x4*)(H + (size_t)(m0 + r) * DM + 512 * j))[lane] = w; } }
	v_div_fmas_f32 v88, v88, v89, v91
	v_div_fixup_f32 v80, v88, v80, 1.0
	v_mov_b32_e32 v89, v72
	v_mov_b32_e32 v91, v82
	v_mov_b32_e32 v72, v71
	v_mov_b32_e32 v82, v77
	v_mov_b32_e32 v88, v70
	v_mov_b32_e32 v90, v76
	v_pk_mul_f32 v[70:71], v[80:81], v[72:73] op_sel_hi:[0,1]
	v_pk_mul_f32 v[72:73], v[80:81], v[82:83] op_sel_hi:[0,1]
	v_pk_mul_f32 v[74:75], v[80:81], v[78:79] op_sel_hi:[0,1]
	v_pk_mul_f32 v[76:77], v[80:81], v[86:87] op_sel_hi:[0,1]
	v_pk_fma_f32 v[72:73], v[72:73], v[108:109], v[10:11]
	v_pk_fma_f32 v[70:71], v[70:71], v[110:111], v[8:9]
	v_pk_fma_f32 v[76:77], v[76:77], v[104:105], v[2:3]
	v_pk_fma_f32 v[74:75], v[74:75], v[106:107], v[0:1]
	v_lshl_add_u64 v[92:93], v[20:21], 0, s[44:45]
	v_cvt_pk_bf16_f32 v70, v70, v71
	v_cvt_pk_bf16_f32 v71, v72, v73
	v_cvt_pk_bf16_f32 v72, v74, v75
	v_cvt_pk_bf16_f32 v73, v76, v77
	flat_store_dwordx4 v[92:93], v[70:73] offset:1024 sc0 sc1
	v_mov_b32_e32 v79, v62
	v_mov_b32_e32 v83, v68
	v_fmamk_f32 v70, v188, 0x3a800000, v214
	v_cmp_gt_f32_e32 vcc, s51, v70
	v_mul_f32_e32 v71, 0x4f800000, v70
	v_mov_b32_e32 v62, v59
	v_cndmask_b32_e32 v70, v70, v71, vcc
	v_sqrt_f32_e32 v71, v70
	v_mov_b32_e32 v68, v67
	v_mov_b32_e32 v78, v58
	v_lshl_add_u64 v[76:77], v[20:21], 0, s[42:43]
	v_add_u32_e32 v72, -1, v71
	v_fma_f32 v73, -v72, v71, v70
	v_cmp_ge_f32_e64 s[36:37], 0, v73
	v_add_u32_e32 v73, 1, v71
	v_pk_mul_f32 v[88:89], v[80:81], v[88:89] op_sel_hi:[0,1]
	v_cndmask_b32_e64 v72, v71, v72, s[36:37]
	v_fma_f32 v71, -v73, v71, v70
	v_cmp_lt_f32_e64 s[36:37], 0, v71
	v_pk_mul_f32 v[90:91], v[80:81], v[90:91] op_sel_hi:[0,1]
	v_pk_fma_f32 v[90:91], v[116:117], v[90:91], v[14:15]
	v_cndmask_b32_e64 v71, v72, v73, s[36:37]
	v_mul_f32_e32 v72, 0x37800000, v71
	v_cndmask_b32_e32 v71, v71, v72, vcc
	v_cmp_class_f32_e32 vcc, v70, v215
	v_pk_fma_f32 v[88:89], v[118:119], v[88:89], v[12:13]
	v_mov_b32_e32 v82, v66
	v_cndmask_b32_e32 v70, v71, v70, vcc
	v_div_scale_f32 v71, s[2:3], v70, v70, 1.0
	v_rcp_f32_e32 v72, v71
	v_pk_mul_f32 v[96:97], v[80:81], v[96:97] op_sel_hi:[0,1]
	v_pk_mul_f32 v[94:95], v[80:81], v[94:95] op_sel_hi:[0,1]
	v_pk_fma_f32 v[96:97], v[112:113], v[96:97], v[6:7]
	v_fma_f32 v73, -v71, v72, 1.0
	v_fmac_f32_e32 v72, v73, v72
	v_div_scale_f32 v73, vcc, 1.0, v70, 1.0
	v_mul_f32_e32 v74, v73, v72
	v_fma_f32 v75, -v71, v74, v73
	v_fmac_f32_e32 v74, v75, v72
	v_fma_f32 v71, -v71, v74, v73
	v_div_fmas_f32 v71, v71, v72, v74
	v_div_fixup_f32 v70, v71, v70, 1.0
	v_mov_b32_e32 v73, v56
	v_mov_b32_e32 v75, v64
	v_mov_b32_e32 v56, v55
	v_mov_b32_e32 v64, v61
	v_mov_b32_e32 v72, v54
	v_mov_b32_e32 v74, v60
	v_pk_mul_f32 v[54:55], v[70:71], v[56:57] op_sel_hi:[0,1]
	v_pk_mul_f32 v[56:57], v[70:71], v[64:65] op_sel_hi:[0,1]
	v_pk_mul_f32 v[58:59], v[70:71], v[62:63] op_sel_hi:[0,1]
	v_pk_mul_f32 v[60:61], v[70:71], v[68:69] op_sel_hi:[0,1]
	v_pk_fma_f32 v[56:57], v[108:109], v[56:57], v[10:11]
	v_pk_fma_f32 v[54:55], v[110:111], v[54:55], v[8:9]
	v_pk_fma_f32 v[60:61], v[60:61], v[104:105], v[2:3]
	v_pk_fma_f32 v[58:59], v[58:59], v[106:107], v[0:1]
	v_cvt_pk_bf16_f32 v54, v54, v55
	v_cvt_pk_bf16_f32 v55, v56, v57
	v_cvt_pk_bf16_f32 v56, v58, v59
	v_cvt_pk_bf16_f32 v57, v60, v61
	flat_store_dwordx4 v[76:77], v[54:57] offset:1024 sc0 sc1
	v_mov_b32_e32 v63, v46
	v_mov_b32_e32 v65, v52
	v_fmamk_f32 v54, v187, 0x3a800000, v214
	v_cmp_gt_f32_e32 vcc, s51, v54
	v_mul_f32_e32 v55, 0x4f800000, v54
	v_mov_b32_e32 v46, v43
	v_cndmask_b32_e32 v54, v54, v55, vcc
	v_sqrt_f32_e32 v55, v54
	v_mov_b32_e32 v52, v51
	v_mov_b32_e32 v62, v42
	v_lshl_add_u64 v[60:61], v[20:21], 0, s[40:41]
	v_add_u32_e32 v56, -1, v55
	v_fma_f32 v57, -v56, v55, v54
	v_cmp_ge_f32_e64 s[36:37], 0, v57
	v_add_u32_e32 v57, 1, v55
	v_pk_mul_f32 v[72:73], v[70:71], v[72:73] op_sel_hi:[0,1]
	v_cndmask_b32_e64 v56, v55, v56, s[36:37]
	v_fma_f32 v55, -v57, v55, v54
	v_cmp_lt_f32_e64 s[36:37], 0, v55
	v_pk_mul_f32 v[74:75], v[70:71], v[74:75] op_sel_hi:[0,1]
	v_pk_fma_f32 v[74:75], v[116:117], v[74:75], v[14:15]
	v_cndmask_b32_e64 v55, v56, v57, s[36:37]
	v_mul_f32_e32 v56, 0x37800000, v55
	v_cndmask_b32_e32 v55, v55, v56, vcc
	v_cmp_class_f32_e32 vcc, v54, v215
	v_pk_fma_f32 v[72:73], v[118:119], v[72:73], v[12:13]
	v_mov_b32_e32 v64, v50
	v_cndmask_b32_e32 v54, v55, v54, vcc
	v_div_scale_f32 v55, s[2:3], v54, v54, 1.0
	v_rcp_f32_e32 v56, v55
	v_pk_mul_f32 v[82:83], v[70:71], v[82:83] op_sel_hi:[0,1]
	v_pk_mul_f32 v[78:79], v[70:71], v[78:79] op_sel_hi:[0,1]
	v_pk_fma_f32 v[82:83], v[112:113], v[82:83], v[6:7]
	v_fma_f32 v57, -v55, v56, 1.0
	v_fmac_f32_e32 v56, v57, v56
	v_div_scale_f32 v57, vcc, 1.0, v54, 1.0
	v_mul_f32_e32 v58, v57, v56
	v_fma_f32 v59, -v55, v58, v57
	v_fmac_f32_e32 v58, v59, v56
	v_fma_f32 v55, -v55, v58, v57
	v_div_fmas_f32 v55, v55, v56, v58
	v_div_fixup_f32 v54, v55, v54, 1.0
	v_mov_b32_e32 v57, v40
	v_mov_b32_e32 v59, v48
	v_mov_b32_e32 v40, v39
	v_mov_b32_e32 v48, v45
; __device__ __forceinline__ unsigned pk2(float lo, float hi) { return pg8::cvt_pk_bf16(lo, hi); }
; __device__ __forceinline__ void unpack8(const u32x4 w, f32x4& a, f32x4& c) { a = (f32x4){bf_lo(w.x), bf_hi(w.x), bf_lo(w.y), bf_hi(w.y)}; c = (f32x4){bf_lo(w.z), bf_hi(w.z), bf_lo(w.w), bf_hi(w.w)}; }
; template <bool X_F32> __device__ __forceinline__ void phase_norm_mod(const Ctx& C, const void* xin, const float* modl, int shift_idx, int scale_idx) {
;     ...
;             for (int r = 0; r < NR; ++r) { const float rs = 1.0f / sqrtf(s[r] * (1.f / DM) + EPS);
; #pragma unroll
;                 for (int j = 0; j < 2; ++j) { f32x4 t0, t1; unpack8(raw[r][j], t0, t1);
;                     const f32x4 y0 = t0 * rs * g[2 * j] + a[2 * j], y1 = t1 * rs * g[2 * j + 1] + a[2 * j + 1];
;                     u32x4 w; w.x = pk2(y0.x, y0.y); w.y = pk2(y0.z, y0.w); w.z = pk2(y1.x, y1.y); w.w = pk2(y1.z, y1.w);
;                     ((u32x4*)(H + (size_t)(m0 + r) * DM + 512 * j))[lane] = w; } }
;         }
	v_mov_b32_e32 v56, v38
	v_mov_b32_e32 v58, v44
	v_pk_mul_f32 v[38:39], v[54:55], v[40:41] op_sel_hi:[0,1]
	v_pk_mul_f32 v[40:41], v[54:55], v[48:49] op_sel_hi:[0,1]
	v_pk_mul_f32 v[42:43], v[54:55], v[46:47] op_sel_hi:[0,1]
	v_pk_mul_f32 v[44:45], v[54:55], v[52:53] op_sel_hi:[0,1]
	v_pk_fma_f32 v[40:41], v[108:109], v[40:41], v[10:11]
	v_pk_fma_f32 v[38:39], v[110:111], v[38:39], v[8:9]
	v_pk_fma_f32 v[44:45], v[44:45], v[104:105], v[2:3]
	v_pk_fma_f32 v[42:43], v[42:43], v[106:107], v[0:1]
	v_cvt_pk_bf16_f32 v38, v38, v39
	v_cvt_pk_bf16_f32 v39, v40, v41
	v_cvt_pk_bf16_f32 v40, v42, v43
	v_cvt_pk_bf16_f32 v41, v44, v45
	flat_store_dwordx4 v[60:61], v[38:41] offset:1024 sc0 sc1
	v_mov_b32_e32 v44, v28
	v_mov_b32_e32 v45, v32
	v_fmamk_f32 v38, v186, 0x3a800000, v214
	v_cmp_gt_f32_e32 vcc, s51, v38
	v_mul_f32_e32 v39, 0x4f800000, v38
	v_pk_mul_f32 v[56:57], v[54:55], v[56:57] op_sel_hi:[0,1]
	v_cndmask_b32_e32 v38, v38, v39, vcc
	v_sqrt_f32_e32 v39, v38
	v_pk_mul_f32 v[58:59], v[54:55], v[58:59] op_sel_hi:[0,1]
	v_pk_fma_f32 v[58:59], v[116:117], v[58:59], v[14:15]
	v_pk_fma_f32 v[56:57], v[118:119], v[56:57], v[12:13]
	v_add_u32_e32 v40, -1, v39
	v_fma_f32 v41, -v40, v39, v38
	v_cmp_ge_f32_e64 s[36:37], 0, v41
	v_add_u32_e32 v41, 1, v39
	v_pk_mul_f32 v[64:65], v[54:55], v[64:65] op_sel_hi:[0,1]
	v_cndmask_b32_e64 v40, v39, v40, s[36:37]
	v_fma_f32 v39, -v41, v39, v38
	v_cmp_lt_f32_e64 s[36:37], 0, v39
	v_pk_mul_f32 v[62:63], v[54:55], v[62:63] op_sel_hi:[0,1]
	v_pk_fma_f32 v[64:65], v[112:113], v[64:65], v[6:7]
	v_cndmask_b32_e64 v39, v40, v41, s[36:37]
	v_mul_f32_e32 v40, 0x37800000, v39
	v_cndmask_b32_e32 v39, v39, v40, vcc
	v_cmp_class_f32_e32 vcc, v38, v215
	v_pk_fma_f32 v[94:95], v[114:115], v[94:95], v[4:5]
	v_pk_fma_f32 v[78:79], v[114:115], v[78:79], v[4:5]
	v_cndmask_b32_e32 v38, v39, v38, vcc
	v_div_scale_f32 v39, s[2:3], v38, v38, 1.0
	v_rcp_f32_e32 v40, v39
	v_pk_fma_f32 v[62:63], v[114:115], v[62:63], v[4:5]
	v_mov_b32_e32 v32, v29
	s_add_i32 s2, s12, s13
	v_fma_f32 v41, -v39, v40, 1.0
	v_fmac_f32_e32 v40, v41, v40
	v_div_scale_f32 v41, vcc, 1.0, v38, 1.0
	v_mul_f32_e32 v42, v41, v40
	v_fma_f32 v43, -v39, v42, v41
	v_fmac_f32_e32 v42, v43, v40
	v_fma_f32 v39, -v39, v42, v41
	v_div_fmas_f32 v39, v39, v40, v42
	v_div_fixup_f32 v38, v39, v38, 1.0
	v_mov_b32_e32 v42, v22
	v_mov_b32_e32 v43, v24
	v_pk_mul_f32 v[42:43], v[38:39], v[42:43] op_sel_hi:[0,1]
	v_pk_mul_f32 v[44:45], v[38:39], v[44:45] op_sel_hi:[0,1]
	v_pk_fma_f32 v[14:15], v[116:117], v[44:45], v[14:15]
	v_pk_fma_f32 v[12:13], v[118:119], v[42:43], v[12:13]
	v_mov_b32_e32 v42, v26
	v_mov_b32_e32 v43, v30
	v_mov_b32_e32 v44, v34
	v_mov_b32_e32 v45, v36
	v_pk_mul_f32 v[42:43], v[38:39], v[42:43] op_sel_hi:[0,1]
	v_pk_mul_f32 v[44:45], v[38:39], v[44:45] op_sel_hi:[0,1]
	v_pk_fma_f32 v[44:45], v[112:113], v[44:45], v[6:7]
	v_pk_fma_f32 v[6:7], v[114:115], v[42:43], v[4:5]
	v_lshl_add_u64 v[40:41], v[20:21], 0, s[38:39]
	v_cvt_pk_bf16_f32 v4, v12, v13
	v_cvt_pk_bf16_f32 v5, v14, v15
	v_cvt_pk_bf16_f32 v6, v6, v7
	v_cvt_pk_bf16_f32 v7, v44, v45
	v_mov_b32_e32 v24, v23
	flat_store_dwordx4 v[40:41], v[4:7] sc0 sc1
	v_mov_b32_e32 v30, v27
	v_mov_b32_e32 v36, v35
	v_pk_mul_f32 v[4:5], v[38:39], v[24:25] op_sel_hi:[0,1]
	v_pk_mul_f32 v[6:7], v[38:39], v[32:33] op_sel_hi:[0,1]
	v_pk_fma_f32 v[6:7], v[108:109], v[6:7], v[10:11]
	v_pk_fma_f32 v[4:5], v[110:111], v[4:5], v[8:9]
	v_pk_mul_f32 v[8:9], v[38:39], v[30:31] op_sel_hi:[0,1]
	v_pk_mul_f32 v[10:11], v[38:39], v[36:37] op_sel_hi:[0,1]
	v_pk_fma_f32 v[10:11], v[104:105], v[10:11], v[2:3]
	v_pk_fma_f32 v[2:3], v[106:107], v[8:9], v[0:1]
	v_cvt_pk_bf16_f32 v136, v136, v137
	v_cvt_pk_bf16_f32 v137, v138, v139
	v_cvt_pk_bf16_f32 v138, v142, v143
	v_cvt_pk_bf16_f32 v139, v144, v145
	v_cvt_pk_bf16_f32 v120, v120, v121
	v_cvt_pk_bf16_f32 v121, v122, v123
	v_cvt_pk_bf16_f32 v122, v126, v127
	v_cvt_pk_bf16_f32 v123, v128, v129
	v_cvt_pk_bf16_f32 v88, v88, v89
	v_cvt_pk_bf16_f32 v89, v90, v91
	v_cvt_pk_bf16_f32 v90, v94, v95
	v_cvt_pk_bf16_f32 v91, v96, v97
	v_cvt_pk_bf16_f32 v72, v72, v73
	v_cvt_pk_bf16_f32 v73, v74, v75
	v_cvt_pk_bf16_f32 v74, v78, v79
	v_cvt_pk_bf16_f32 v75, v82, v83
	v_cvt_pk_bf16_f32 v56, v56, v57
	v_cvt_pk_bf16_f32 v57, v58, v59
	v_cvt_pk_bf16_f32 v58, v62, v63
	v_cvt_pk_bf16_f32 v59, v64, v65
	v_cvt_pk_bf16_f32 v0, v4, v5
	v_cvt_pk_bf16_f32 v1, v6, v7
	v_cvt_pk_bf16_f32 v2, v2, v3
	v_cvt_pk_bf16_f32 v3, v10, v11
	s_cmpk_lt_i32 s2, 0x1000
	flat_store_dwordx4 v[198:199], v[194:197] sc0 sc1
	flat_store_dwordx4 v[156:157], v[152:155] sc0 sc1
	flat_store_dwordx4 v[140:141], v[136:139] sc0 sc1
	flat_store_dwordx4 v[124:125], v[120:123] sc0 sc1
	flat_store_dwordx4 v[92:93], v[88:91] sc0 sc1
	flat_store_dwordx4 v[76:77], v[72:75] sc0 sc1
	flat_store_dwordx4 v[60:61], v[56:59] sc0 sc1
	flat_store_dwordx4 v[40:41], v[0:3] offset:1024 sc0 sc1
	s_cbranch_scc1 .LBB0_129

; template <bool X_F32> __device__ __forceinline__ void phase_norm_mod(const Ctx& C, const void* xin, const float* modl, int shift_idx, int scale_idx) {
;     ...
;         for (int r0_ = (gw % (NGW >> 3)) * NRW; r0_ < T / 8; r0_ += (NGW >> 3) * NRW) { const int m0 = (gw / (NGW >> 3)) * (T / 8) + r0_;
;             const int b = m0 >> 12;
;             f32x4 v[NRW][4]; float s[NRW];
; #pragma unroll
;             for (int r = 0; r < NRW; ++r) { s[r] = 0.f;
; #pragma unroll
;                 for (int j = 0; j < 2; ++j) { const f32x4* xr = (const f32x4*)((const float*)xin + (size_t)(m0 + r) * DM + 512 * j + 8 * lane); v[r][2 * j] = xr[0]; v[r][2 * j + 1] = xr[1];
; #pragma unroll
;                     for (int q = 0; q < 2; ++q) { const f32x4 t = v[r][2 * j + q]; s[r] += (t.x * t.x + t.y * t.y) + (t.z * t.z + t.w * t.w); } } }
;             wave_sumN<NRW>(s);
;             f32x4 a[4], g[4];
; #pragma unroll
;             for (int j = 0; j < 2; ++j)
; #pragma unroll
;                 for (int q = 0; q < 2; ++q) { a[2 * j + q] = *(const f32x4*)(modl + (size_t)b * NMOD + shift_idx * DM + 512 * j + 8 * lane + 4 * q);
;                     g[2 * j + q] = *(const f32x4*)(modl + (size_t)b * NMOD + scale_idx * DM + 512 * j + 8 * lane + 4 * q) + 1.0f; }
.LBB0_134:
	s_add_i32 s20, s10, s48
	s_ashr_i32 s21, s20, 31
	s_lshl_b64 s[36:37], s[20:21], 12
	v_lshl_add_u64 v[0:1], v[70:71], 0, s[36:37]
	global_load_dwordx4 v[60:63], v[0:1], off
	global_load_dwordx4 v[52:55], v[0:1], off offset:16
	global_load_dwordx4 v[48:51], v[0:1], off offset:2064
	global_load_dwordx4 v[56:59], v[0:1], off offset:2048
	s_add_i32 s12, s20, 1
	s_add_i32 s4, s20, 2
	s_add_i32 s14, s20, 3
	s_ashr_i32 s13, s12, 31
	s_ashr_i32 s5, s4, 31
	s_ashr_i32 s15, s14, 31
	s_lshl_b64 s[36:37], s[12:13], 12
	s_lshl_b64 s[38:39], s[4:5], 12
	s_lshl_b64 s[40:41], s[14:15], 12
	v_lshl_add_u64 v[8:9], v[70:71], 0, s[36:37]
	v_lshl_add_u64 v[10:11], v[70:71], 0, s[38:39]
	v_lshl_add_u64 v[12:13], v[70:71], 0, s[40:41]
	global_load_dwordx4 v[36:39], v[8:9], off
	global_load_dwordx4 v[32:35], v[8:9], off offset:16
	global_load_dwordx4 v[20:23], v[10:11], off
	global_load_dwordx4 v[16:19], v[10:11], off offset:16
	global_load_dwordx4 v[4:7], v[12:13], off
	global_load_dwordx4 v[0:3], v[12:13], off offset:16
	global_load_dwordx4 v[40:43], v[8:9], off offset:2064
	global_load_dwordx4 v[44:47], v[8:9], off offset:2048
	global_load_dwordx4 v[24:27], v[10:11], off offset:2064
	global_load_dwordx4 v[28:31], v[10:11], off offset:2048
	s_nop 0
	global_load_dwordx4 v[8:11], v[12:13], off offset:2064
	s_nop 0
	global_load_dwordx4 v[12:15], v[12:13], off offset:2048
	s_ashr_i32 s3, s20, 12
	s_mul_hi_i32 s42, s3, 0x6000
	s_mulk_i32 s3, 0x6000
	s_add_u32 s36, s78, s3
	s_addc_u32 s37, s1, s42
	v_lshl_add_u64 v[100:101], v[68:69], 2, s[36:37]
	v_add_co_u32_e32 v64, vcc, s49, v100
	v_lshl_add_u64 v[76:77], v[100:101], 0, s[90:91]
	s_nop 0
	v_addc_co_u32_e32 v65, vcc, 0, v101, vcc
	global_load_dwordx4 v[82:85], v[64:65], off
	s_lshl_b64 s[4:5], s[4:5], 11
	s_lshl_b64 s[20:21], s[20:21], 11
	s_lshl_b64 s[12:13], s[12:13], 11
	v_lshl_add_u64 v[74:75], v[72:73], 0, s[20:21]
	s_add_i32 s19, s19, s2
	s_lshl_b64 s[14:15], s[14:15], 11
	s_add_i32 s48, s48, s2
	s_add_i32 s3, s10, s19
	s_cmpk_gt_i32 s3, 0xfff
	s_waitcnt vmcnt(0)
	v_pk_mul_f32 v[64:65], v[62:63], v[62:63]
	v_pk_mul_f32 v[66:67], v[60:61], v[60:61]
	v_pk_mul_f32 v[78:79], v[54:55], v[54:55]
	v_pk_mul_f32 v[86:87], v[52:53], v[52:53]
	v_mul_f32_e32 v88, v57, v57
	v_mul_f32_e32 v90, v59, v59
	v_mul_f32_e32 v123, v50, v50
	v_mul_f32_e32 v124, v51, v51
	v_pk_mov_b32 v[92:93], v[66:67], v[64:65] op_sel:[1,0]
	v_mov_b32_e32 v67, v65
	v_pk_mov_b32 v[64:65], v[86:87], v[78:79] op_sel:[1,0]
	v_mov_b32_e32 v87, v79
	v_pk_fma_f32 v[78:79], v[56:57], v[56:57], v[88:89] op_sel_hi:[1,1,0]
	v_pk_fma_f32 v[90:91], v[58:59], v[58:59], v[90:91] op_sel_hi:[1,1,0]
	v_mov_b32_e32 v79, v123
	v_mov_b32_e32 v91, v124
	v_pk_mul_f32 v[88:89], v[38:39], v[38:39]
	v_pk_mul_f32 v[94:95], v[36:37], v[36:37]
	v_pk_add_f32 v[116:117], v[64:65], v[86:87]
	v_pk_add_f32 v[64:65], v[78:79], v[90:91]
	v_mul_f32_e32 v78, v45, v45
	v_pk_mul_f32 v[96:97], v[34:35], v[34:35]
	v_pk_mul_f32 v[98:99], v[32:33], v[32:33]
	v_pk_mul_f32 v[102:103], v[22:23], v[22:23]
	v_pk_mul_f32 v[104:105], v[20:21], v[20:21]
	v_pk_mul_f32 v[106:107], v[18:19], v[18:19]
	v_pk_mul_f32 v[108:109], v[16:17], v[16:17]
	v_pk_mul_f32 v[110:111], v[6:7], v[6:7]
	v_pk_mul_f32 v[112:113], v[4:5], v[4:5]
	v_pk_mul_f32 v[114:115], v[2:3], v[2:3]
	v_pk_add_f32 v[66:67], v[92:93], v[66:67]
	v_pk_mul_f32 v[92:93], v[0:1], v[0:1]
	v_pk_mov_b32 v[124:125], v[94:95], v[88:89] op_sel:[1,0]
	v_mov_b32_e32 v95, v89
	v_mul_f32_e32 v91, v42, v42
	v_mul_f32_e32 v90, v47, v47
	v_pk_fma_f32 v[78:79], v[44:45], v[44:45], v[78:79] op_sel_hi:[1,1,0]
	v_pk_mov_b32 v[126:127], v[98:99], v[96:97] op_sel:[1,0]
	v_mov_b32_e32 v99, v97
	v_pk_mov_b32 v[96:97], v[104:105], v[102:103] op_sel:[1,0]
	v_mov_b32_e32 v105, v103
	v_pk_mov_b32 v[102:103], v[108:109], v[106:107] op_sel:[1,0]
	v_mov_b32_e32 v109, v107
	v_pk_mov_b32 v[128:129], v[112:113], v[110:111] op_sel:[1,0]
	v_mov_b32_e32 v113, v111
	v_pk_mov_b32 v[130:131], v[92:93], v[114:115] op_sel:[1,0]
	v_mov_b32_e32 v93, v115
	v_pk_add_f32 v[106:107], v[124:125], v[94:95]
	v_mul_f32_e32 v95, v43, v43
	v_mov_b32_e32 v79, v91
	v_mul_f32_e32 v94, v29, v29
	v_pk_fma_f32 v[90:91], v[46:47], v[46:47], v[90:91] op_sel_hi:[1,1,0]
	v_pk_add_f32 v[96:97], v[96:97], v[104:105]
	v_mul_f32_e32 v104, v26, v26
	v_pk_add_f32 v[110:111], v[102:103], v[108:109]
	v_pk_add_f32 v[108:109], v[128:129], v[112:113]
	v_mov_b32_e32 v91, v95
	v_pk_fma_f32 v[94:95], v[28:29], v[28:29], v[94:95] op_sel_hi:[1,1,0]
	v_pk_add_f32 v[112:113], v[130:131], v[92:93]
	v_mul_f32_e32 v92, v13, v13
	v_mul_f32_e32 v102, v31, v31
	v_mov_b32_e32 v95, v104
	v_pk_fma_f32 v[104:105], v[12:13], v[12:13], v[92:93] op_sel_hi:[1,1,0]
	v_mul_f32_e32 v92, v15, v15
	v_mul_f32_e32 v114, v27, v27
	v_mul_f32_e32 v115, v10, v10
	v_mul_f32_e32 v124, v11, v11
	v_pk_fma_f32 v[102:103], v[30:31], v[30:31], v[102:103] op_sel_hi:[1,1,0]
	v_pk_fma_f32 v[128:129], v[14:15], v[14:15], v[92:93] op_sel_hi:[1,1,0]
	v_mul_f32_e32 v92, v49, v49
	v_pk_add_f32 v[116:117], v[116:117], v[116:117] op_sel:[0,1] op_sel_hi:[1,0]
	global_load_dwordx4 v[86:89], v[76:77], off offset:16
	v_pk_add_f32 v[98:99], v[126:127], v[98:99]
	v_mov_b32_e32 v103, v114
	v_mov_b32_e32 v105, v115
	v_mov_b32_e32 v129, v124
	v_pk_add_f32 v[114:115], v[66:67], v[66:67] op_sel:[0,1] op_sel_hi:[1,0]
	v_mov_b32_e32 v117, v92
	v_pk_add_f32 v[66:67], v[78:79], v[90:91]
	global_load_dwordx4 v[90:93], v[76:77], off offset:2048
	global_load_dwordx4 v[124:127], v[76:77], off offset:2064
	v_mul_f32_e32 v123, v48, v48
	v_mov_b32_e32 v115, v123
	v_pk_add_f32 v[114:115], v[114:115], v[116:117]
	v_mul_f32_e32 v116, v40, v40
	v_pk_add_f32 v[106:107], v[106:107], v[106:107] op_sel:[0,1] op_sel_hi:[1,0]
	v_pk_add_f32 v[76:77], v[84:85], 1.0 op_sel_hi:[1,0]
	v_pk_add_f32 v[78:79], v[82:83], 1.0 op_sel_hi:[1,0]
	v_mul_f32_e32 v123, v41, v41
	v_mov_b32_e32 v107, v116
	v_pk_add_f32 v[116:117], v[98:99], v[98:99] op_sel:[0,1] op_sel_hi:[1,0]
	v_mul_f32_e32 v98, v25, v25
	v_pk_add_f32 v[110:111], v[110:111], v[110:111] op_sel:[0,1] op_sel_hi:[1,0]
	v_mov_b32_e32 v117, v123
	v_mov_b32_e32 v111, v98
	v_pk_add_f32 v[108:109], v[108:109], v[108:109] op_sel:[0,1] op_sel_hi:[1,0]
	v_pk_add_f32 v[112:113], v[112:113], v[112:113] op_sel:[0,1] op_sel_hi:[1,0]
	v_pk_add_f32 v[102:103], v[94:95], v[102:103]
	v_pk_add_f32 v[64:65], v[114:115], v[64:65]
	v_pk_add_f32 v[106:107], v[106:107], v[116:117]
	v_pk_add_f32 v[104:105], v[104:105], v[128:129]
	v_lshl_add_u64 v[98:99], v[72:73], 0, s[4:5]
	v_lshl_add_u64 v[94:95], v[72:73], 0, s[12:13]
	s_waitcnt vmcnt(0)
; template <int NR> __device__ __forceinline__ void wave_sumN(float (&s)[NR]) {
; #pragma unroll
;     for (int o = 1; o < 64; o <<= 1) {
;         float t[NR];
; #pragma unroll
;         for (int r = 0; r < NR; ++r) t[r] = __shfl_xor(s[r], o);
; #pragma unroll
;         for (int r = 0; r < NR; ++r) s[r] += t[r];
;     }
; }
; template <bool X_F32> __device__ __forceinline__ void phase_norm_mod(const Ctx& C, const void* xin, const float* modl, int shift_idx, int scale_idx) {
;     ...
;                 for (int q = 0; q < 2; ++q) { a[2 * j + q] = *(const f32x4*)(modl + (size_t)b * NMOD + shift_idx * DM + 512 * j + 8 * lane + 4 * q);
;                     g[2 * j + q] = *(const f32x4*)(modl + (size_t)b * NMOD + scale_idx * DM + 512 * j + 8 * lane + 4 * q) + 1.0f; }
; #pragma unroll
;             for (int r = 0; r < NRW; ++r) { const float rs = 1.0f / sqrtf(s[r] * (1.f / DM) + EPS);
	v_pk_add_f32 v[82:83], v[88:89], 1.0 op_sel_hi:[1,0]
	v_pk_add_f32 v[84:85], v[86:87], 1.0 op_sel_hi:[1,0]
	v_pk_add_f32 v[86:87], v[92:93], 1.0 op_sel_hi:[1,0]
	v_pk_add_f32 v[88:89], v[90:91], 1.0 op_sel_hi:[1,0]
	v_pk_add_f32 v[90:91], v[126:127], 1.0 op_sel_hi:[1,0]
	v_pk_add_f32 v[92:93], v[124:125], 1.0 op_sel_hi:[1,0]
	v_mul_f32_e32 v126, v24, v24
	v_pk_add_f32 v[124:125], v[96:97], v[96:97] op_sel:[0,1] op_sel_hi:[1,0]
	v_mul_f32_e32 v96, v8, v8
	v_mov_b32_e32 v125, v126
	v_mul_f32_e32 v97, v9, v9
	v_mov_b32_e32 v109, v96
	v_mov_b32_e32 v113, v97
	v_pk_add_f32 v[110:111], v[124:125], v[110:111]
	v_pk_add_f32 v[108:109], v[108:109], v[112:113]
	v_add_f32_e32 v112, v64, v65
	v_pk_add_f32 v[64:65], v[106:107], v[66:67]
	v_pk_add_f32 v[66:67], v[110:111], v[102:103]
	v_pk_add_f32 v[102:103], v[108:109], v[104:105]
	v_add_f32_e32 v64, v64, v65
	v_add_f32_e32 v65, v66, v67
	ds_bpermute_b32 v67, v80, v112
	v_add_f32_e32 v66, v102, v103
	ds_bpermute_b32 v102, v80, v64
	ds_bpermute_b32 v103, v80, v65
	ds_bpermute_b32 v104, v80, v66
	s_waitcnt lgkmcnt(0)
	v_add_f32_e32 v67, v112, v67
	v_lshl_add_u64 v[96:97], v[72:73], 0, s[14:15]
	v_add_f32_e32 v64, v64, v102
	ds_bpermute_b32 v102, v118, v67
	v_add_f32_e32 v65, v65, v103
	v_add_f32_e32 v66, v66, v104
	ds_bpermute_b32 v103, v118, v64
	ds_bpermute_b32 v104, v118, v65
	ds_bpermute_b32 v105, v118, v66
	s_waitcnt lgkmcnt(3)
	v_add_f32_e32 v67, v67, v102
	ds_bpermute_b32 v102, v119, v67
	s_waitcnt lgkmcnt(3)
	v_add_f32_e32 v64, v64, v103
	s_waitcnt lgkmcnt(2)
	v_add_f32_e32 v65, v65, v104
	s_waitcnt lgkmcnt(1)
	v_add_f32_e32 v66, v66, v105
	ds_bpermute_b32 v103, v119, v64
	ds_bpermute_b32 v104, v119, v65
	ds_bpermute_b32 v105, v119, v66
	s_waitcnt lgkmcnt(3)
	v_add_f32_e32 v67, v67, v102
	ds_bpermute_b32 v102, v120, v67
	s_waitcnt lgkmcnt(3)
	v_add_f32_e32 v64, v64, v103
	s_waitcnt lgkmcnt(2)
	v_add_f32_e32 v65, v65, v104
	s_waitcnt lgkmcnt(1)
	v_add_f32_e32 v66, v66, v105
	ds_bpermute_b32 v103, v120, v64
	ds_bpermute_b32 v104, v120, v65
	ds_bpermute_b32 v105, v120, v66
	s_waitcnt lgkmcnt(3)
	v_add_f32_e32 v67, v67, v102
	ds_bpermute_b32 v102, v121, v67
	s_waitcnt lgkmcnt(3)
	v_add_f32_e32 v64, v64, v103
	s_waitcnt lgkmcnt(2)
	v_add_f32_e32 v65, v65, v104
	s_waitcnt lgkmcnt(1)
	v_add_f32_e32 v66, v66, v105
	ds_bpermute_b32 v103, v121, v64
	ds_bpermute_b32 v104, v121, v65
	ds_bpermute_b32 v105, v121, v66
	s_waitcnt lgkmcnt(3)
	v_add_f32_e32 v67, v67, v102
	ds_bpermute_b32 v102, v122, v67
	s_waitcnt lgkmcnt(3)
	v_add_f32_e32 v64, v64, v103
	s_waitcnt lgkmcnt(2)
	v_add_f32_e32 v65, v65, v104
	s_waitcnt lgkmcnt(1)
	v_add_f32_e32 v66, v66, v105
	ds_bpermute_b32 v103, v122, v64
	ds_bpermute_b32 v104, v122, v65
	ds_bpermute_b32 v105, v122, v66
	s_waitcnt lgkmcnt(3)
	v_add_f32_e32 v67, v67, v102
	v_fmamk_f32 v67, v67, 0x3a800000, v214
	s_waitcnt lgkmcnt(2)
	v_add_f32_e32 v64, v64, v103
	v_mul_f32_e32 v102, 0x4f800000, v67
	v_cmp_gt_f32_e32 vcc, s50, v67
	s_waitcnt lgkmcnt(1)
	v_add_f32_e32 v65, v65, v104
	s_waitcnt lgkmcnt(0)
	v_add_f32_e32 v66, v66, v105
	v_fmamk_f32 v64, v64, 0x3a800000, v214
	v_cndmask_b32_e32 v67, v67, v102, vcc
	v_fmamk_f32 v65, v65, 0x3a800000, v214
	v_fmamk_f32 v66, v66, 0x3a800000, v214
	v_mul_f32_e32 v102, 0x4f800000, v64
	v_cmp_gt_f32_e64 s[36:37], s50, v64
	v_sqrt_f32_e32 v105, v67
	v_mul_f32_e32 v103, 0x4f800000, v65
	v_cmp_gt_f32_e64 s[38:39], s50, v65
	v_mul_f32_e32 v104, 0x4f800000, v66
	v_cmp_gt_f32_e64 s[40:41], s50, v66
	v_cndmask_b32_e64 v64, v64, v102, s[36:37]
	v_cndmask_b32_e64 v65, v65, v103, s[38:39]
	v_cndmask_b32_e64 v66, v66, v104, s[40:41]
	v_sqrt_f32_e32 v102, v64
	v_sqrt_f32_e32 v103, v65
	v_sqrt_f32_e32 v104, v66
	v_add_u32_e32 v106, -1, v105
	v_add_u32_e32 v107, 1, v105
	v_fma_f32 v108, -v106, v105, v67
	v_fma_f32 v109, -v107, v105, v67
	v_add_u32_e32 v110, -1, v102
	v_cmp_ge_f32_e64 s[42:43], 0, v108
	v_add_u32_e32 v111, 1, v102
	v_add_u32_e32 v112, -1, v103
	v_add_u32_e32 v114, -1, v104
	v_cndmask_b32_e64 v105, v105, v106, s[42:43]
	v_cmp_lt_f32_e64 s[42:43], 0, v109
	v_fma_f32 v106, -v110, v102, v64
	v_add_u32_e32 v113, 1, v103
	v_add_u32_e32 v115, 1, v104
	v_fma_f32 v108, -v111, v102, v64
	v_fma_f32 v109, -v112, v103, v65
	v_fma_f32 v117, -v114, v104, v66
	v_cndmask_b32_e64 v105, v105, v107, s[42:43]
	v_cmp_ge_f32_e64 s[42:43], 0, v106
	v_fma_f32 v116, -v113, v103, v65
	v_fma_f32 v107, -v115, v104, v66
	v_cndmask_b32_e64 v102, v102, v110, s[42:43]
	v_cmp_lt_f32_e64 s[42:43], 0, v108
	v_cmp_ge_f32_e64 s[44:45], 0, v109
	v_cmp_ge_f32_e64 s[46:47], 0, v117
	v_mul_f32_e32 v106, 0x37800000, v105
	v_cndmask_b32_e64 v103, v103, v112, s[44:45]
	v_cmp_lt_f32_e64 s[44:45], 0, v116
	v_cndmask_b32_e64 v104, v104, v114, s[46:47]
	v_cmp_lt_f32_e64 s[46:47], 0, v107
	v_cndmask_b32_e64 v107, v102, v111, s[42:43]
	v_cndmask_b32_e32 v102, v105, v106, vcc
	v_cmp_class_f32_e32 vcc, v67, v215
	v_cndmask_b32_e64 v103, v103, v113, s[44:45]
	v_mul_f32_e32 v105, 0x37800000, v107
	v_cndmask_b32_e32 v102, v102, v67, vcc
	v_cndmask_b32_e64 v104, v104, v115, s[46:47]
	v_mul_f32_e32 v106, 0x37800000, v103
	v_cndmask_b32_e64 v67, v107, v105, s[36:37]
	v_cmp_class_f32_e32 vcc, v64, v215
	v_div_scale_f32 v109, s[4:5], v102, v102, 1.0
	v_mul_f32_e32 v108, 0x37800000, v104
	v_cndmask_b32_e64 v103, v103, v106, s[38:39]
	v_cmp_class_f32_e64 s[36:37], v65, v215
	v_cndmask_b32_e32 v106, v67, v64, vcc
	v_rcp_f32_e32 v64, v109
	v_cndmask_b32_e64 v104, v104, v108, s[40:41]
	v_cmp_class_f32_e64 s[38:39], v66, v215
	v_cndmask_b32_e64 v115, v103, v65, s[36:37]
	v_div_scale_f32 v65, s[4:5], v106, v106, 1.0
	v_cndmask_b32_e64 v114, v104, v66, s[38:39]
	v_div_scale_f32 v103, s[4:5], v115, v115, 1.0
; __device__ __forceinline__ unsigned pk2(float lo, float hi) { return pg8::cvt_pk_bf16(lo, hi); }
; template <bool X_F32> __device__ __forceinline__ void phase_norm_mod(const Ctx& C, const void* xin, const float* modl, int shift_idx, int scale_idx) {
;     ...
;             for (int r = 0; r < NRW; ++r) { const float rs = 1.0f / sqrtf(s[r] * (1.f / DM) + EPS);
; #pragma unroll
;                 for (int j = 0; j < 2; ++j) { const f32x4 y0 = v[r][2 * j] * rs * g[2 * j] + a[2 * j], y1 = v[r][2 * j + 1] * rs * g[2 * j + 1] + a[2 * j + 1];
;                     u32x4 w; w.x = pk2(y0.x, y0.y); w.y = pk2(y0.z, y0.w); w.z = pk2(y1.x, y1.y); w.w = pk2(y1.z, y1.w);
;                     ((u32x4*)(H + (size_t)(m0 + r) * DM + 512 * j))[lane] = w; } }
	v_rcp_f32_e32 v107, v65
	v_div_scale_f32 v105, s[4:5], v114, v114, 1.0
	v_rcp_f32_e32 v124, v103
	v_rcp_f32_e32 v116, v105
	v_fma_f32 v67, -v109, v64, 1.0
	v_div_scale_f32 v111, s[42:43], 1.0, v102, 1.0
	v_fmac_f32_e32 v64, v67, v64
	v_fma_f32 v67, -v65, v107, 1.0
	v_mul_f32_e32 v113, v111, v64
	v_div_scale_f32 v66, s[40:41], 1.0, v106, 1.0
	v_fma_f32 v108, -v103, v124, 1.0
	v_fmac_f32_e32 v107, v67, v107
	v_fma_f32 v67, -v109, v113, v111
	v_div_scale_f32 v104, s[38:39], 1.0, v115, 1.0
	v_fma_f32 v112, -v105, v116, 1.0
	v_fmac_f32_e32 v124, v108, v124
	v_mul_f32_e32 v108, v66, v107
	v_fmac_f32_e32 v113, v67, v64
	v_div_scale_f32 v110, s[36:37], 1.0, v114, 1.0
	v_fmac_f32_e32 v116, v112, v116
	v_mul_f32_e32 v125, v104, v124
	v_fma_f32 v67, -v109, v113, v111
	v_fma_f32 v109, -v65, v108, v66
	v_mul_f32_e32 v117, v110, v116
	v_fmac_f32_e32 v108, v109, v107
	v_fma_f32 v109, -v103, v125, v104
	v_fmac_f32_e32 v125, v109, v124
	v_fma_f32 v109, -v105, v117, v110
	s_mov_b64 vcc, s[42:43]
	v_fmac_f32_e32 v117, v109, v116
	v_div_fmas_f32 v111, v67, v64, v113
	v_fma_f32 v109, -v65, v108, v66
	s_mov_b64 vcc, s[40:41]
	v_div_fmas_f32 v107, v109, v107, v108
	v_fma_f32 v127, -v103, v125, v104
	v_div_fixup_f32 v104, v111, v102, 1.0
	v_div_fixup_f32 v126, v107, v106, 1.0
	global_load_dwordx4 v[64:67], v[100:101], off offset:16
	v_fma_f32 v123, -v105, v117, v110
	v_pk_mul_f32 v[60:61], v[60:61], v[104:105] op_sel_hi:[1,0]
	v_pk_mul_f32 v[62:63], v[62:63], v[104:105] op_sel_hi:[1,0]
	v_pk_mul_f32 v[52:53], v[52:53], v[104:105] op_sel_hi:[1,0]
	v_pk_mul_f32 v[102:103], v[54:55], v[104:105] op_sel_hi:[1,0]
	v_pk_mul_f32 v[54:55], v[56:57], v[104:105] op_sel_hi:[1,0]
	v_pk_mul_f32 v[58:59], v[58:59], v[104:105] op_sel_hi:[1,0]
	v_pk_mul_f32 v[56:57], v[48:49], v[104:105] op_sel_hi:[1,0]
	v_pk_mul_f32 v[104:105], v[50:51], v[104:105] op_sel_hi:[1,0]
	global_load_dwordx4 v[48:51], v[100:101], off
	v_pk_mul_f32 v[106:107], v[36:37], v[126:127] op_sel_hi:[1,0]
	v_pk_mul_f32 v[110:111], v[38:39], v[126:127] op_sel_hi:[1,0]
	v_pk_mul_f32 v[108:109], v[32:33], v[126:127] op_sel_hi:[1,0]
	v_pk_mul_f32 v[112:113], v[34:35], v[126:127] op_sel_hi:[1,0]
	global_load_dwordx4 v[32:35], v[100:101], off offset:2048
	global_load_dwordx4 v[36:39], v[100:101], off offset:2064
	s_mov_b64 vcc, s[38:39]
	v_div_fmas_f32 v124, v127, v124, v125
	s_mov_b64 vcc, s[36:37]
	v_pk_mul_f32 v[44:45], v[44:45], v[126:127] op_sel_hi:[1,0]
	v_pk_mul_f32 v[46:47], v[46:47], v[126:127] op_sel_hi:[1,0]
	v_pk_mul_f32 v[40:41], v[40:41], v[126:127] op_sel_hi:[1,0]
	v_pk_mul_f32 v[42:43], v[42:43], v[126:127] op_sel_hi:[1,0]
	v_div_fixup_f32 v124, v124, v115, 1.0
	v_div_fmas_f32 v115, v123, v116, v117
	v_pk_mul_f32 v[28:29], v[28:29], v[124:125] op_sel_hi:[1,0]
	v_pk_mul_f32 v[30:31], v[30:31], v[124:125] op_sel_hi:[1,0]
	v_pk_mul_f32 v[24:25], v[24:25], v[124:125] op_sel_hi:[1,0]
	v_pk_mul_f32 v[26:27], v[26:27], v[124:125] op_sel_hi:[1,0]
	s_waitcnt vmcnt(3)
	v_pk_fma_f32 v[100:101], v[82:83], v[102:103], v[66:67]
	v_pk_fma_f32 v[102:103], v[84:85], v[52:53], v[64:65]
	s_waitcnt vmcnt(2)
	v_pk_fma_f32 v[62:63], v[76:77], v[62:63], v[50:51]
	v_pk_fma_f32 v[60:61], v[78:79], v[60:61], v[48:49]
	v_cvt_pk_bf16_f32 v53, v62, v63
	v_cvt_pk_bf16_f32 v52, v60, v61
	v_pk_fma_f32 v[60:61], v[76:77], v[110:111], v[50:51]
	s_waitcnt vmcnt(1)
	v_pk_fma_f32 v[58:59], v[58:59], v[86:87], v[34:35]
	v_pk_fma_f32 v[126:127], v[54:55], v[88:89], v[32:33]
	s_waitcnt vmcnt(0)
	v_pk_fma_f32 v[104:105], v[104:105], v[90:91], v[38:39]
	v_pk_fma_f32 v[128:129], v[56:57], v[92:93], v[36:37]
	v_cvt_pk_bf16_f32 v54, v102, v103
	v_cvt_pk_bf16_f32 v55, v100, v101
	v_cvt_pk_bf16_f32 v56, v126, v127
	v_cvt_pk_bf16_f32 v57, v58, v59
	v_cvt_pk_bf16_f32 v58, v128, v129
	v_cvt_pk_bf16_f32 v59, v104, v105
	v_pk_fma_f32 v[62:63], v[78:79], v[106:107], v[48:49]
	v_pk_fma_f32 v[100:101], v[82:83], v[112:113], v[66:67]
	v_pk_fma_f32 v[102:103], v[84:85], v[108:109], v[64:65]
	v_pk_fma_f32 v[46:47], v[46:47], v[86:87], v[34:35]
	v_pk_fma_f32 v[44:45], v[44:45], v[88:89], v[32:33]
	v_pk_fma_f32 v[42:43], v[42:43], v[90:91], v[38:39]
	v_pk_fma_f32 v[40:41], v[40:41], v[92:93], v[36:37]
	v_pk_mul_f32 v[104:105], v[20:21], v[124:125] op_sel_hi:[1,0]
	v_pk_mul_f32 v[106:107], v[22:23], v[124:125] op_sel_hi:[1,0]
	v_pk_mul_f32 v[108:109], v[16:17], v[124:125] op_sel_hi:[1,0]
	v_pk_mul_f32 v[110:111], v[18:19], v[124:125] op_sel_hi:[1,0]
	v_div_fixup_f32 v112, v115, v114, 1.0
	flat_store_dwordx4 v[74:75], v[52:55] sc0 sc1
	flat_store_dwordx4 v[74:75], v[56:59] offset:1024 sc0 sc1
	v_cvt_pk_bf16_f32 v16, v62, v63
	v_cvt_pk_bf16_f32 v17, v60, v61
	v_cvt_pk_bf16_f32 v18, v102, v103
	v_cvt_pk_bf16_f32 v19, v100, v101
	v_cvt_pk_bf16_f32 v20, v44, v45
	v_cvt_pk_bf16_f32 v21, v46, v47
	v_cvt_pk_bf16_f32 v22, v40, v41
	v_cvt_pk_bf16_f32 v23, v42, v43
	v_pk_fma_f32 v[40:41], v[76:77], v[106:107], v[50:51]
	v_pk_fma_f32 v[42:43], v[78:79], v[104:105], v[48:49]
	v_pk_fma_f32 v[44:45], v[82:83], v[110:111], v[66:67]
	v_pk_fma_f32 v[46:47], v[84:85], v[108:109], v[64:65]
	v_pk_mul_f32 v[52:53], v[4:5], v[112:113] op_sel_hi:[1,0]
	v_pk_mul_f32 v[54:55], v[6:7], v[112:113] op_sel_hi:[1,0]
	v_pk_mul_f32 v[56:57], v[0:1], v[112:113] op_sel_hi:[1,0]
	v_pk_mul_f32 v[58:59], v[2:3], v[112:113] op_sel_hi:[1,0]
	v_pk_fma_f32 v[30:31], v[86:87], v[30:31], v[34:35]
	v_pk_fma_f32 v[28:29], v[88:89], v[28:29], v[32:33]
	v_pk_fma_f32 v[26:27], v[26:27], v[90:91], v[38:39]
	v_pk_fma_f32 v[24:25], v[24:25], v[92:93], v[36:37]
	v_pk_mul_f32 v[12:13], v[12:13], v[112:113] op_sel_hi:[1,0]
	v_pk_mul_f32 v[14:15], v[14:15], v[112:113] op_sel_hi:[1,0]
	v_pk_mul_f32 v[8:9], v[8:9], v[112:113] op_sel_hi:[1,0]
	v_pk_mul_f32 v[10:11], v[10:11], v[112:113] op_sel_hi:[1,0]
	flat_store_dwordx4 v[94:95], v[16:19] sc0 sc1
	flat_store_dwordx4 v[94:95], v[20:23] offset:1024 sc0 sc1
	v_cvt_pk_bf16_f32 v0, v42, v43
	v_cvt_pk_bf16_f32 v1, v40, v41
	v_cvt_pk_bf16_f32 v2, v46, v47
	v_cvt_pk_bf16_f32 v3, v44, v45
	v_pk_fma_f32 v[16:17], v[76:77], v[54:55], v[50:51]
	v_pk_fma_f32 v[18:19], v[78:79], v[52:53], v[48:49]
	v_pk_fma_f32 v[20:21], v[82:83], v[58:59], v[66:67]
	v_pk_fma_f32 v[22:23], v[84:85], v[56:57], v[64:65]
	v_cvt_pk_bf16_f32 v4, v28, v29
	v_cvt_pk_bf16_f32 v5, v30, v31
	v_cvt_pk_bf16_f32 v6, v24, v25
	v_cvt_pk_bf16_f32 v7, v26, v27
	v_pk_fma_f32 v[14:15], v[86:87], v[14:15], v[34:35]
	v_pk_fma_f32 v[12:13], v[88:89], v[12:13], v[32:33]
	v_pk_fma_f32 v[10:11], v[10:11], v[90:91], v[38:39]
	v_pk_fma_f32 v[8:9], v[8:9], v[92:93], v[36:37]
	flat_store_dwordx4 v[98:99], v[0:3] sc0 sc1
	flat_store_dwordx4 v[98:99], v[4:7] offset:1024 sc0 sc1
	s_nop 0
	v_cvt_pk_bf16_f32 v0, v18, v19
	v_cvt_pk_bf16_f32 v1, v16, v17
	v_cvt_pk_bf16_f32 v2, v22, v23
	v_cvt_pk_bf16_f32 v3, v20, v21
	v_cvt_pk_bf16_f32 v4, v12, v13
	v_cvt_pk_bf16_f32 v5, v14, v15
	v_cvt_pk_bf16_f32 v6, v8, v9
	v_cvt_pk_bf16_f32 v7, v10, v11
	flat_store_dwordx4 v[96:97], v[0:3] sc0 sc1
	flat_store_dwordx4 v[96:97], v[4:7] offset:1024 sc0 sc1
	s_cbranch_scc0 .LBB0_134

; __device__ __forceinline__ unsigned cvt_pk_bf16(float lo, float hi) { f32x2_cv v = {lo, hi}; bf16x2_cv b = __builtin_convertvector(v, bf16x2_cv); return __builtin_bit_cast(unsigned, b); }
;     __device__ __forceinline__ void operator()(const f32x4 (&acc)[2][2][4][2], const Unit& u, int wr, int wc, int fr, int fq) const {
;         const int row0 = u.pm * BM + wr * 64 + fr;
;         const float sc = (u.pn < 8 && ((u.pn >> 1) & 1) == 0) ? qscale : 1.f;
;         const int col0 = u.pn * BM + wc * 32 + 8 * fq;
; #pragma unroll
;         for (int ai = 0; ai < 2; ++ai)
; #pragma unroll
;             for (int m = 0; m < 4; ++m) { bf16_t* rowp = QKV + (size_t)(row0 + ai * HALF + m * 16) * 3072 + col0;
; #pragma unroll
;                 for (int bj = 0; bj < 2; ++bj) { const f32x4 v0 = acc[ai][bj][m][0] * sc, v1 = acc[ai][bj][m][1] * sc;
;                     u32x4 w; w.x = cvt_pk_bf16(v0[0], v0[1]); w.y = cvt_pk_bf16(v0[2], v0[3]); w.z = cvt_pk_bf16(v1[0], v1[1]); w.w = cvt_pk_bf16(v1[2], v1[3]);
;                     *(u32x4*)(rowp + bj * HALF) = w; } }
.LBB0_195:
	s_cmp_lt_i32 s60, 8
	s_cselect_b64 s[12:13], -1, 0
	s_bitcmp0_b32 s60, 1
	s_cselect_b64 s[48:49], -1, 0
	s_and_b64 vcc, s[12:13], s[48:49]
	v_mov_b32_e32 v140, 0x3e38aa3b
	v_lshl_or_b32 v144, s60, 8, v147
	v_lshl_add_u32 v149, s42, 8, v141
	v_cndmask_b32_e32 v140, 1.0, v140, vcc
	v_ashrrev_i32_e32 v145, 31, v144
	v_mov_b64_e32 v[142:143], s[14:15]
	s_movk_i32 s3, 0x1800
	v_mad_i64_i32 v[150:151], s[12:13], v149, s3, v[142:143]
	v_lshlrev_b64 v[144:145], 1, v[144:145]
	v_pk_mul_f32 v[128:129], v[140:141], v[128:129] op_sel_hi:[0,1]
	v_pk_mul_f32 v[126:127], v[140:141], v[126:127] op_sel_hi:[0,1]
	v_pk_mul_f32 v[152:153], v[140:141], v[124:125] op_sel_hi:[0,1]
	v_pk_mul_f32 v[124:125], v[140:141], v[122:123] op_sel_hi:[0,1]
	v_lshl_add_u64 v[150:151], v[150:151], 0, v[144:145]
	v_cvt_pk_bf16_f32 v122, v126, v127
	v_cvt_pk_bf16_f32 v123, v128, v129
	v_cvt_pk_bf16_f32 v124, v124, v125
	v_cvt_pk_bf16_f32 v125, v152, v153
	flat_store_dwordx4 v[150:151], v[122:125] sc0 sc1
	v_pk_mul_f32 v[116:117], v[140:141], v[116:117] op_sel_hi:[0,1]
	v_pk_mul_f32 v[114:115], v[140:141], v[114:115] op_sel_hi:[0,1]
	v_pk_mul_f32 v[122:123], v[140:141], v[108:109] op_sel_hi:[0,1]
	v_pk_mul_f32 v[108:109], v[140:141], v[106:107] op_sel_hi:[0,1]
	v_cvt_pk_bf16_f32 v106, v114, v115
	v_cvt_pk_bf16_f32 v107, v116, v117
	v_cvt_pk_bf16_f32 v108, v108, v109
	v_cvt_pk_bf16_f32 v109, v122, v123
	flat_store_dwordx4 v[150:151], v[106:109] offset:256 sc0 sc1
	v_pk_mul_f32 v[112:113], v[140:141], v[112:113] op_sel_hi:[0,1]
	v_pk_mul_f32 v[110:111], v[140:141], v[110:111] op_sel_hi:[0,1]
	v_or_b32_e32 v106, 16, v149
	v_mad_i64_i32 v[106:107], s[12:13], v106, s3, v[142:143]
	v_lshl_add_u64 v[114:115], v[106:107], 0, v[144:145]
	v_pk_mul_f32 v[108:109], v[140:141], v[120:121] op_sel_hi:[0,1]
	v_pk_mul_f32 v[106:107], v[140:141], v[118:119] op_sel_hi:[0,1]
	v_cvt_pk_bf16_f32 v106, v106, v107
	v_cvt_pk_bf16_f32 v107, v108, v109
	v_cvt_pk_bf16_f32 v108, v110, v111
	v_cvt_pk_bf16_f32 v109, v112, v113
	flat_store_dwordx4 v[114:115], v[106:109] sc0 sc1
	v_pk_mul_f32 v[100:101], v[140:141], v[100:101] op_sel_hi:[0,1]
	v_pk_mul_f32 v[98:99], v[140:141], v[98:99] op_sel_hi:[0,1]
	v_pk_mul_f32 v[106:107], v[140:141], v[92:93] op_sel_hi:[0,1]
	v_pk_mul_f32 v[92:93], v[140:141], v[90:91] op_sel_hi:[0,1]
	v_cvt_pk_bf16_f32 v90, v98, v99
	v_cvt_pk_bf16_f32 v91, v100, v101
	v_cvt_pk_bf16_f32 v92, v92, v93
	v_cvt_pk_bf16_f32 v93, v106, v107
	flat_store_dwordx4 v[114:115], v[90:93] offset:256 sc0 sc1
	v_pk_mul_f32 v[96:97], v[140:141], v[96:97] op_sel_hi:[0,1]
	v_pk_mul_f32 v[94:95], v[140:141], v[94:95] op_sel_hi:[0,1]
	v_or_b32_e32 v90, 32, v149
	v_mad_i64_i32 v[90:91], s[12:13], v90, s3, v[142:143]
	v_lshl_add_u64 v[98:99], v[90:91], 0, v[144:145]
	v_pk_mul_f32 v[92:93], v[140:141], v[104:105] op_sel_hi:[0,1]
	v_pk_mul_f32 v[90:91], v[140:141], v[102:103] op_sel_hi:[0,1]
	v_cvt_pk_bf16_f32 v90, v90, v91
	v_cvt_pk_bf16_f32 v91, v92, v93
	v_cvt_pk_bf16_f32 v92, v94, v95
	v_cvt_pk_bf16_f32 v93, v96, v97
	flat_store_dwordx4 v[98:99], v[90:93] sc0 sc1
	v_pk_mul_f32 v[84:85], v[140:141], v[84:85] op_sel_hi:[0,1]
	v_pk_mul_f32 v[82:83], v[140:141], v[82:83] op_sel_hi:[0,1]
	v_pk_mul_f32 v[90:91], v[140:141], v[74:75] op_sel_hi:[0,1]
	v_pk_mul_f32 v[74:75], v[140:141], v[72:73] op_sel_hi:[0,1]
	v_cvt_pk_bf16_f32 v72, v82, v83
	v_cvt_pk_bf16_f32 v73, v84, v85
	v_cvt_pk_bf16_f32 v74, v74, v75
	v_cvt_pk_bf16_f32 v75, v90, v91
	flat_store_dwordx4 v[98:99], v[72:75] offset:256 sc0 sc1
	v_pk_mul_f32 v[78:79], v[140:141], v[78:79] op_sel_hi:[0,1]
	v_pk_mul_f32 v[76:77], v[140:141], v[76:77] op_sel_hi:[0,1]
	v_or_b32_e32 v72, 48, v149
	v_mad_i64_i32 v[72:73], s[12:13], v72, s3, v[142:143]
	v_lshl_add_u64 v[82:83], v[72:73], 0, v[144:145]
	v_pk_mul_f32 v[74:75], v[140:141], v[88:89] op_sel_hi:[0,1]
	v_pk_mul_f32 v[72:73], v[140:141], v[86:87] op_sel_hi:[0,1]
	v_cvt_pk_bf16_f32 v72, v72, v73
	v_cvt_pk_bf16_f32 v73, v74, v75
	v_cvt_pk_bf16_f32 v74, v76, v77
	v_cvt_pk_bf16_f32 v75, v78, v79
	flat_store_dwordx4 v[82:83], v[72:75] sc0 sc1
	v_pk_mul_f32 v[70:71], v[140:141], v[70:71] op_sel_hi:[0,1]
	v_pk_mul_f32 v[68:69], v[140:141], v[68:69] op_sel_hi:[0,1]
	v_pk_mul_f32 v[72:73], v[140:141], v[66:67] op_sel_hi:[0,1]
	v_pk_mul_f32 v[66:67], v[140:141], v[64:65] op_sel_hi:[0,1]
; __device__ __forceinline__ unsigned cvt_pk_bf16(float lo, float hi) { f32x2_cv v = {lo, hi}; bf16x2_cv b = __builtin_convertvector(v, bf16x2_cv); return __builtin_bit_cast(unsigned, b); }
;     __device__ __forceinline__ void operator()(const f32x4 (&acc)[2][2][4][2], const Unit& u, int wr, int wc, int fr, int fq) const {
;     ...
;             for (int m = 0; m < 4; ++m) { bf16_t* rowp = QKV + (size_t)(row0 + ai * HALF + m * 16) * 3072 + col0;
; #pragma unroll
;                 for (int bj = 0; bj < 2; ++bj) { const f32x4 v0 = acc[ai][bj][m][0] * sc, v1 = acc[ai][bj][m][1] * sc;
;                     u32x4 w; w.x = cvt_pk_bf16(v0[0], v0[1]); w.y = cvt_pk_bf16(v0[2], v0[3]); w.z = cvt_pk_bf16(v1[0], v1[1]); w.w = cvt_pk_bf16(v1[2], v1[3]);
;                     *(u32x4*)(rowp + bj * HALF) = w; } }
	v_cvt_pk_bf16_f32 v64, v68, v69
	v_cvt_pk_bf16_f32 v65, v70, v71
	v_cvt_pk_bf16_f32 v66, v66, v67
	v_cvt_pk_bf16_f32 v67, v72, v73
	flat_store_dwordx4 v[82:83], v[64:67] offset:256 sc0 sc1
	v_pk_mul_f32 v[62:63], v[140:141], v[62:63] op_sel_hi:[0,1]
	v_pk_mul_f32 v[60:61], v[140:141], v[60:61] op_sel_hi:[0,1]
	v_add_u32_e32 v64, 0x80, v149
	v_mad_i64_i32 v[64:65], s[12:13], v64, s3, v[142:143]
	v_pk_mul_f32 v[66:67], v[140:141], v[58:59] op_sel_hi:[0,1]
	v_pk_mul_f32 v[58:59], v[140:141], v[56:57] op_sel_hi:[0,1]
	v_lshl_add_u64 v[64:65], v[64:65], 0, v[144:145]
	v_cvt_pk_bf16_f32 v56, v60, v61
	v_cvt_pk_bf16_f32 v57, v62, v63
	v_cvt_pk_bf16_f32 v58, v58, v59
	v_cvt_pk_bf16_f32 v59, v66, v67
	flat_store_dwordx4 v[64:65], v[56:59] sc0 sc1
	v_pk_mul_f32 v[50:51], v[140:141], v[50:51] op_sel_hi:[0,1]
	v_pk_mul_f32 v[48:49], v[140:141], v[48:49] op_sel_hi:[0,1]
	v_pk_mul_f32 v[56:57], v[140:141], v[42:43] op_sel_hi:[0,1]
	v_pk_mul_f32 v[42:43], v[140:141], v[40:41] op_sel_hi:[0,1]
	v_cvt_pk_bf16_f32 v40, v48, v49
	v_cvt_pk_bf16_f32 v41, v50, v51
	v_cvt_pk_bf16_f32 v42, v42, v43
	v_cvt_pk_bf16_f32 v43, v56, v57
	flat_store_dwordx4 v[64:65], v[40:43] offset:256 sc0 sc1
	v_pk_mul_f32 v[46:47], v[140:141], v[46:47] op_sel_hi:[0,1]
	v_pk_mul_f32 v[44:45], v[140:141], v[44:45] op_sel_hi:[0,1]
	v_add_u32_e32 v40, 0x90, v149
	v_mad_i64_i32 v[40:41], s[12:13], v40, s3, v[142:143]
	v_lshl_add_u64 v[48:49], v[40:41], 0, v[144:145]
	v_pk_mul_f32 v[42:43], v[140:141], v[54:55] op_sel_hi:[0,1]
	v_pk_mul_f32 v[40:41], v[140:141], v[52:53] op_sel_hi:[0,1]
	v_cvt_pk_bf16_f32 v40, v40, v41
	v_cvt_pk_bf16_f32 v41, v42, v43
	v_cvt_pk_bf16_f32 v42, v44, v45
	v_cvt_pk_bf16_f32 v43, v46, v47
	flat_store_dwordx4 v[48:49], v[40:43] sc0 sc1
	v_pk_mul_f32 v[34:35], v[140:141], v[34:35] op_sel_hi:[0,1]
	v_pk_mul_f32 v[32:33], v[140:141], v[32:33] op_sel_hi:[0,1]
	v_pk_mul_f32 v[40:41], v[140:141], v[26:27] op_sel_hi:[0,1]
	v_pk_mul_f32 v[26:27], v[140:141], v[24:25] op_sel_hi:[0,1]
	v_cvt_pk_bf16_f32 v24, v32, v33
	v_cvt_pk_bf16_f32 v25, v34, v35
	v_cvt_pk_bf16_f32 v26, v26, v27
	v_cvt_pk_bf16_f32 v27, v40, v41
	flat_store_dwordx4 v[48:49], v[24:27] offset:256 sc0 sc1
	v_pk_mul_f32 v[30:31], v[140:141], v[30:31] op_sel_hi:[0,1]
	v_pk_mul_f32 v[28:29], v[140:141], v[28:29] op_sel_hi:[0,1]
	v_add_u32_e32 v24, 0xa0, v149
	v_mad_i64_i32 v[24:25], s[12:13], v24, s3, v[142:143]
	v_lshl_add_u64 v[32:33], v[24:25], 0, v[144:145]
	v_pk_mul_f32 v[26:27], v[140:141], v[38:39] op_sel_hi:[0,1]
	v_pk_mul_f32 v[24:25], v[140:141], v[36:37] op_sel_hi:[0,1]
	v_cvt_pk_bf16_f32 v24, v24, v25
	v_cvt_pk_bf16_f32 v25, v26, v27
	v_cvt_pk_bf16_f32 v26, v28, v29
	v_cvt_pk_bf16_f32 v27, v30, v31
	flat_store_dwordx4 v[32:33], v[24:27] sc0 sc1
	v_pk_mul_f32 v[18:19], v[140:141], v[18:19] op_sel_hi:[0,1]
	v_pk_mul_f32 v[16:17], v[140:141], v[16:17] op_sel_hi:[0,1]
	v_pk_mul_f32 v[24:25], v[140:141], v[10:11] op_sel_hi:[0,1]
	v_pk_mul_f32 v[10:11], v[140:141], v[8:9] op_sel_hi:[0,1]
	v_cvt_pk_bf16_f32 v8, v16, v17
	v_cvt_pk_bf16_f32 v9, v18, v19
	v_cvt_pk_bf16_f32 v10, v10, v11
	v_cvt_pk_bf16_f32 v11, v24, v25
	flat_store_dwordx4 v[32:33], v[8:11] offset:256 sc0 sc1
	v_pk_mul_f32 v[14:15], v[140:141], v[14:15] op_sel_hi:[0,1]
	v_pk_mul_f32 v[12:13], v[140:141], v[12:13] op_sel_hi:[0,1]
	v_add_u32_e32 v8, 0xb0, v149
	v_mad_i64_i32 v[8:9], s[12:13], v8, s3, v[142:143]
	v_lshl_add_u64 v[16:17], v[8:9], 0, v[144:145]
	v_pk_mul_f32 v[10:11], v[140:141], v[22:23] op_sel_hi:[0,1]
	v_pk_mul_f32 v[8:9], v[140:141], v[20:21] op_sel_hi:[0,1]
	v_cvt_pk_bf16_f32 v8, v8, v9
	v_cvt_pk_bf16_f32 v9, v10, v11
	v_cvt_pk_bf16_f32 v10, v12, v13
	v_cvt_pk_bf16_f32 v11, v14, v15
	flat_store_dwordx4 v[16:17], v[8:11] sc0 sc1
	v_pk_mul_f32 v[6:7], v[140:141], v[6:7] op_sel_hi:[0,1]
	v_pk_mul_f32 v[4:5], v[140:141], v[4:5] op_sel_hi:[0,1]
	v_pk_mul_f32 v[8:9], v[140:141], v[2:3] op_sel_hi:[0,1]
	v_pk_mul_f32 v[2:3], v[140:141], v[0:1] op_sel_hi:[0,1]
	s_movk_i32 s0, 0x1800
	v_cvt_pk_bf16_f32 v0, v4, v5
	v_cvt_pk_bf16_f32 v1, v6, v7
	v_cvt_pk_bf16_f32 v2, v2, v3
	v_cvt_pk_bf16_f32 v3, v8, v9
	s_andn2_b64 vcc, exec, s[36:37]
	s_mov_b64 s[12:13], -1
	flat_store_dwordx4 v[16:17], v[0:3] offset:256 sc0 sc1
	s_cbranch_vccnz .LBB0_188
	s_andn2_b64 vcc, exec, s[4:5]
	s_cbranch_vccnz .LBB0_187
	s_barrier
	s_branch .LBB0_187

; __device__ __forceinline__ unsigned cvt_pk_bf16(float lo, float hi) { f32x2_cv v = {lo, hi}; bf16x2_cv b = __builtin_convertvector(v, bf16x2_cv); return __builtin_bit_cast(unsigned, b); }
;     __device__ __forceinline__ void operator()(const f32x4 (&acc)[2][2][4][2], const Unit& u, int wr, int wc, int fr, int fq) const {
;         const int row0 = u.pm * BM + wr * 64 + fr; const int col0 = u.pn * BM + wc * 32 + 8 * fq;
;         const int b = (u.pm * BM) >> 12;
;         f32x4 gv[2][2];
; #pragma unroll
;         for (int bj = 0; bj < 2; ++bj)
; #pragma unroll
;             for (int n = 0; n < 2; ++n) gv[bj][n] = *(const f32x4*)(gate + (size_t)b * gate_ld + col0 + bj * HALF + n * 4);
;         f32x4 xv[2][2][2];
;         load_x(xv[0], (size_t)row0 * 1024 + col0);
; #pragma unroll
;         for (int g = 0; g < 8; ++g) { const int ai = g >> 2, m = g & 3; const size_t off = (size_t)(row0 + ai * HALF + m * 16) * 1024 + col0;
;             if (g + 1 < 8) { const int ai2 = (g + 1) >> 2, m2 = (g + 1) & 3; load_x(xv[(g + 1) & 1], (size_t)(row0 + ai2 * HALF + m2 * 16) * 1024 + col0); }
;             float rs_ = 1.0f; if constexpr (ROWSCALE) rs_ = tab[((u.pm == pm0 ? 0 : 256) + ai * HALF + wr * 64 + m * 16 + fr) * 2 + 1];
; #pragma unroll
;             for (int bj = 0; bj < 2; ++bj) { const f32x4 v0 = xv[g & 1][bj][0] + gv[bj][0] * (acc[ai][bj][m][0] * rs_), v1 = xv[g & 1][bj][1] + gv[bj][1] * (acc[ai][bj][m][1] * rs_);
;                 u32x4 w; w.x = cvt_pk_bf16(v0[0], v0[1]); w.y = cvt_pk_bf16(v0[2], v0[3]); w.z = cvt_pk_bf16(v1[0], v1[1]); w.w = cvt_pk_bf16(v1[2], v1[3]);
;                 *(u32x4*)(out + off + bj * HALF) = w; } }
.LBB0_417:
	v_lshl_or_b32 v221, s5, 8, v203
	s_ashr_i32 s3, s4, 4
	s_mul_hi_i32 s5, s3, 0x6000
	s_mulk_i32 s3, 0x6000
	s_add_u32 s12, s64, s3
	s_addc_u32 s13, s65, s5
	v_lshlrev_b32_e32 v223, 2, v221
	global_load_dwordx4 v[60:63], v223, s[12:13]
	global_load_dwordx4 v[56:59], v223, s[12:13] offset:16
	global_load_dwordx4 v[52:55], v223, s[12:13] offset:512
	global_load_dwordx4 v[48:51], v223, s[12:13] offset:528
	v_lshlrev_b32_e32 v213, 11, v198
	v_lshl_add_u32 v213, v221, 1, v213
	s_lshl_b32 s3, s4, 19
	s_add_u32 s98, s38, s3
	s_addc_u32 s99, s39, 0
	s_mov_b64 s[100:101], s[98:99]
	v_readlane_b32 s3, v255, 49
	s_nop 0
	s_cmp_eq_u32 s4, s3
	s_cselect_b32 s4, 0, 0x100
	v_add_u32_e32 v80, s4, v198
	s_add_i32 s5, 0, 0x22800
	v_lshl_add_u32 v80, v80, 3, s5
	s_mov_b32 s3, 0x40000
	s_mov_b64 s[12:13], 0x40000
	s_mov_b32 s78, s1
	global_load_dwordx4 v[176:179], v213, s[98:99]
	global_load_dwordx4 v[180:183], v213, s[98:99] offset:256
	s_add_u32 s98, s98, 0x8000
	s_addc_u32 s99, s99, 0
	global_load_dwordx4 v[184:187], v213, s[98:99]
	global_load_dwordx4 v[188:191], v213, s[98:99] offset:256
	s_add_u32 s98, s98, 0x8000
	s_addc_u32 s99, s99, 0
	global_load_dwordx4 v[192:195], v213, s[98:99]
	global_load_dwordx4 v[224:227], v213, s[98:99] offset:256
	s_add_u32 s98, s98, 0x8000
	s_addc_u32 s99, s99, 0
	global_load_dwordx4 v[232:235], v213, s[98:99]
	global_load_dwordx4 v[236:239], v213, s[98:99] offset:256
	s_add_u32 s98, s98, 0x28000
	s_addc_u32 s99, s99, 0
	global_load_dwordx4 v[240:243], v213, s[98:99]
	global_load_dwordx4 v[244:247], v213, s[98:99] offset:256
	s_add_u32 s98, s98, 0x8000
	s_addc_u32 s99, s99, 0
	ds_read_b32 v212, v80 offset:4
	ds_read_b32 v220, v80 offset:132
	ds_read_b32 v222, v80 offset:260
	ds_read_b32 v228, v80 offset:388
	ds_read_b32 v230, v80 offset:1028
	ds_read_b32 v248, v80 offset:1156
	ds_read_b32 v250, v80 offset:1284
	ds_read_b32 v82, v80 offset:1412
	s_waitcnt lgkmcnt(0)
	s_waitcnt vmcnt(8)
	v_pk_mul_f32 v[144:145], v[144:145], v[212:213] op_sel_hi:[1,0]
	v_pk_mul_f32 v[146:147], v[146:147], v[212:213] op_sel_hi:[1,0]
	v_pk_mul_f32 v[140:141], v[140:141], v[212:213] op_sel_hi:[1,0]
	v_pk_mul_f32 v[142:143], v[142:143], v[212:213] op_sel_hi:[1,0]
	v_lshlrev_b32_e32 v160, 16, v176
	v_and_b32_e32 v161, 0xffff0000, v176
	v_lshlrev_b32_e32 v174, 16, v177
	v_and_b32_e32 v175, 0xffff0000, v177
	v_lshlrev_b32_e32 v196, 16, v178
	v_and_b32_e32 v197, 0xffff0000, v178
	v_lshlrev_b32_e32 v210, 16, v179
	v_and_b32_e32 v211, 0xffff0000, v179
	v_pk_fma_f32 v[144:145], v[60:61], v[144:145], v[160:161]
	v_pk_fma_f32 v[146:147], v[62:63], v[146:147], v[174:175]
	v_pk_fma_f32 v[140:141], v[56:57], v[140:141], v[196:197]
	v_pk_fma_f32 v[142:143], v[58:59], v[142:143], v[210:211]
	v_cvt_pk_bf16_f32 v176, v144, v145
	v_cvt_pk_bf16_f32 v177, v146, v147
	v_cvt_pk_bf16_f32 v178, v140, v141
	v_cvt_pk_bf16_f32 v179, v142, v143
	global_store_dwordx4 v213, v[176:179], s[100:101] sc0 sc1
	v_pk_mul_f32 v[136:137], v[136:137], v[212:213] op_sel_hi:[1,0]
	v_pk_mul_f32 v[138:139], v[138:139], v[212:213] op_sel_hi:[1,0]
	v_pk_mul_f32 v[132:133], v[132:133], v[212:213] op_sel_hi:[1,0]
	v_pk_mul_f32 v[134:135], v[134:135], v[212:213] op_sel_hi:[1,0]
	v_lshlrev_b32_e32 v160, 16, v180
	v_and_b32_e32 v161, 0xffff0000, v180
	v_lshlrev_b32_e32 v174, 16, v181
	v_and_b32_e32 v175, 0xffff0000, v181
	v_lshlrev_b32_e32 v196, 16, v182
	v_and_b32_e32 v197, 0xffff0000, v182
	v_lshlrev_b32_e32 v210, 16, v183
	v_and_b32_e32 v211, 0xffff0000, v183
	v_pk_fma_f32 v[136:137], v[52:53], v[136:137], v[160:161]
	v_pk_fma_f32 v[138:139], v[54:55], v[138:139], v[174:175]
	v_pk_fma_f32 v[132:133], v[48:49], v[132:133], v[196:197]
	v_pk_fma_f32 v[134:135], v[50:51], v[134:135], v[210:211]
	v_cvt_pk_bf16_f32 v180, v136, v137
	v_cvt_pk_bf16_f32 v181, v138, v139
	v_cvt_pk_bf16_f32 v182, v132, v133
	v_cvt_pk_bf16_f32 v183, v134, v135
	global_store_dwordx4 v213, v[180:183], s[100:101] offset:256 sc0 sc1
	s_add_u32 s100, s100, 0x8000
	s_addc_u32 s101, s101, 0
	global_load_dwordx4 v[176:179], v213, s[98:99]
	global_load_dwordx4 v[180:183], v213, s[98:99] offset:256
	s_add_u32 s98, s98, 0x8000
	s_addc_u32 s99, s99, 0
	s_waitcnt vmcnt(10)
	v_pk_mul_f32 v[128:129], v[128:129], v[220:221] op_sel_hi:[1,0]
	v_pk_mul_f32 v[130:131], v[130:131], v[220:221] op_sel_hi:[1,0]
	v_pk_mul_f32 v[124:125], v[124:125], v[220:221] op_sel_hi:[1,0]
	v_pk_mul_f32 v[126:127], v[126:127], v[220:221] op_sel_hi:[1,0]
	v_lshlrev_b32_e32 v160, 16, v184
	v_and_b32_e32 v161, 0xffff0000, v184
	v_lshlrev_b32_e32 v174, 16, v185
	v_and_b32_e32 v175, 0xffff0000, v185
	v_lshlrev_b32_e32 v196, 16, v186
	v_and_b32_e32 v197, 0xffff0000, v186
	v_lshlrev_b32_e32 v210, 16, v187
	v_and_b32_e32 v211, 0xffff0000, v187
	v_pk_fma_f32 v[128:129], v[60:61], v[128:129], v[160:161]
	v_pk_fma_f32 v[130:131], v[62:63], v[130:131], v[174:175]
	v_pk_fma_f32 v[124:125], v[56:57], v[124:125], v[196:197]
	v_pk_fma_f32 v[126:127], v[58:59], v[126:127], v[210:211]
	v_cvt_pk_bf16_f32 v184, v128, v129
	v_cvt_pk_bf16_f32 v185, v130, v131
	v_cvt_pk_bf16_f32 v186, v124, v125
	v_cvt_pk_bf16_f32 v187, v126, v127
	global_store_dwordx4 v213, v[184:187], s[100:101] sc0 sc1
	v_pk_mul_f32 v[120:121], v[120:121], v[220:221] op_sel_hi:[1,0]
	v_pk_mul_f32 v[122:123], v[122:123], v[220:221] op_sel_hi:[1,0]
	v_pk_mul_f32 v[116:117], v[116:117], v[220:221] op_sel_hi:[1,0]
	v_pk_mul_f32 v[118:119], v[118:119], v[220:221] op_sel_hi:[1,0]
	v_lshlrev_b32_e32 v160, 16, v188
	v_and_b32_e32 v161, 0xffff0000, v188
	v_lshlrev_b32_e32 v174, 16, v189
	v_and_b32_e32 v175, 0xffff0000, v189
	v_lshlrev_b32_e32 v196, 16, v190
	v_and_b32_e32 v197, 0xffff0000, v190
	v_lshlrev_b32_e32 v210, 16, v191
	v_and_b32_e32 v211, 0xffff0000, v191
	v_pk_fma_f32 v[120:121], v[52:53], v[120:121], v[160:161]
	v_pk_fma_f32 v[122:123], v[54:55], v[122:123], v[174:175]
	v_pk_fma_f32 v[116:117], v[48:49], v[116:117], v[196:197]
	v_pk_fma_f32 v[118:119], v[50:51], v[118:119], v[210:211]
	v_cvt_pk_bf16_f32 v188, v120, v121
	v_cvt_pk_bf16_f32 v189, v122, v123
	v_cvt_pk_bf16_f32 v190, v116, v117
	v_cvt_pk_bf16_f32 v191, v118, v119
	global_store_dwordx4 v213, v[188:191], s[100:101] offset:256 sc0 sc1
	s_add_u32 s100, s100, 0x8000
	s_addc_u32 s101, s101, 0
	global_load_dwordx4 v[184:187], v213, s[98:99]
	global_load_dwordx4 v[188:191], v213, s[98:99] offset:256
	s_add_u32 s98, s98, 0x8000
	s_addc_u32 s99, s99, 0
	s_waitcnt vmcnt(12)
; __device__ __forceinline__ unsigned cvt_pk_bf16(float lo, float hi) { f32x2_cv v = {lo, hi}; bf16x2_cv b = __builtin_convertvector(v, bf16x2_cv); return __builtin_bit_cast(unsigned, b); }
;     __device__ __forceinline__ void operator()(const f32x4 (&acc)[2][2][4][2], const Unit& u, int wr, int wc, int fr, int fq) const {
;     ...
;         for (int g = 0; g < 8; ++g) { const int ai = g >> 2, m = g & 3; const size_t off = (size_t)(row0 + ai * HALF + m * 16) * 1024 + col0;
;             if (g + 1 < 8) { const int ai2 = (g + 1) >> 2, m2 = (g + 1) & 3; load_x(xv[(g + 1) & 1], (size_t)(row0 + ai2 * HALF + m2 * 16) * 1024 + col0); }
;             float rs_ = 1.0f; if constexpr (ROWSCALE) rs_ = tab[((u.pm == pm0 ? 0 : 256) + ai * HALF + wr * 64 + m * 16 + fr) * 2 + 1];
; #pragma unroll
;             for (int bj = 0; bj < 2; ++bj) { const f32x4 v0 = xv[g & 1][bj][0] + gv[bj][0] * (acc[ai][bj][m][0] * rs_), v1 = xv[g & 1][bj][1] + gv[bj][1] * (acc[ai][bj][m][1] * rs_);
;                 u32x4 w; w.x = cvt_pk_bf16(v0[0], v0[1]); w.y = cvt_pk_bf16(v0[2], v0[3]); w.z = cvt_pk_bf16(v1[0], v1[1]); w.w = cvt_pk_bf16(v1[2], v1[3]);
;                 *(u32x4*)(out + off + bj * HALF) = w; } }
	v_pk_mul_f32 v[112:113], v[112:113], v[222:223] op_sel_hi:[1,0]
	v_pk_mul_f32 v[114:115], v[114:115], v[222:223] op_sel_hi:[1,0]
	v_pk_mul_f32 v[108:109], v[108:109], v[222:223] op_sel_hi:[1,0]
	v_pk_mul_f32 v[110:111], v[110:111], v[222:223] op_sel_hi:[1,0]
	v_lshlrev_b32_e32 v160, 16, v192
	v_and_b32_e32 v161, 0xffff0000, v192
	v_lshlrev_b32_e32 v174, 16, v193
	v_and_b32_e32 v175, 0xffff0000, v193
	v_lshlrev_b32_e32 v196, 16, v194
	v_and_b32_e32 v197, 0xffff0000, v194
	v_lshlrev_b32_e32 v210, 16, v195
	v_and_b32_e32 v211, 0xffff0000, v195
	v_pk_fma_f32 v[112:113], v[60:61], v[112:113], v[160:161]
	v_pk_fma_f32 v[114:115], v[62:63], v[114:115], v[174:175]
	v_pk_fma_f32 v[108:109], v[56:57], v[108:109], v[196:197]
	v_pk_fma_f32 v[110:111], v[58:59], v[110:111], v[210:211]
	v_cvt_pk_bf16_f32 v192, v112, v113
	v_cvt_pk_bf16_f32 v193, v114, v115
	v_cvt_pk_bf16_f32 v194, v108, v109
	v_cvt_pk_bf16_f32 v195, v110, v111
	global_store_dwordx4 v213, v[192:195], s[100:101] sc0 sc1
	v_pk_mul_f32 v[104:105], v[104:105], v[222:223] op_sel_hi:[1,0]
	v_pk_mul_f32 v[106:107], v[106:107], v[222:223] op_sel_hi:[1,0]
	v_pk_mul_f32 v[100:101], v[100:101], v[222:223] op_sel_hi:[1,0]
	v_pk_mul_f32 v[102:103], v[102:103], v[222:223] op_sel_hi:[1,0]
	v_lshlrev_b32_e32 v160, 16, v224
	v_and_b32_e32 v161, 0xffff0000, v224
	v_lshlrev_b32_e32 v174, 16, v225
	v_and_b32_e32 v175, 0xffff0000, v225
	v_lshlrev_b32_e32 v196, 16, v226
	v_and_b32_e32 v197, 0xffff0000, v226
	v_lshlrev_b32_e32 v210, 16, v227
	v_and_b32_e32 v211, 0xffff0000, v227
	v_pk_fma_f32 v[104:105], v[52:53], v[104:105], v[160:161]
	v_pk_fma_f32 v[106:107], v[54:55], v[106:107], v[174:175]
	v_pk_fma_f32 v[100:101], v[48:49], v[100:101], v[196:197]
	v_pk_fma_f32 v[102:103], v[50:51], v[102:103], v[210:211]
	v_cvt_pk_bf16_f32 v224, v104, v105
	v_cvt_pk_bf16_f32 v225, v106, v107
	v_cvt_pk_bf16_f32 v226, v100, v101
	v_cvt_pk_bf16_f32 v227, v102, v103
	global_store_dwordx4 v213, v[224:227], s[100:101] offset:256 sc0 sc1
	s_add_u32 s100, s100, 0x8000
	s_addc_u32 s101, s101, 0
	global_load_dwordx4 v[192:195], v213, s[98:99]
	global_load_dwordx4 v[224:227], v213, s[98:99] offset:256
	s_add_u32 s98, s98, 0x8000
	s_addc_u32 s99, s99, 0
	s_waitcnt vmcnt(14)
	v_pk_mul_f32 v[96:97], v[96:97], v[228:229] op_sel_hi:[1,0]
	v_pk_mul_f32 v[98:99], v[98:99], v[228:229] op_sel_hi:[1,0]
	v_pk_mul_f32 v[92:93], v[92:93], v[228:229] op_sel_hi:[1,0]
	v_pk_mul_f32 v[94:95], v[94:95], v[228:229] op_sel_hi:[1,0]
	v_lshlrev_b32_e32 v160, 16, v232
	v_and_b32_e32 v161, 0xffff0000, v232
	v_lshlrev_b32_e32 v174, 16, v233
	v_and_b32_e32 v175, 0xffff0000, v233
	v_lshlrev_b32_e32 v196, 16, v234
	v_and_b32_e32 v197, 0xffff0000, v234
	v_lshlrev_b32_e32 v210, 16, v235
	v_and_b32_e32 v211, 0xffff0000, v235
	v_pk_fma_f32 v[96:97], v[60:61], v[96:97], v[160:161]
	v_pk_fma_f32 v[98:99], v[62:63], v[98:99], v[174:175]
	v_pk_fma_f32 v[92:93], v[56:57], v[92:93], v[196:197]
	v_pk_fma_f32 v[94:95], v[58:59], v[94:95], v[210:211]
	v_cvt_pk_bf16_f32 v232, v96, v97
	v_cvt_pk_bf16_f32 v233, v98, v99
	v_cvt_pk_bf16_f32 v234, v92, v93
	v_cvt_pk_bf16_f32 v235, v94, v95
	global_store_dwordx4 v213, v[232:235], s[100:101] sc0 sc1
	v_pk_mul_f32 v[88:89], v[88:89], v[228:229] op_sel_hi:[1,0]
	v_pk_mul_f32 v[90:91], v[90:91], v[228:229] op_sel_hi:[1,0]
	v_pk_mul_f32 v[84:85], v[84:85], v[228:229] op_sel_hi:[1,0]
	v_pk_mul_f32 v[86:87], v[86:87], v[228:229] op_sel_hi:[1,0]
	v_lshlrev_b32_e32 v160, 16, v236
	v_and_b32_e32 v161, 0xffff0000, v236
	v_lshlrev_b32_e32 v174, 16, v237
	v_and_b32_e32 v175, 0xffff0000, v237
	v_lshlrev_b32_e32 v196, 16, v238
	v_and_b32_e32 v197, 0xffff0000, v238
	v_lshlrev_b32_e32 v210, 16, v239
	v_and_b32_e32 v211, 0xffff0000, v239
	v_pk_fma_f32 v[88:89], v[52:53], v[88:89], v[160:161]
	v_pk_fma_f32 v[90:91], v[54:55], v[90:91], v[174:175]
	v_pk_fma_f32 v[84:85], v[48:49], v[84:85], v[196:197]
	v_pk_fma_f32 v[86:87], v[50:51], v[86:87], v[210:211]
	v_cvt_pk_bf16_f32 v236, v88, v89
	v_cvt_pk_bf16_f32 v237, v90, v91
	v_cvt_pk_bf16_f32 v238, v84, v85
	v_cvt_pk_bf16_f32 v239, v86, v87
	global_store_dwordx4 v213, v[236:239], s[100:101] offset:256 sc0 sc1
	s_add_u32 s100, s100, 0x28000
	s_addc_u32 s101, s101, 0
	s_waitcnt vmcnt(14)
	v_pk_mul_f32 v[76:77], v[76:77], v[230:231] op_sel_hi:[1,0]
	v_pk_mul_f32 v[78:79], v[78:79], v[230:231] op_sel_hi:[1,0]
	v_pk_mul_f32 v[72:73], v[72:73], v[230:231] op_sel_hi:[1,0]
	v_pk_mul_f32 v[74:75], v[74:75], v[230:231] op_sel_hi:[1,0]
	v_lshlrev_b32_e32 v160, 16, v240
	v_and_b32_e32 v161, 0xffff0000, v240
	v_lshlrev_b32_e32 v174, 16, v241
	v_and_b32_e32 v175, 0xffff0000, v241
	v_lshlrev_b32_e32 v196, 16, v242
	v_and_b32_e32 v197, 0xffff0000, v242
	v_lshlrev_b32_e32 v210, 16, v243
	v_and_b32_e32 v211, 0xffff0000, v243
	v_pk_fma_f32 v[76:77], v[60:61], v[76:77], v[160:161]
	v_pk_fma_f32 v[78:79], v[62:63], v[78:79], v[174:175]
	v_pk_fma_f32 v[72:73], v[56:57], v[72:73], v[196:197]
	v_pk_fma_f32 v[74:75], v[58:59], v[74:75], v[210:211]
	v_cvt_pk_bf16_f32 v240, v76, v77
	v_cvt_pk_bf16_f32 v241, v78, v79
	v_cvt_pk_bf16_f32 v242, v72, v73
	v_cvt_pk_bf16_f32 v243, v74, v75
	global_store_dwordx4 v213, v[240:243], s[100:101] sc0 sc1
	v_pk_mul_f32 v[68:69], v[68:69], v[230:231] op_sel_hi:[1,0]
	v_pk_mul_f32 v[70:71], v[70:71], v[230:231] op_sel_hi:[1,0]
	v_pk_mul_f32 v[64:65], v[64:65], v[230:231] op_sel_hi:[1,0]
	v_pk_mul_f32 v[66:67], v[66:67], v[230:231] op_sel_hi:[1,0]
	v_lshlrev_b32_e32 v160, 16, v244
	v_and_b32_e32 v161, 0xffff0000, v244
	v_lshlrev_b32_e32 v174, 16, v245
	v_and_b32_e32 v175, 0xffff0000, v245
	v_lshlrev_b32_e32 v196, 16, v246
	v_and_b32_e32 v197, 0xffff0000, v246
	v_lshlrev_b32_e32 v210, 16, v247
	v_and_b32_e32 v211, 0xffff0000, v247
	v_pk_fma_f32 v[68:69], v[52:53], v[68:69], v[160:161]
	v_pk_fma_f32 v[70:71], v[54:55], v[70:71], v[174:175]
	v_pk_fma_f32 v[64:65], v[48:49], v[64:65], v[196:197]
	v_pk_fma_f32 v[66:67], v[50:51], v[66:67], v[210:211]
	v_cvt_pk_bf16_f32 v244, v68, v69
	v_cvt_pk_bf16_f32 v245, v70, v71
	v_cvt_pk_bf16_f32 v246, v64, v65
	v_cvt_pk_bf16_f32 v247, v66, v67
	global_store_dwordx4 v213, v[244:247], s[100:101] offset:256 sc0 sc1
	s_add_u32 s100, s100, 0x8000
	s_addc_u32 s101, s101, 0
	s_waitcnt vmcnt(12)
; __device__ __forceinline__ unsigned cvt_pk_bf16(float lo, float hi) { f32x2_cv v = {lo, hi}; bf16x2_cv b = __builtin_convertvector(v, bf16x2_cv); return __builtin_bit_cast(unsigned, b); }
;     __device__ __forceinline__ void operator()(const f32x4 (&acc)[2][2][4][2], const Unit& u, int wr, int wc, int fr, int fq) const {
;     ...
;         for (int g = 0; g < 8; ++g) { const int ai = g >> 2, m = g & 3; const size_t off = (size_t)(row0 + ai * HALF + m * 16) * 1024 + col0;
;             if (g + 1 < 8) { const int ai2 = (g + 1) >> 2, m2 = (g + 1) & 3; load_x(xv[(g + 1) & 1], (size_t)(row0 + ai2 * HALF + m2 * 16) * 1024 + col0); }
;             float rs_ = 1.0f; if constexpr (ROWSCALE) rs_ = tab[((u.pm == pm0 ? 0 : 256) + ai * HALF + wr * 64 + m * 16 + fr) * 2 + 1];
; #pragma unroll
;             for (int bj = 0; bj < 2; ++bj) { const f32x4 v0 = xv[g & 1][bj][0] + gv[bj][0] * (acc[ai][bj][m][0] * rs_), v1 = xv[g & 1][bj][1] + gv[bj][1] * (acc[ai][bj][m][1] * rs_);
;                 u32x4 w; w.x = cvt_pk_bf16(v0[0], v0[1]); w.y = cvt_pk_bf16(v0[2], v0[3]); w.z = cvt_pk_bf16(v1[0], v1[1]); w.w = cvt_pk_bf16(v1[2], v1[3]);
;                 *(u32x4*)(out + off + bj * HALF) = w; } }
	v_pk_mul_f32 v[44:45], v[44:45], v[248:249] op_sel_hi:[1,0]
	v_pk_mul_f32 v[46:47], v[46:47], v[248:249] op_sel_hi:[1,0]
	v_pk_mul_f32 v[40:41], v[40:41], v[248:249] op_sel_hi:[1,0]
	v_pk_mul_f32 v[42:43], v[42:43], v[248:249] op_sel_hi:[1,0]
	v_lshlrev_b32_e32 v160, 16, v176
	v_and_b32_e32 v161, 0xffff0000, v176
	v_lshlrev_b32_e32 v174, 16, v177
	v_and_b32_e32 v175, 0xffff0000, v177
	v_lshlrev_b32_e32 v196, 16, v178
	v_and_b32_e32 v197, 0xffff0000, v178
	v_lshlrev_b32_e32 v210, 16, v179
	v_and_b32_e32 v211, 0xffff0000, v179
	v_pk_fma_f32 v[44:45], v[60:61], v[44:45], v[160:161]
	v_pk_fma_f32 v[46:47], v[62:63], v[46:47], v[174:175]
	v_pk_fma_f32 v[40:41], v[56:57], v[40:41], v[196:197]
	v_pk_fma_f32 v[42:43], v[58:59], v[42:43], v[210:211]
	v_cvt_pk_bf16_f32 v176, v44, v45
	v_cvt_pk_bf16_f32 v177, v46, v47
	v_cvt_pk_bf16_f32 v178, v40, v41
	v_cvt_pk_bf16_f32 v179, v42, v43
	global_store_dwordx4 v213, v[176:179], s[100:101] sc0 sc1
	v_pk_mul_f32 v[36:37], v[36:37], v[248:249] op_sel_hi:[1,0]
	v_pk_mul_f32 v[38:39], v[38:39], v[248:249] op_sel_hi:[1,0]
	v_pk_mul_f32 v[32:33], v[32:33], v[248:249] op_sel_hi:[1,0]
	v_pk_mul_f32 v[34:35], v[34:35], v[248:249] op_sel_hi:[1,0]
	v_lshlrev_b32_e32 v160, 16, v180
	v_and_b32_e32 v161, 0xffff0000, v180
	v_lshlrev_b32_e32 v174, 16, v181
	v_and_b32_e32 v175, 0xffff0000, v181
	v_lshlrev_b32_e32 v196, 16, v182
	v_and_b32_e32 v197, 0xffff0000, v182
	v_lshlrev_b32_e32 v210, 16, v183
	v_and_b32_e32 v211, 0xffff0000, v183
	v_pk_fma_f32 v[36:37], v[52:53], v[36:37], v[160:161]
	v_pk_fma_f32 v[38:39], v[54:55], v[38:39], v[174:175]
	v_pk_fma_f32 v[32:33], v[48:49], v[32:33], v[196:197]
	v_pk_fma_f32 v[34:35], v[50:51], v[34:35], v[210:211]
	v_cvt_pk_bf16_f32 v180, v36, v37
	v_cvt_pk_bf16_f32 v181, v38, v39
	v_cvt_pk_bf16_f32 v182, v32, v33
	v_cvt_pk_bf16_f32 v183, v34, v35
	global_store_dwordx4 v213, v[180:183], s[100:101] offset:256 sc0 sc1
	s_add_u32 s100, s100, 0x8000
	s_addc_u32 s101, s101, 0
	s_waitcnt vmcnt(10)
	v_pk_mul_f32 v[28:29], v[28:29], v[250:251] op_sel_hi:[1,0]
	v_pk_mul_f32 v[30:31], v[30:31], v[250:251] op_sel_hi:[1,0]
	v_pk_mul_f32 v[24:25], v[24:25], v[250:251] op_sel_hi:[1,0]
	v_pk_mul_f32 v[26:27], v[26:27], v[250:251] op_sel_hi:[1,0]
	v_lshlrev_b32_e32 v160, 16, v184
	v_and_b32_e32 v161, 0xffff0000, v184
	v_lshlrev_b32_e32 v174, 16, v185
	v_and_b32_e32 v175, 0xffff0000, v185
	v_lshlrev_b32_e32 v196, 16, v186
	v_and_b32_e32 v197, 0xffff0000, v186
	v_lshlrev_b32_e32 v210, 16, v187
	v_and_b32_e32 v211, 0xffff0000, v187
	v_pk_fma_f32 v[28:29], v[60:61], v[28:29], v[160:161]
	v_pk_fma_f32 v[30:31], v[62:63], v[30:31], v[174:175]
	v_pk_fma_f32 v[24:25], v[56:57], v[24:25], v[196:197]
	v_pk_fma_f32 v[26:27], v[58:59], v[26:27], v[210:211]
	v_cvt_pk_bf16_f32 v184, v28, v29
	v_cvt_pk_bf16_f32 v185, v30, v31
	v_cvt_pk_bf16_f32 v186, v24, v25
	v_cvt_pk_bf16_f32 v187, v26, v27
	global_store_dwordx4 v213, v[184:187], s[100:101] sc0 sc1
	v_pk_mul_f32 v[20:21], v[20:21], v[250:251] op_sel_hi:[1,0]
	v_pk_mul_f32 v[22:23], v[22:23], v[250:251] op_sel_hi:[1,0]
	v_pk_mul_f32 v[16:17], v[16:17], v[250:251] op_sel_hi:[1,0]
	v_pk_mul_f32 v[18:19], v[18:19], v[250:251] op_sel_hi:[1,0]
	v_lshlrev_b32_e32 v160, 16, v188
	v_and_b32_e32 v161, 0xffff0000, v188
	v_lshlrev_b32_e32 v174, 16, v189
	v_and_b32_e32 v175, 0xffff0000, v189
	v_lshlrev_b32_e32 v196, 16, v190
	v_and_b32_e32 v197, 0xffff0000, v190
	v_lshlrev_b32_e32 v210, 16, v191
	v_and_b32_e32 v211, 0xffff0000, v191
	v_pk_fma_f32 v[20:21], v[52:53], v[20:21], v[160:161]
	v_pk_fma_f32 v[22:23], v[54:55], v[22:23], v[174:175]
	v_pk_fma_f32 v[16:17], v[48:49], v[16:17], v[196:197]
	v_pk_fma_f32 v[18:19], v[50:51], v[18:19], v[210:211]
	v_cvt_pk_bf16_f32 v188, v20, v21
	v_cvt_pk_bf16_f32 v189, v22, v23
	v_cvt_pk_bf16_f32 v190, v16, v17
	v_cvt_pk_bf16_f32 v191, v18, v19
	global_store_dwordx4 v213, v[188:191], s[100:101] offset:256 sc0 sc1
	s_add_u32 s100, s100, 0x8000
	s_addc_u32 s101, s101, 0
	s_waitcnt vmcnt(8)
	v_pk_mul_f32 v[12:13], v[12:13], v[82:83] op_sel_hi:[1,0]
	v_pk_mul_f32 v[14:15], v[14:15], v[82:83] op_sel_hi:[1,0]
	v_pk_mul_f32 v[8:9], v[8:9], v[82:83] op_sel_hi:[1,0]
	v_pk_mul_f32 v[10:11], v[10:11], v[82:83] op_sel_hi:[1,0]
	v_lshlrev_b32_e32 v160, 16, v192
	v_and_b32_e32 v161, 0xffff0000, v192
	v_lshlrev_b32_e32 v174, 16, v193
	v_and_b32_e32 v175, 0xffff0000, v193
	v_lshlrev_b32_e32 v196, 16, v194
	v_and_b32_e32 v197, 0xffff0000, v194
	v_lshlrev_b32_e32 v210, 16, v195
	v_and_b32_e32 v211, 0xffff0000, v195
	v_pk_fma_f32 v[12:13], v[60:61], v[12:13], v[160:161]
	v_pk_fma_f32 v[14:15], v[62:63], v[14:15], v[174:175]
	v_pk_fma_f32 v[8:9], v[56:57], v[8:9], v[196:197]
	v_pk_fma_f32 v[10:11], v[58:59], v[10:11], v[210:211]
	v_cvt_pk_bf16_f32 v192, v12, v13
	v_cvt_pk_bf16_f32 v193, v14, v15
	v_cvt_pk_bf16_f32 v194, v8, v9
	v_cvt_pk_bf16_f32 v195, v10, v11
	global_store_dwordx4 v213, v[192:195], s[100:101] sc0 sc1
	v_pk_mul_f32 v[4:5], v[4:5], v[82:83] op_sel_hi:[1,0]
	v_pk_mul_f32 v[6:7], v[6:7], v[82:83] op_sel_hi:[1,0]
	v_pk_mul_f32 v[0:1], v[0:1], v[82:83] op_sel_hi:[1,0]
	v_pk_mul_f32 v[2:3], v[2:3], v[82:83] op_sel_hi:[1,0]
	v_lshlrev_b32_e32 v160, 16, v224
	v_and_b32_e32 v161, 0xffff0000, v224
	v_lshlrev_b32_e32 v174, 16, v225
	v_and_b32_e32 v175, 0xffff0000, v225
	v_lshlrev_b32_e32 v196, 16, v226
	v_and_b32_e32 v197, 0xffff0000, v226
	v_lshlrev_b32_e32 v210, 16, v227
	v_and_b32_e32 v211, 0xffff0000, v227
	v_pk_fma_f32 v[4:5], v[52:53], v[4:5], v[160:161]
	v_pk_fma_f32 v[6:7], v[54:55], v[6:7], v[174:175]
	v_pk_fma_f32 v[0:1], v[48:49], v[0:1], v[196:197]
	v_pk_fma_f32 v[2:3], v[50:51], v[2:3], v[210:211]
	v_cvt_pk_bf16_f32 v224, v4, v5
	v_cvt_pk_bf16_f32 v225, v6, v7
	v_cvt_pk_bf16_f32 v226, v0, v1
	v_cvt_pk_bf16_f32 v227, v2, v3
	global_store_dwordx4 v213, v[224:227], s[100:101] offset:256 sc0 sc1
	s_add_u32 s100, s100, 0x8000
	s_addc_u32 s101, s101, 0
	s_mov_b64 s[4:5], -1
	s_andn2_b64 vcc, exec, s[36:37]
	s_cbranch_vccnz .LBB0_404
	s_andn2_b64 vcc, exec, s[42:43]
	s_cbranch_vccnz .LBB0_403
	s_barrier
	s_branch .LBB0_403

;     __device__ __forceinline__ void load_x(f32x4 (&x)[2][2], size_t off) const {
; #pragma unroll
;         for (int bj = 0; bj < 2; ++bj) {
;             if constexpr (XIN_F32) { x[bj][0] = *(const f32x4*)((const float*)xin + off + bj * HALF); x[bj][1] = *(const f32x4*)((const float*)xin + off + bj * HALF + 4); }
;             else { const u32x4 w = *(const u32x4*)((const bf16_t*)xin + off + bj * HALF);
;                 x[bj][0] = (f32x4){__builtin_bit_cast(float, w.x << 16), __builtin_bit_cast(float, w.x & 0xffff0000u), __builtin_bit_cast(float, w.y << 16), __builtin_bit_cast(float, w.y & 0xffff0000u)};
;                 x[bj][1] = (f32x4){__builtin_bit_cast(float, w.z << 16), __builtin_bit_cast(float, w.z & 0xffff0000u), __builtin_bit_cast(float, w.w << 16), __builtin_bit_cast(float, w.w & 0xffff0000u)}; } }
;     }
;     __device__ __forceinline__ void operator()(const f32x4 (&acc)[2][2][4][2], const Unit& u, int wr, int wc, int fr, int fq) const {
;         const int row0 = u.pm * BM + wr * 64 + fr; const int col0 = u.pn * BM + wc * 32 + 8 * fq;
;         const int b = (u.pm * BM) >> 12;
;         f32x4 gv[2][2];
; #pragma unroll
;         for (int bj = 0; bj < 2; ++bj)
; #pragma unroll
;             for (int n = 0; n < 2; ++n) gv[bj][n] = *(const f32x4*)(gate + (size_t)b * gate_ld + col0 + bj * HALF + n * 4);
;         f32x4 xv[2][2][2];
;         load_x(xv[0], (size_t)row0 * 1024 + col0);
; #pragma unroll
;         for (int g = 0; g < 8; ++g) { const int ai = g >> 2, m = g & 3; const size_t off = (size_t)(row0 + ai * HALF + m * 16) * 1024 + col0;
;             if (g + 1 < 8) { const int ai2 = (g + 1) >> 2, m2 = (g + 1) & 3; load_x(xv[(g + 1) & 1], (size_t)(row0 + ai2 * HALF + m2 * 16) * 1024 + col0); }
;             float rs_ = 1.0f; if constexpr (ROWSCALE) rs_ = tab[((u.pm == pm0 ? 0 : 256) + ai * HALF + wr * 64 + m * 16 + fr) * 2 + 1];
; #pragma unroll
;             for (int bj = 0; bj < 2; ++bj) { const f32x4 v0 = xv[g & 1][bj][0] + gv[bj][0] * (acc[ai][bj][m][0] * rs_), v1 = xv[g & 1][bj][1] + gv[bj][1] * (acc[ai][bj][m][1] * rs_);
;                 u32x4 w; w.x = cvt_pk_bf16(v0[0], v0[1]); w.y = cvt_pk_bf16(v0[2], v0[3]); w.z = cvt_pk_bf16(v1[0], v1[1]); w.w = cvt_pk_bf16(v1[2], v1[3]);
;                 *(u32x4*)(out + off + bj * HALF) = w; } }
.LBB0_445:
	s_ashr_i32 s3, s4, 4
	v_lshl_or_b32 v205, s5, 8, v191
	s_mul_hi_i32 s5, s3, 0x6000
	s_mulk_i32 s3, 0x6000
	v_readlane_b32 s80, v254, 4
	s_add_u32 s12, s64, s3
	v_readlane_b32 s81, v254, 5
	s_addc_u32 s13, s65, s5
	v_lshlrev_b32_e32 v211, 2, v205
	global_load_dwordx4 v[76:79], v211, s[12:13]
	global_load_dwordx4 v[72:75], v211, s[12:13] offset:16
	global_load_dwordx4 v[68:71], v211, s[12:13] offset:512
	global_load_dwordx4 v[64:67], v211, s[12:13] offset:528
	v_lshl_add_u32 v185, v186, 12, v211
	v_lshlrev_b32_e32 v195, 11, v186
	v_lshl_add_u32 v195, v205, 1, v195
	s_lshl_b32 s3, s4, 20
	s_add_u32 s98, s80, s3
	s_addc_u32 s99, s81, 0
	s_lshl_b32 s3, s4, 19
	s_add_u32 s100, s38, s3
	s_addc_u32 s101, s39, 0
	global_load_dwordx4 v[148:151], v185, s[98:99]
	global_load_dwordx4 v[152:155], v185, s[98:99] offset:16
	global_load_dwordx4 v[180:183], v185, s[98:99] offset:512
	global_load_dwordx4 v[196:199], v185, s[98:99] offset:528
	s_add_u32 s98, s98, 0x10000
	s_addc_u32 s99, s99, 0
	global_load_dwordx4 v[200:203], v185, s[98:99]
	global_load_dwordx4 v[220:223], v185, s[98:99] offset:16
	global_load_dwordx4 v[224:227], v185, s[98:99] offset:512
	global_load_dwordx4 v[228:231], v185, s[98:99] offset:528
	s_add_u32 s98, s98, 0x10000
	s_addc_u32 s99, s99, 0
	global_load_dwordx4 v[236:239], v185, s[98:99]
	global_load_dwordx4 v[240:243], v185, s[98:99] offset:16
	global_load_dwordx4 v[244:247], v185, s[98:99] offset:512
	global_load_dwordx4 v[248:251], v185, s[98:99] offset:528
	s_add_u32 s98, s98, 0x10000
	s_addc_u32 s99, s99, 0
	v_readlane_b32 s3, v255, 49
	s_nop 0
	s_cmp_eq_u32 s4, s3
	s_cselect_b32 s4, 0, 0x100
	v_add_u32_e32 v83, s4, v186
	s_add_i32 s5, 0, 0x22800
	v_lshl_add_u32 v83, v83, 3, s5
	s_andn2_b64 vcc, exec, s[36:37]
	s_mov_b32 s78, s1
	v_readlane_b32 s82, v254, 6
	v_readlane_b32 s83, v254, 7
	v_readlane_b32 s84, v254, 8
	v_readlane_b32 s85, v254, 9
	v_readlane_b32 s86, v254, 10
	v_readlane_b32 s87, v254, 11
	v_readlane_b32 s88, v254, 12
	v_readlane_b32 s89, v254, 13
	v_readlane_b32 s90, v254, 14
	v_readlane_b32 s91, v254, 15
	v_readlane_b32 s92, v254, 16
	v_readlane_b32 s93, v254, 17
	v_readlane_b32 s94, v254, 18
	v_readlane_b32 s95, v254, 19
	ds_read_b32 v184, v83 offset:4
	ds_read_b32 v194, v83 offset:132
	ds_read_b32 v204, v83 offset:260
	ds_read_b32 v210, v83 offset:388
	ds_read_b32 v232, v83 offset:1028
	ds_read_b32 v234, v83 offset:1156
	ds_read_b32 v82, v83 offset:1284
	ds_read_b32 v80, v83 offset:1412
	s_waitcnt lgkmcnt(0)
	s_waitcnt vmcnt(8)
	v_pk_mul_f32 v[144:145], v[144:145], v[184:185] op_sel_hi:[1,0]
	v_pk_mul_f32 v[146:147], v[146:147], v[184:185] op_sel_hi:[1,0]
	v_pk_mul_f32 v[140:141], v[140:141], v[184:185] op_sel_hi:[1,0]
	v_pk_mul_f32 v[142:143], v[142:143], v[184:185] op_sel_hi:[1,0]
	v_pk_fma_f32 v[144:145], v[76:77], v[144:145], v[148:149]
	v_pk_fma_f32 v[146:147], v[78:79], v[146:147], v[150:151]
	v_pk_fma_f32 v[140:141], v[72:73], v[140:141], v[152:153]
	v_pk_fma_f32 v[142:143], v[74:75], v[142:143], v[154:155]
	v_cvt_pk_bf16_f32 v148, v144, v145
	v_cvt_pk_bf16_f32 v149, v146, v147
	v_cvt_pk_bf16_f32 v150, v140, v141
	v_cvt_pk_bf16_f32 v151, v142, v143
	global_store_dwordx4 v195, v[148:151], s[100:101] sc0 sc1
	v_pk_mul_f32 v[136:137], v[136:137], v[184:185] op_sel_hi:[1,0]
	v_pk_mul_f32 v[138:139], v[138:139], v[184:185] op_sel_hi:[1,0]
	v_pk_mul_f32 v[132:133], v[132:133], v[184:185] op_sel_hi:[1,0]
	v_pk_mul_f32 v[134:135], v[134:135], v[184:185] op_sel_hi:[1,0]
	v_pk_fma_f32 v[136:137], v[68:69], v[136:137], v[180:181]
	v_pk_fma_f32 v[138:139], v[70:71], v[138:139], v[182:183]
	v_pk_fma_f32 v[132:133], v[64:65], v[132:133], v[196:197]
	v_pk_fma_f32 v[134:135], v[66:67], v[134:135], v[198:199]
	v_cvt_pk_bf16_f32 v180, v136, v137
	v_cvt_pk_bf16_f32 v181, v138, v139
	v_cvt_pk_bf16_f32 v182, v132, v133
	v_cvt_pk_bf16_f32 v183, v134, v135
	global_store_dwordx4 v195, v[180:183], s[100:101] offset:256 sc0 sc1
	s_add_u32 s100, s100, 0x8000
	s_addc_u32 s101, s101, 0
	global_load_dwordx4 v[148:151], v185, s[98:99]
	global_load_dwordx4 v[152:155], v185, s[98:99] offset:16
	global_load_dwordx4 v[180:183], v185, s[98:99] offset:512
	global_load_dwordx4 v[196:199], v185, s[98:99] offset:528
	s_add_u32 s98, s98, 0x50000
	s_addc_u32 s99, s99, 0
	s_waitcnt vmcnt(10)
	v_pk_mul_f32 v[128:129], v[128:129], v[194:195] op_sel_hi:[1,0]
	v_pk_mul_f32 v[130:131], v[130:131], v[194:195] op_sel_hi:[1,0]
	v_pk_mul_f32 v[124:125], v[124:125], v[194:195] op_sel_hi:[1,0]
	v_pk_mul_f32 v[126:127], v[126:127], v[194:195] op_sel_hi:[1,0]
	v_pk_fma_f32 v[128:129], v[76:77], v[128:129], v[200:201]
	v_pk_fma_f32 v[130:131], v[78:79], v[130:131], v[202:203]
	v_pk_fma_f32 v[124:125], v[72:73], v[124:125], v[220:221]
	v_pk_fma_f32 v[126:127], v[74:75], v[126:127], v[222:223]
	v_cvt_pk_bf16_f32 v200, v128, v129
	v_cvt_pk_bf16_f32 v201, v130, v131
	v_cvt_pk_bf16_f32 v202, v124, v125
	v_cvt_pk_bf16_f32 v203, v126, v127
	global_store_dwordx4 v195, v[200:203], s[100:101] sc0 sc1
	v_pk_mul_f32 v[120:121], v[120:121], v[194:195] op_sel_hi:[1,0]
	v_pk_mul_f32 v[122:123], v[122:123], v[194:195] op_sel_hi:[1,0]
	v_pk_mul_f32 v[116:117], v[116:117], v[194:195] op_sel_hi:[1,0]
	v_pk_mul_f32 v[118:119], v[118:119], v[194:195] op_sel_hi:[1,0]
	v_pk_fma_f32 v[120:121], v[68:69], v[120:121], v[224:225]
	v_pk_fma_f32 v[122:123], v[70:71], v[122:123], v[226:227]
	v_pk_fma_f32 v[116:117], v[64:65], v[116:117], v[228:229]
	v_pk_fma_f32 v[118:119], v[66:67], v[118:119], v[230:231]
	v_cvt_pk_bf16_f32 v224, v120, v121
	v_cvt_pk_bf16_f32 v225, v122, v123
	v_cvt_pk_bf16_f32 v226, v116, v117
	v_cvt_pk_bf16_f32 v227, v118, v119
	global_store_dwordx4 v195, v[224:227], s[100:101] offset:256 sc0 sc1
	s_add_u32 s100, s100, 0x8000
	s_addc_u32 s101, s101, 0
	global_load_dwordx4 v[200:203], v185, s[98:99]
	global_load_dwordx4 v[220:223], v185, s[98:99] offset:16
	global_load_dwordx4 v[224:227], v185, s[98:99] offset:512
	global_load_dwordx4 v[228:231], v185, s[98:99] offset:528
	s_add_u32 s98, s98, 0x10000
	s_addc_u32 s99, s99, 0
	s_waitcnt vmcnt(12)
; __device__ __forceinline__ unsigned cvt_pk_bf16(float lo, float hi) { f32x2_cv v = {lo, hi}; bf16x2_cv b = __builtin_convertvector(v, bf16x2_cv); return __builtin_bit_cast(unsigned, b); }
;     __device__ __forceinline__ void operator()(const f32x4 (&acc)[2][2][4][2], const Unit& u, int wr, int wc, int fr, int fq) const {
;     ...
;         for (int g = 0; g < 8; ++g) { const int ai = g >> 2, m = g & 3; const size_t off = (size_t)(row0 + ai * HALF + m * 16) * 1024 + col0;
;             if (g + 1 < 8) { const int ai2 = (g + 1) >> 2, m2 = (g + 1) & 3; load_x(xv[(g + 1) & 1], (size_t)(row0 + ai2 * HALF + m2 * 16) * 1024 + col0); }
;             float rs_ = 1.0f; if constexpr (ROWSCALE) rs_ = tab[((u.pm == pm0 ? 0 : 256) + ai * HALF + wr * 64 + m * 16 + fr) * 2 + 1];
; #pragma unroll
;             for (int bj = 0; bj < 2; ++bj) { const f32x4 v0 = xv[g & 1][bj][0] + gv[bj][0] * (acc[ai][bj][m][0] * rs_), v1 = xv[g & 1][bj][1] + gv[bj][1] * (acc[ai][bj][m][1] * rs_);
;                 u32x4 w; w.x = cvt_pk_bf16(v0[0], v0[1]); w.y = cvt_pk_bf16(v0[2], v0[3]); w.z = cvt_pk_bf16(v1[0], v1[1]); w.w = cvt_pk_bf16(v1[2], v1[3]);
;                 *(u32x4*)(out + off + bj * HALF) = w; } }
	v_pk_mul_f32 v[112:113], v[112:113], v[204:205] op_sel_hi:[1,0]
	v_pk_mul_f32 v[114:115], v[114:115], v[204:205] op_sel_hi:[1,0]
	v_pk_mul_f32 v[108:109], v[108:109], v[204:205] op_sel_hi:[1,0]
	v_pk_mul_f32 v[110:111], v[110:111], v[204:205] op_sel_hi:[1,0]
	v_pk_fma_f32 v[112:113], v[76:77], v[112:113], v[236:237]
	v_pk_fma_f32 v[114:115], v[78:79], v[114:115], v[238:239]
	v_pk_fma_f32 v[108:109], v[72:73], v[108:109], v[240:241]
	v_pk_fma_f32 v[110:111], v[74:75], v[110:111], v[242:243]
	v_cvt_pk_bf16_f32 v236, v112, v113
	v_cvt_pk_bf16_f32 v237, v114, v115
	v_cvt_pk_bf16_f32 v238, v108, v109
	v_cvt_pk_bf16_f32 v239, v110, v111
	global_store_dwordx4 v195, v[236:239], s[100:101] sc0 sc1
	v_pk_mul_f32 v[104:105], v[104:105], v[204:205] op_sel_hi:[1,0]
	v_pk_mul_f32 v[106:107], v[106:107], v[204:205] op_sel_hi:[1,0]
	v_pk_mul_f32 v[100:101], v[100:101], v[204:205] op_sel_hi:[1,0]
	v_pk_mul_f32 v[102:103], v[102:103], v[204:205] op_sel_hi:[1,0]
	v_pk_fma_f32 v[104:105], v[68:69], v[104:105], v[244:245]
	v_pk_fma_f32 v[106:107], v[70:71], v[106:107], v[246:247]
	v_pk_fma_f32 v[100:101], v[64:65], v[100:101], v[248:249]
	v_pk_fma_f32 v[102:103], v[66:67], v[102:103], v[250:251]
	v_cvt_pk_bf16_f32 v244, v104, v105
	v_cvt_pk_bf16_f32 v245, v106, v107
	v_cvt_pk_bf16_f32 v246, v100, v101
	v_cvt_pk_bf16_f32 v247, v102, v103
	global_store_dwordx4 v195, v[244:247], s[100:101] offset:256 sc0 sc1
	s_add_u32 s100, s100, 0x8000
	s_addc_u32 s101, s101, 0
	global_load_dwordx4 v[236:239], v185, s[98:99]
	global_load_dwordx4 v[240:243], v185, s[98:99] offset:16
	global_load_dwordx4 v[244:247], v185, s[98:99] offset:512
	global_load_dwordx4 v[248:251], v185, s[98:99] offset:528
	s_add_u32 s98, s98, 0x10000
	s_addc_u32 s99, s99, 0
	s_waitcnt vmcnt(12)
	v_pk_mul_f32 v[96:97], v[96:97], v[210:211] op_sel_hi:[1,0]
	v_pk_mul_f32 v[98:99], v[98:99], v[210:211] op_sel_hi:[1,0]
	v_pk_mul_f32 v[92:93], v[92:93], v[210:211] op_sel_hi:[1,0]
	v_pk_mul_f32 v[94:95], v[94:95], v[210:211] op_sel_hi:[1,0]
	v_pk_fma_f32 v[96:97], v[76:77], v[96:97], v[148:149]
	v_pk_fma_f32 v[98:99], v[78:79], v[98:99], v[150:151]
	v_pk_fma_f32 v[92:93], v[72:73], v[92:93], v[152:153]
	v_pk_fma_f32 v[94:95], v[74:75], v[94:95], v[154:155]
	v_cvt_pk_bf16_f32 v148, v96, v97
	v_cvt_pk_bf16_f32 v149, v98, v99
	v_cvt_pk_bf16_f32 v150, v92, v93
	v_cvt_pk_bf16_f32 v151, v94, v95
	global_store_dwordx4 v195, v[148:151], s[100:101] sc0 sc1
	v_pk_mul_f32 v[88:89], v[88:89], v[210:211] op_sel_hi:[1,0]
	v_pk_mul_f32 v[90:91], v[90:91], v[210:211] op_sel_hi:[1,0]
	v_pk_mul_f32 v[84:85], v[84:85], v[210:211] op_sel_hi:[1,0]
	v_pk_mul_f32 v[86:87], v[86:87], v[210:211] op_sel_hi:[1,0]
	v_pk_fma_f32 v[88:89], v[68:69], v[88:89], v[180:181]
	v_pk_fma_f32 v[90:91], v[70:71], v[90:91], v[182:183]
	v_pk_fma_f32 v[84:85], v[64:65], v[84:85], v[196:197]
	v_pk_fma_f32 v[86:87], v[66:67], v[86:87], v[198:199]
	v_cvt_pk_bf16_f32 v180, v88, v89
	v_cvt_pk_bf16_f32 v181, v90, v91
	v_cvt_pk_bf16_f32 v182, v84, v85
	v_cvt_pk_bf16_f32 v183, v86, v87
	global_store_dwordx4 v195, v[180:183], s[100:101] offset:256 sc0 sc1
	s_add_u32 s100, s100, 0x28000
	s_addc_u32 s101, s101, 0
	global_load_dwordx4 v[148:151], v185, s[98:99]
	global_load_dwordx4 v[152:155], v185, s[98:99] offset:16
	global_load_dwordx4 v[180:183], v185, s[98:99] offset:512
	global_load_dwordx4 v[196:199], v185, s[98:99] offset:528
	s_add_u32 s98, s98, 0x10000
	s_addc_u32 s99, s99, 0
	s_waitcnt vmcnt(12)
	v_pk_mul_f32 v[60:61], v[60:61], v[232:233] op_sel_hi:[1,0]
	v_pk_mul_f32 v[62:63], v[62:63], v[232:233] op_sel_hi:[1,0]
	v_pk_mul_f32 v[56:57], v[56:57], v[232:233] op_sel_hi:[1,0]
	v_pk_mul_f32 v[58:59], v[58:59], v[232:233] op_sel_hi:[1,0]
	v_pk_fma_f32 v[60:61], v[76:77], v[60:61], v[200:201]
	v_pk_fma_f32 v[62:63], v[78:79], v[62:63], v[202:203]
	v_pk_fma_f32 v[56:57], v[72:73], v[56:57], v[220:221]
	v_pk_fma_f32 v[58:59], v[74:75], v[58:59], v[222:223]
	v_cvt_pk_bf16_f32 v200, v60, v61
	v_cvt_pk_bf16_f32 v201, v62, v63
	v_cvt_pk_bf16_f32 v202, v56, v57
	v_cvt_pk_bf16_f32 v203, v58, v59
	global_store_dwordx4 v195, v[200:203], s[100:101] sc0 sc1
	v_pk_mul_f32 v[52:53], v[52:53], v[232:233] op_sel_hi:[1,0]
	v_pk_mul_f32 v[54:55], v[54:55], v[232:233] op_sel_hi:[1,0]
	v_pk_mul_f32 v[48:49], v[48:49], v[232:233] op_sel_hi:[1,0]
	v_pk_mul_f32 v[50:51], v[50:51], v[232:233] op_sel_hi:[1,0]
	v_pk_fma_f32 v[52:53], v[68:69], v[52:53], v[224:225]
	v_pk_fma_f32 v[54:55], v[70:71], v[54:55], v[226:227]
	v_pk_fma_f32 v[48:49], v[64:65], v[48:49], v[228:229]
	v_pk_fma_f32 v[50:51], v[66:67], v[50:51], v[230:231]
	v_cvt_pk_bf16_f32 v224, v52, v53
	v_cvt_pk_bf16_f32 v225, v54, v55
	v_cvt_pk_bf16_f32 v226, v48, v49
	v_cvt_pk_bf16_f32 v227, v50, v51
	global_store_dwordx4 v195, v[224:227], s[100:101] offset:256 sc0 sc1
	s_add_u32 s100, s100, 0x8000
	s_addc_u32 s101, s101, 0
	global_load_dwordx4 v[200:203], v185, s[98:99]
	global_load_dwordx4 v[220:223], v185, s[98:99] offset:16
	global_load_dwordx4 v[224:227], v185, s[98:99] offset:512
	global_load_dwordx4 v[228:231], v185, s[98:99] offset:528
	s_add_u32 s98, s98, 0x10000
	s_addc_u32 s99, s99, 0
	s_waitcnt vmcnt(12)
; __device__ __forceinline__ unsigned cvt_pk_bf16(float lo, float hi) { f32x2_cv v = {lo, hi}; bf16x2_cv b = __builtin_convertvector(v, bf16x2_cv); return __builtin_bit_cast(unsigned, b); }
;     __device__ __forceinline__ void operator()(const f32x4 (&acc)[2][2][4][2], const Unit& u, int wr, int wc, int fr, int fq) const {
;     ...
;         for (int g = 0; g < 8; ++g) { const int ai = g >> 2, m = g & 3; const size_t off = (size_t)(row0 + ai * HALF + m * 16) * 1024 + col0;
;             if (g + 1 < 8) { const int ai2 = (g + 1) >> 2, m2 = (g + 1) & 3; load_x(xv[(g + 1) & 1], (size_t)(row0 + ai2 * HALF + m2 * 16) * 1024 + col0); }
;             float rs_ = 1.0f; if constexpr (ROWSCALE) rs_ = tab[((u.pm == pm0 ? 0 : 256) + ai * HALF + wr * 64 + m * 16 + fr) * 2 + 1];
; #pragma unroll
;             for (int bj = 0; bj < 2; ++bj) { const f32x4 v0 = xv[g & 1][bj][0] + gv[bj][0] * (acc[ai][bj][m][0] * rs_), v1 = xv[g & 1][bj][1] + gv[bj][1] * (acc[ai][bj][m][1] * rs_);
;                 u32x4 w; w.x = cvt_pk_bf16(v0[0], v0[1]); w.y = cvt_pk_bf16(v0[2], v0[3]); w.z = cvt_pk_bf16(v1[0], v1[1]); w.w = cvt_pk_bf16(v1[2], v1[3]);
;                 *(u32x4*)(out + off + bj * HALF) = w; } }
	v_pk_mul_f32 v[44:45], v[44:45], v[234:235] op_sel_hi:[1,0]
	v_pk_mul_f32 v[46:47], v[46:47], v[234:235] op_sel_hi:[1,0]
	v_pk_mul_f32 v[40:41], v[40:41], v[234:235] op_sel_hi:[1,0]
	v_pk_mul_f32 v[42:43], v[42:43], v[234:235] op_sel_hi:[1,0]
	v_pk_fma_f32 v[44:45], v[76:77], v[44:45], v[236:237]
	v_pk_fma_f32 v[46:47], v[78:79], v[46:47], v[238:239]
	v_pk_fma_f32 v[40:41], v[72:73], v[40:41], v[240:241]
	v_pk_fma_f32 v[42:43], v[74:75], v[42:43], v[242:243]
	v_cvt_pk_bf16_f32 v236, v44, v45
	v_cvt_pk_bf16_f32 v237, v46, v47
	v_cvt_pk_bf16_f32 v238, v40, v41
	v_cvt_pk_bf16_f32 v239, v42, v43
	global_store_dwordx4 v195, v[236:239], s[100:101] sc0 sc1
	v_pk_mul_f32 v[36:37], v[36:37], v[234:235] op_sel_hi:[1,0]
	v_pk_mul_f32 v[38:39], v[38:39], v[234:235] op_sel_hi:[1,0]
	v_pk_mul_f32 v[32:33], v[32:33], v[234:235] op_sel_hi:[1,0]
	v_pk_mul_f32 v[34:35], v[34:35], v[234:235] op_sel_hi:[1,0]
	v_pk_fma_f32 v[36:37], v[68:69], v[36:37], v[244:245]
	v_pk_fma_f32 v[38:39], v[70:71], v[38:39], v[246:247]
	v_pk_fma_f32 v[32:33], v[64:65], v[32:33], v[248:249]
	v_pk_fma_f32 v[34:35], v[66:67], v[34:35], v[250:251]
	v_cvt_pk_bf16_f32 v244, v36, v37
	v_cvt_pk_bf16_f32 v245, v38, v39
	v_cvt_pk_bf16_f32 v246, v32, v33
	v_cvt_pk_bf16_f32 v247, v34, v35
	global_store_dwordx4 v195, v[244:247], s[100:101] offset:256 sc0 sc1
	s_add_u32 s100, s100, 0x8000
	s_addc_u32 s101, s101, 0
	s_waitcnt vmcnt(8)
	v_pk_mul_f32 v[28:29], v[28:29], v[82:83] op_sel_hi:[1,0]
	v_pk_mul_f32 v[30:31], v[30:31], v[82:83] op_sel_hi:[1,0]
	v_pk_mul_f32 v[24:25], v[24:25], v[82:83] op_sel_hi:[1,0]
	v_pk_mul_f32 v[26:27], v[26:27], v[82:83] op_sel_hi:[1,0]
	v_pk_fma_f32 v[28:29], v[76:77], v[28:29], v[148:149]
	v_pk_fma_f32 v[30:31], v[78:79], v[30:31], v[150:151]
	v_pk_fma_f32 v[24:25], v[72:73], v[24:25], v[152:153]
	v_pk_fma_f32 v[26:27], v[74:75], v[26:27], v[154:155]
	v_cvt_pk_bf16_f32 v148, v28, v29
	v_cvt_pk_bf16_f32 v149, v30, v31
	v_cvt_pk_bf16_f32 v150, v24, v25
	v_cvt_pk_bf16_f32 v151, v26, v27
	global_store_dwordx4 v195, v[148:151], s[100:101] sc0 sc1
	v_pk_mul_f32 v[20:21], v[20:21], v[82:83] op_sel_hi:[1,0]
	v_pk_mul_f32 v[22:23], v[22:23], v[82:83] op_sel_hi:[1,0]
	v_pk_mul_f32 v[16:17], v[16:17], v[82:83] op_sel_hi:[1,0]
	v_pk_mul_f32 v[18:19], v[18:19], v[82:83] op_sel_hi:[1,0]
	v_pk_fma_f32 v[20:21], v[68:69], v[20:21], v[180:181]
	v_pk_fma_f32 v[22:23], v[70:71], v[22:23], v[182:183]
	v_pk_fma_f32 v[16:17], v[64:65], v[16:17], v[196:197]
	v_pk_fma_f32 v[18:19], v[66:67], v[18:19], v[198:199]
	v_cvt_pk_bf16_f32 v180, v20, v21
	v_cvt_pk_bf16_f32 v181, v22, v23
	v_cvt_pk_bf16_f32 v182, v16, v17
	v_cvt_pk_bf16_f32 v183, v18, v19
	global_store_dwordx4 v195, v[180:183], s[100:101] offset:256 sc0 sc1
	s_add_u32 s100, s100, 0x8000
	s_addc_u32 s101, s101, 0
	s_waitcnt vmcnt(4)
	v_pk_mul_f32 v[12:13], v[12:13], v[80:81] op_sel_hi:[1,0]
	v_pk_mul_f32 v[14:15], v[14:15], v[80:81] op_sel_hi:[1,0]
	v_pk_mul_f32 v[8:9], v[8:9], v[80:81] op_sel_hi:[1,0]
	v_pk_mul_f32 v[10:11], v[10:11], v[80:81] op_sel_hi:[1,0]
	v_pk_fma_f32 v[12:13], v[76:77], v[12:13], v[200:201]
	v_pk_fma_f32 v[14:15], v[78:79], v[14:15], v[202:203]
	v_pk_fma_f32 v[8:9], v[72:73], v[8:9], v[220:221]
	v_pk_fma_f32 v[10:11], v[74:75], v[10:11], v[222:223]
	v_cvt_pk_bf16_f32 v200, v12, v13
	v_cvt_pk_bf16_f32 v201, v14, v15
	v_cvt_pk_bf16_f32 v202, v8, v9
	v_cvt_pk_bf16_f32 v203, v10, v11
	global_store_dwordx4 v195, v[200:203], s[100:101] sc0 sc1
	v_pk_mul_f32 v[4:5], v[4:5], v[80:81] op_sel_hi:[1,0]
	v_pk_mul_f32 v[6:7], v[6:7], v[80:81] op_sel_hi:[1,0]
	v_pk_mul_f32 v[0:1], v[0:1], v[80:81] op_sel_hi:[1,0]
	v_pk_mul_f32 v[2:3], v[2:3], v[80:81] op_sel_hi:[1,0]
	v_pk_fma_f32 v[4:5], v[68:69], v[4:5], v[224:225]
	v_pk_fma_f32 v[6:7], v[70:71], v[6:7], v[226:227]
	v_pk_fma_f32 v[0:1], v[64:65], v[0:1], v[228:229]
	v_pk_fma_f32 v[2:3], v[66:67], v[2:3], v[230:231]
	v_cvt_pk_bf16_f32 v224, v4, v5
	v_cvt_pk_bf16_f32 v225, v6, v7
	v_cvt_pk_bf16_f32 v226, v0, v1
	v_cvt_pk_bf16_f32 v227, v2, v3
	global_store_dwordx4 v195, v[224:227], s[100:101] offset:256 sc0 sc1
	s_add_u32 s100, s100, 0x8000
	s_addc_u32 s101, s101, 0
	s_mov_b64 s[4:5], -1
	s_cbranch_vccnz .LBB0_432
	s_andn2_b64 vcc, exec, s[40:41]
	s_cbranch_vccnz .LBB0_431
	s_barrier
	s_branch .LBB0_431

; __device__ __forceinline__ void unpack8(const u32x4 w, f32x4& a, f32x4& c) { a = (f32x4){bf_lo(w.x), bf_hi(w.x), bf_lo(w.y), bf_hi(w.y)}; c = (f32x4){bf_lo(w.z), bf_hi(w.z), bf_lo(w.w), bf_hi(w.w)}; }
; template <bool X_F32> __device__ __forceinline__ void phase_norm_mod(const Ctx& C, const void* xin, const float* modl, int shift_idx, int scale_idx) {
;     ...
;         for (int r0_ = (gw % (NGW >> 3)) * NR; r0_ < T / 8; r0_ += (NGW >> 3) * NR) { const int m0 = (gw / (NGW >> 3)) * (T / 8) + r0_;
;             const int b = m0 >> 12;
;             u32x4 raw[NR][2]; float s[NR];
; #pragma unroll
;             for (int r = 0; r < NR; ++r)
; #pragma unroll
;                 for (int j = 0; j < 2; ++j) raw[r][j] = ((const u32x4*)((const bf16*)xin + (size_t)(m0 + r) * DM + 512 * j))[lane];
; #pragma unroll
;             for (int r = 0; r < NR; ++r) { s[r] = 0.f;
; #pragma unroll
;                 for (int j = 0; j < 2; ++j) { f32x4 t0, t1; unpack8(raw[r][j], t0, t1);
;                     s[r] += ((t0.x * t0.x + t0.y * t0.y) + (t0.z * t0.z + t0.w * t0.w)) + ((t1.x * t1.x + t1.y * t1.y) + (t1.z * t1.z + t1.w * t1.w)); } }
.LBB0_499:
	s_add_i32 s12, s20, s50
	s_ashr_i32 s13, s12, 31
	s_lshl_b64 s[48:49], s[12:13], 11
	v_lshl_add_u64 v[4:5], v[16:17], 0, s[48:49]
	global_load_dwordx4 v[0:3], v[4:5], off
	s_nop 0
	global_load_dwordx4 v[4:7], v[4:5], off offset:1024
	s_add_i32 s2, s12, 1
	s_ashr_i32 s3, s2, 31
	s_lshl_b64 s[14:15], s[2:3], 11
	v_lshl_add_u64 v[12:13], v[16:17], 0, s[14:15]
	global_load_dwordx4 v[8:11], v[12:13], off
	s_nop 0
	global_load_dwordx4 v[12:15], v[12:13], off offset:1024
	s_add_i32 s2, s12, 2
	s_ashr_i32 s3, s2, 31
	s_lshl_b64 s[4:5], s[2:3], 11
	v_lshl_add_u64 v[26:27], v[16:17], 0, s[4:5]
	global_load_dwordx4 v[22:25], v[26:27], off
	s_nop 0
	global_load_dwordx4 v[26:29], v[26:27], off offset:1024
	s_add_i32 s2, s12, 3
	s_ashr_i32 s3, s2, 31
	s_lshl_b64 s[46:47], s[2:3], 11
	v_lshl_add_u64 v[34:35], v[16:17], 0, s[46:47]
	global_load_dwordx4 v[30:33], v[34:35], off
	s_nop 0
	global_load_dwordx4 v[34:37], v[34:35], off offset:1024
	s_add_i32 s2, s12, 4
	s_ashr_i32 s3, s2, 31
	s_lshl_b64 s[44:45], s[2:3], 11
	v_lshl_add_u64 v[42:43], v[16:17], 0, s[44:45]
	global_load_dwordx4 v[38:41], v[42:43], off
	s_nop 0
	global_load_dwordx4 v[42:45], v[42:43], off offset:1024
	s_add_i32 s2, s12, 5
	s_ashr_i32 s3, s2, 31
	s_lshl_b64 s[42:43], s[2:3], 11
	v_lshl_add_u64 v[50:51], v[16:17], 0, s[42:43]
	global_load_dwordx4 v[46:49], v[50:51], off
	s_nop 0
	global_load_dwordx4 v[50:53], v[50:51], off offset:1024
	s_add_i32 s2, s12, 6
	s_ashr_i32 s3, s2, 31
	s_lshl_b64 s[40:41], s[2:3], 11
	v_lshl_add_u64 v[54:55], v[16:17], 0, s[40:41]
	global_load_dwordx4 v[120:123], v[54:55], off
	global_load_dwordx4 v[124:127], v[54:55], off offset:1024
	s_add_i32 s2, s12, 7
	s_ashr_i32 s3, s2, 31
	s_lshl_b64 s[38:39], s[2:3], 11
	v_lshl_add_u64 v[54:55], v[16:17], 0, s[38:39]
	global_load_dwordx4 v[128:131], v[54:55], off
	global_load_dwordx4 v[132:135], v[54:55], off offset:1024
	s_ashr_i32 s2, s12, 12
	s_mul_hi_i32 s3, s2, 0x6000
	s_mulk_i32 s2, 0x6000
	s_add_u32 s2, s78, s2
	s_addc_u32 s3, s51, s3
	v_lshl_add_u64 v[198:199], v[20:21], 0, s[48:49]
	s_add_i32 s21, s21, s10
	s_add_i32 s50, s50, s10
	s_waitcnt vmcnt(0)
	v_and_b32_e32 v154, 0xffff0000, v0
	v_and_b32_e32 v155, 0xffff0000, v4
	v_and_b32_e32 v175, 0xffff0000, v5
	v_and_b32_e32 v174, 0xffff0000, v1
	v_lshlrev_b32_e32 v153, 16, v4
	v_lshlrev_b32_e32 v152, 16, v0
	v_lshlrev_b32_e32 v159, 16, v5
	v_lshlrev_b32_e32 v158, 16, v1
	v_lshlrev_b32_e32 v156, 16, v2
	v_and_b32_e32 v160, 0xffff0000, v2
	v_lshlrev_b32_e32 v176, 16, v3
	v_and_b32_e32 v178, 0xffff0000, v3
	v_pk_mul_f32 v[0:1], v[154:155], v[154:155]
	v_pk_mul_f32 v[2:3], v[174:175], v[174:175]
	v_and_b32_e32 v161, 0xffff0000, v6
	v_and_b32_e32 v179, 0xffff0000, v7
	v_pk_fma_f32 v[0:1], v[152:153], v[152:153], v[0:1]
	v_pk_fma_f32 v[2:3], v[158:159], v[158:159], v[2:3]
	v_lshlrev_b32_e32 v157, 16, v6
	v_lshlrev_b32_e32 v177, 16, v7
	v_pk_add_f32 v[0:1], v[0:1], v[2:3]
	v_pk_mul_f32 v[2:3], v[160:161], v[160:161]
	v_pk_mul_f32 v[4:5], v[178:179], v[178:179]
	v_pk_fma_f32 v[2:3], v[156:157], v[156:157], v[2:3]
	v_pk_fma_f32 v[4:5], v[176:177], v[176:177], v[4:5]
	v_and_b32_e32 v139, 0xffff0000, v12
	v_pk_add_f32 v[2:3], v[2:3], v[4:5]
	v_and_b32_e32 v138, 0xffff0000, v8
	v_pk_add_f32 v[0:1], v[0:1], v[2:3]
	v_and_b32_e32 v147, 0xffff0000, v13
	v_and_b32_e32 v146, 0xffff0000, v9
	v_add_f32_e32 v6, v0, v1
	v_lshlrev_b32_e32 v137, 16, v12
	v_lshlrev_b32_e32 v136, 16, v8
	v_lshlrev_b32_e32 v143, 16, v13
	v_lshlrev_b32_e32 v142, 16, v9
	v_pk_mul_f32 v[0:1], v[138:139], v[138:139]
	v_pk_mul_f32 v[2:3], v[146:147], v[146:147]
	v_and_b32_e32 v145, 0xffff0000, v14
	v_and_b32_e32 v144, 0xffff0000, v10
	v_and_b32_e32 v151, 0xffff0000, v15
	v_and_b32_e32 v150, 0xffff0000, v11
	v_pk_fma_f32 v[0:1], v[136:137], v[136:137], v[0:1]
	v_pk_fma_f32 v[2:3], v[142:143], v[142:143], v[2:3]
	v_lshlrev_b32_e32 v141, 16, v14
	v_lshlrev_b32_e32 v140, 16, v10
	v_lshlrev_b32_e32 v149, 16, v15
	v_lshlrev_b32_e32 v148, 16, v11
	v_pk_add_f32 v[0:1], v[0:1], v[2:3]
	v_pk_mul_f32 v[2:3], v[144:145], v[144:145]
	v_pk_mul_f32 v[4:5], v[150:151], v[150:151]
	v_pk_fma_f32 v[2:3], v[140:141], v[140:141], v[2:3]
	v_pk_fma_f32 v[4:5], v[148:149], v[148:149], v[4:5]
	v_and_b32_e32 v107, 0xffff0000, v26
	v_pk_add_f32 v[2:3], v[2:3], v[4:5]
	v_and_b32_e32 v106, 0xffff0000, v22
	v_pk_add_f32 v[0:1], v[0:1], v[2:3]
	v_and_b32_e32 v115, 0xffff0000, v27
	v_and_b32_e32 v114, 0xffff0000, v23
	v_add_f32_e32 v7, v0, v1
	v_lshlrev_b32_e32 v105, 16, v26
	v_lshlrev_b32_e32 v104, 16, v22
	v_lshlrev_b32_e32 v111, 16, v27
	v_lshlrev_b32_e32 v110, 16, v23
	v_pk_mul_f32 v[0:1], v[106:107], v[106:107]
	v_pk_mul_f32 v[2:3], v[114:115], v[114:115]
	v_and_b32_e32 v113, 0xffff0000, v28
	v_and_b32_e32 v112, 0xffff0000, v24
	v_and_b32_e32 v119, 0xffff0000, v29
	v_and_b32_e32 v118, 0xffff0000, v25
	v_pk_fma_f32 v[0:1], v[104:105], v[104:105], v[0:1]
	v_pk_fma_f32 v[2:3], v[110:111], v[110:111], v[2:3]
	v_lshlrev_b32_e32 v109, 16, v28
	v_lshlrev_b32_e32 v108, 16, v24
	v_lshlrev_b32_e32 v117, 16, v29
	v_lshlrev_b32_e32 v116, 16, v25
	v_pk_add_f32 v[0:1], v[0:1], v[2:3]
	v_pk_mul_f32 v[2:3], v[112:113], v[112:113]
	v_pk_mul_f32 v[4:5], v[118:119], v[118:119]
	v_pk_fma_f32 v[2:3], v[108:109], v[108:109], v[2:3]
	v_pk_fma_f32 v[4:5], v[116:117], v[116:117], v[4:5]
	v_and_b32_e32 v91, 0xffff0000, v34
	v_pk_add_f32 v[2:3], v[2:3], v[4:5]
	v_and_b32_e32 v90, 0xffff0000, v30
	v_pk_add_f32 v[0:1], v[0:1], v[2:3]
	v_and_b32_e32 v99, 0xffff0000, v35
	v_and_b32_e32 v98, 0xffff0000, v31
	v_add_f32_e32 v8, v0, v1
	v_lshlrev_b32_e32 v89, 16, v34
	v_lshlrev_b32_e32 v88, 16, v30
	v_lshlrev_b32_e32 v95, 16, v35
	v_lshlrev_b32_e32 v94, 16, v31
; __device__ __forceinline__ void unpack8(const u32x4 w, f32x4& a, f32x4& c) { a = (f32x4){bf_lo(w.x), bf_hi(w.x), bf_lo(w.y), bf_hi(w.y)}; c = (f32x4){bf_lo(w.z), bf_hi(w.z), bf_lo(w.w), bf_hi(w.w)}; }
; template <bool X_F32> __device__ __forceinline__ void phase_norm_mod(const Ctx& C, const void* xin, const float* modl, int shift_idx, int scale_idx) {
;     ...
;             for (int r = 0; r < NR; ++r) { s[r] = 0.f;
; #pragma unroll
;                 for (int j = 0; j < 2; ++j) { f32x4 t0, t1; unpack8(raw[r][j], t0, t1);
;                     s[r] += ((t0.x * t0.x + t0.y * t0.y) + (t0.z * t0.z + t0.w * t0.w)) + ((t1.x * t1.x + t1.y * t1.y) + (t1.z * t1.z + t1.w * t1.w)); } }
;             wave_sumN<NR>(s);
	v_pk_mul_f32 v[0:1], v[90:91], v[90:91]
	v_pk_mul_f32 v[2:3], v[98:99], v[98:99]
	v_and_b32_e32 v97, 0xffff0000, v36
	v_and_b32_e32 v96, 0xffff0000, v32
	v_and_b32_e32 v103, 0xffff0000, v37
	v_and_b32_e32 v102, 0xffff0000, v33
	v_pk_fma_f32 v[0:1], v[88:89], v[88:89], v[0:1]
	v_pk_fma_f32 v[2:3], v[94:95], v[94:95], v[2:3]
	v_lshlrev_b32_e32 v93, 16, v36
	v_lshlrev_b32_e32 v92, 16, v32
	v_lshlrev_b32_e32 v101, 16, v37
	v_lshlrev_b32_e32 v100, 16, v33
	v_pk_add_f32 v[0:1], v[0:1], v[2:3]
	v_pk_mul_f32 v[2:3], v[96:97], v[96:97]
	v_pk_mul_f32 v[4:5], v[102:103], v[102:103]
	v_pk_fma_f32 v[2:3], v[92:93], v[92:93], v[2:3]
	v_pk_fma_f32 v[4:5], v[100:101], v[100:101], v[4:5]
	v_and_b32_e32 v73, 0xffff0000, v42
	v_pk_add_f32 v[2:3], v[2:3], v[4:5]
	v_and_b32_e32 v72, 0xffff0000, v38
	v_pk_add_f32 v[0:1], v[0:1], v[2:3]
	v_and_b32_e32 v83, 0xffff0000, v43
	v_and_b32_e32 v82, 0xffff0000, v39
	v_add_f32_e32 v9, v0, v1
	v_lshlrev_b32_e32 v71, 16, v42
	v_lshlrev_b32_e32 v70, 16, v38
	v_lshlrev_b32_e32 v77, 16, v43
	v_lshlrev_b32_e32 v76, 16, v39
	v_pk_mul_f32 v[0:1], v[72:73], v[72:73]
	v_pk_mul_f32 v[2:3], v[82:83], v[82:83]
	v_and_b32_e32 v79, 0xffff0000, v44
	v_and_b32_e32 v78, 0xffff0000, v40
	v_and_b32_e32 v87, 0xffff0000, v45
	v_and_b32_e32 v86, 0xffff0000, v41
	v_pk_fma_f32 v[0:1], v[70:71], v[70:71], v[0:1]
	v_pk_fma_f32 v[2:3], v[76:77], v[76:77], v[2:3]
	v_lshlrev_b32_e32 v75, 16, v44
	v_lshlrev_b32_e32 v74, 16, v40
	v_lshlrev_b32_e32 v85, 16, v45
	v_lshlrev_b32_e32 v84, 16, v41
	v_pk_add_f32 v[0:1], v[0:1], v[2:3]
	v_pk_mul_f32 v[2:3], v[78:79], v[78:79]
	v_pk_mul_f32 v[4:5], v[86:87], v[86:87]
	v_pk_fma_f32 v[2:3], v[74:75], v[74:75], v[2:3]
	v_pk_fma_f32 v[4:5], v[84:85], v[84:85], v[4:5]
	v_and_b32_e32 v57, 0xffff0000, v50
	v_pk_add_f32 v[2:3], v[2:3], v[4:5]
	v_and_b32_e32 v56, 0xffff0000, v46
	v_pk_add_f32 v[0:1], v[0:1], v[2:3]
	v_and_b32_e32 v65, 0xffff0000, v51
	v_and_b32_e32 v64, 0xffff0000, v47
	v_add_f32_e32 v10, v0, v1
	v_lshlrev_b32_e32 v55, 16, v50
	v_lshlrev_b32_e32 v54, 16, v46
	v_lshlrev_b32_e32 v61, 16, v51
	v_lshlrev_b32_e32 v60, 16, v47
	v_pk_mul_f32 v[0:1], v[56:57], v[56:57]
	v_pk_mul_f32 v[2:3], v[64:65], v[64:65]
	v_and_b32_e32 v63, 0xffff0000, v52
	v_and_b32_e32 v62, 0xffff0000, v48
	v_and_b32_e32 v69, 0xffff0000, v53
	v_and_b32_e32 v68, 0xffff0000, v49
	v_pk_fma_f32 v[0:1], v[54:55], v[54:55], v[0:1]
	v_pk_fma_f32 v[2:3], v[60:61], v[60:61], v[2:3]
	v_lshlrev_b32_e32 v59, 16, v52
	v_lshlrev_b32_e32 v58, 16, v48
	v_lshlrev_b32_e32 v67, 16, v53
	v_lshlrev_b32_e32 v66, 16, v49
	v_pk_add_f32 v[0:1], v[0:1], v[2:3]
	v_pk_mul_f32 v[2:3], v[62:63], v[62:63]
	v_pk_mul_f32 v[4:5], v[68:69], v[68:69]
	v_pk_fma_f32 v[2:3], v[58:59], v[58:59], v[2:3]
	v_pk_fma_f32 v[4:5], v[66:67], v[66:67], v[4:5]
	v_and_b32_e32 v41, 0xffff0000, v124
	v_pk_add_f32 v[2:3], v[2:3], v[4:5]
	v_and_b32_e32 v40, 0xffff0000, v120
	v_pk_add_f32 v[0:1], v[0:1], v[2:3]
	v_and_b32_e32 v49, 0xffff0000, v125
	v_and_b32_e32 v48, 0xffff0000, v121
	v_add_f32_e32 v11, v0, v1
	v_lshlrev_b32_e32 v39, 16, v124
	v_lshlrev_b32_e32 v38, 16, v120
	v_lshlrev_b32_e32 v45, 16, v125
	v_lshlrev_b32_e32 v44, 16, v121
	v_pk_mul_f32 v[0:1], v[40:41], v[40:41]
	v_pk_mul_f32 v[2:3], v[48:49], v[48:49]
	v_and_b32_e32 v47, 0xffff0000, v126
	v_and_b32_e32 v46, 0xffff0000, v122
	v_and_b32_e32 v53, 0xffff0000, v127
	v_and_b32_e32 v52, 0xffff0000, v123
	v_pk_fma_f32 v[0:1], v[38:39], v[38:39], v[0:1]
	v_pk_fma_f32 v[2:3], v[44:45], v[44:45], v[2:3]
	v_lshlrev_b32_e32 v43, 16, v126
	v_lshlrev_b32_e32 v42, 16, v122
	v_lshlrev_b32_e32 v51, 16, v127
	v_lshlrev_b32_e32 v50, 16, v123
	v_pk_add_f32 v[0:1], v[0:1], v[2:3]
	v_pk_mul_f32 v[2:3], v[46:47], v[46:47]
	v_pk_mul_f32 v[4:5], v[52:53], v[52:53]
	v_pk_fma_f32 v[2:3], v[42:43], v[42:43], v[2:3]
	v_pk_fma_f32 v[4:5], v[50:51], v[50:51], v[4:5]
	v_and_b32_e32 v25, 0xffff0000, v132
	v_pk_add_f32 v[2:3], v[2:3], v[4:5]
	v_and_b32_e32 v24, 0xffff0000, v128
	v_pk_add_f32 v[0:1], v[0:1], v[2:3]
	v_and_b32_e32 v33, 0xffff0000, v133
	v_and_b32_e32 v32, 0xffff0000, v129
	v_add_f32_e32 v12, v0, v1
	v_lshlrev_b32_e32 v23, 16, v132
	v_lshlrev_b32_e32 v22, 16, v128
	v_lshlrev_b32_e32 v29, 16, v133
	v_lshlrev_b32_e32 v28, 16, v129
	v_pk_mul_f32 v[0:1], v[24:25], v[24:25]
	v_pk_mul_f32 v[2:3], v[32:33], v[32:33]
	v_and_b32_e32 v31, 0xffff0000, v134
	v_and_b32_e32 v30, 0xffff0000, v130
	v_and_b32_e32 v37, 0xffff0000, v135
	v_and_b32_e32 v36, 0xffff0000, v131
	v_pk_fma_f32 v[0:1], v[22:23], v[22:23], v[0:1]
	v_pk_fma_f32 v[2:3], v[28:29], v[28:29], v[2:3]
	v_lshlrev_b32_e32 v27, 16, v134
	v_lshlrev_b32_e32 v26, 16, v130
	v_lshlrev_b32_e32 v35, 16, v135
	v_lshlrev_b32_e32 v34, 16, v131
	v_pk_add_f32 v[0:1], v[0:1], v[2:3]
	v_pk_mul_f32 v[2:3], v[30:31], v[30:31]
	v_pk_mul_f32 v[4:5], v[36:37], v[36:37]
	v_pk_fma_f32 v[2:3], v[26:27], v[26:27], v[2:3]
	v_pk_fma_f32 v[4:5], v[34:35], v[34:35], v[4:5]
	ds_bpermute_b32 v13, v180, v11
	v_pk_add_f32 v[2:3], v[2:3], v[4:5]
	ds_bpermute_b32 v4, v180, v9
	v_pk_add_f32 v[0:1], v[0:1], v[2:3]
	ds_bpermute_b32 v3, v180, v8
	v_add_f32_e32 v0, v0, v1
	ds_bpermute_b32 v1, v180, v6
	ds_bpermute_b32 v15, v180, v0
	ds_bpermute_b32 v2, v180, v7
	ds_bpermute_b32 v5, v180, v10
	ds_bpermute_b32 v14, v180, v12
	s_waitcnt lgkmcnt(0)
	v_add_f32_e32 v1, v6, v1
	s_waitcnt lgkmcnt(3)
	v_add_f32_e32 v0, v0, v15
	v_add_f32_e32 v3, v8, v3
	ds_bpermute_b32 v8, v181, v1
	ds_bpermute_b32 v15, v181, v0
	s_waitcnt lgkmcnt(4)
	v_add_f32_e32 v2, v7, v2
	v_add_f32_e32 v4, v9, v4
	s_waitcnt lgkmcnt(3)
	v_add_f32_e32 v5, v10, v5
	v_add_f32_e32 v6, v11, v13
	s_waitcnt lgkmcnt(2)
; template <bool X_F32> __device__ __forceinline__ void phase_norm_mod(const Ctx& C, const void* xin, const float* modl, int shift_idx, int scale_idx) {
;     ...
;             wave_sumN<NR>(s);
;             f32x4 a[4], g[4];
; #pragma unroll
;             for (int j = 0; j < 2; ++j)
; #pragma unroll
;                 for (int q = 0; q < 2; ++q) { a[2 * j + q] = *(const f32x4*)(modl + (size_t)b * NMOD + shift_idx * DM + 512 * j + 8 * lane + 4 * q);
;                     g[2 * j + q] = *(const f32x4*)(modl + (size_t)b * NMOD + scale_idx * DM + 512 * j + 8 * lane + 4 * q) + 1.0f; }
	v_add_f32_e32 v7, v12, v14
	ds_bpermute_b32 v9, v181, v2
	ds_bpermute_b32 v10, v181, v3
	ds_bpermute_b32 v11, v181, v4
	ds_bpermute_b32 v12, v181, v5
	ds_bpermute_b32 v13, v181, v6
	ds_bpermute_b32 v14, v181, v7
	s_waitcnt lgkmcnt(7)
	v_add_f32_e32 v1, v1, v8
	s_waitcnt lgkmcnt(6)
	v_add_f32_e32 v0, v0, v15
	ds_bpermute_b32 v8, v182, v1
	ds_bpermute_b32 v15, v182, v0
	s_waitcnt lgkmcnt(7)
	v_add_f32_e32 v2, v2, v9
	s_waitcnt lgkmcnt(6)
	v_add_f32_e32 v3, v3, v10
	s_waitcnt lgkmcnt(5)
	v_add_f32_e32 v4, v4, v11
	s_waitcnt lgkmcnt(4)
	v_add_f32_e32 v5, v5, v12
	s_waitcnt lgkmcnt(3)
	v_add_f32_e32 v6, v6, v13
	s_waitcnt lgkmcnt(2)
	v_add_f32_e32 v7, v7, v14
	ds_bpermute_b32 v9, v182, v2
	ds_bpermute_b32 v10, v182, v3
	ds_bpermute_b32 v11, v182, v4
	ds_bpermute_b32 v12, v182, v5
	ds_bpermute_b32 v13, v182, v6
	ds_bpermute_b32 v14, v182, v7
	s_waitcnt lgkmcnt(7)
	v_add_f32_e32 v1, v1, v8
	s_waitcnt lgkmcnt(6)
	v_add_f32_e32 v0, v0, v15
	ds_bpermute_b32 v8, v183, v1
	ds_bpermute_b32 v15, v183, v0
	s_waitcnt lgkmcnt(7)
	v_add_f32_e32 v2, v2, v9
	s_waitcnt lgkmcnt(6)
	v_add_f32_e32 v3, v3, v10
	s_waitcnt lgkmcnt(5)
	v_add_f32_e32 v4, v4, v11
	s_waitcnt lgkmcnt(4)
	v_add_f32_e32 v5, v5, v12
	s_waitcnt lgkmcnt(3)
	v_add_f32_e32 v6, v6, v13
	s_waitcnt lgkmcnt(2)
	v_add_f32_e32 v7, v7, v14
	ds_bpermute_b32 v9, v183, v2
	ds_bpermute_b32 v10, v183, v3
	ds_bpermute_b32 v11, v183, v4
	ds_bpermute_b32 v12, v183, v5
	ds_bpermute_b32 v13, v183, v6
	ds_bpermute_b32 v14, v183, v7
	s_waitcnt lgkmcnt(7)
	v_add_f32_e32 v1, v1, v8
	s_waitcnt lgkmcnt(6)
	v_add_f32_e32 v0, v0, v15
	ds_bpermute_b32 v8, v184, v1
	ds_bpermute_b32 v15, v184, v0
	s_waitcnt lgkmcnt(7)
	v_add_f32_e32 v2, v2, v9
	s_waitcnt lgkmcnt(6)
	v_add_f32_e32 v3, v3, v10
	s_waitcnt lgkmcnt(5)
	v_add_f32_e32 v4, v4, v11
	s_waitcnt lgkmcnt(4)
	v_add_f32_e32 v5, v5, v12
	s_waitcnt lgkmcnt(3)
	v_add_f32_e32 v6, v6, v13
	s_waitcnt lgkmcnt(2)
	v_add_f32_e32 v7, v7, v14
	ds_bpermute_b32 v9, v184, v2
	ds_bpermute_b32 v10, v184, v3
	ds_bpermute_b32 v11, v184, v4
	ds_bpermute_b32 v12, v184, v5
	ds_bpermute_b32 v13, v184, v6
	ds_bpermute_b32 v14, v184, v7
	s_waitcnt lgkmcnt(7)
	v_add_f32_e32 v1, v1, v8
	s_waitcnt lgkmcnt(6)
	v_add_f32_e32 v0, v0, v15
	ds_bpermute_b32 v8, v185, v1
	ds_bpermute_b32 v15, v185, v0
	s_waitcnt lgkmcnt(7)
	v_add_f32_e32 v2, v2, v9
	s_waitcnt lgkmcnt(6)
	v_add_f32_e32 v3, v3, v10
	s_waitcnt lgkmcnt(5)
	v_add_f32_e32 v4, v4, v11
	s_waitcnt lgkmcnt(4)
	v_add_f32_e32 v5, v5, v12
	s_waitcnt lgkmcnt(3)
	v_add_f32_e32 v6, v6, v13
	s_waitcnt lgkmcnt(2)
	v_add_f32_e32 v7, v7, v14
	ds_bpermute_b32 v9, v185, v2
	ds_bpermute_b32 v10, v185, v3
	ds_bpermute_b32 v11, v185, v4
	ds_bpermute_b32 v12, v185, v5
	ds_bpermute_b32 v13, v185, v6
	ds_bpermute_b32 v14, v185, v7
	s_waitcnt lgkmcnt(7)
	v_add_f32_e32 v80, v1, v8
	s_waitcnt lgkmcnt(6)
	v_add_f32_e32 v186, v0, v15
	v_lshl_add_u64 v[0:1], v[18:19], 2, s[2:3]
	s_mov_b64 s[2:3], 0x3000
	v_lshl_add_u64 v[120:121], v[0:1], 0, s[2:3]
	s_mov_b64 s[2:3], 0x4000
	v_lshl_add_u64 v[122:123], v[0:1], 0, s[2:3]
	s_movk_i32 s2, 0x4000
	v_add_co_u32_e32 v0, vcc, s2, v0
	s_waitcnt lgkmcnt(5)
	v_add_f32_e32 v192, v2, v9
	v_addc_co_u32_e32 v1, vcc, 0, v1, vcc
	s_waitcnt lgkmcnt(4)
	v_add_f32_e32 v191, v3, v10
	s_waitcnt lgkmcnt(3)
	v_add_f32_e32 v190, v4, v11
	s_waitcnt lgkmcnt(2)
	v_add_f32_e32 v189, v5, v12
	s_waitcnt lgkmcnt(1)
	v_add_f32_e32 v188, v6, v13
	s_waitcnt lgkmcnt(0)
	v_add_f32_e32 v187, v7, v14
	global_load_dwordx4 v[12:15], v[0:1], off offset:-4096
	global_load_dwordx4 v[8:11], v[120:121], off offset:16
	s_nop 0
	global_load_dwordx4 v[0:3], v[0:1], off
	s_nop 0
	global_load_dwordx4 v[4:7], v[122:123], off offset:16
	v_fmamk_f32 v80, v80, 0x3a800000, v214
	v_cmp_gt_f32_e32 vcc, s19, v80
	v_mul_f32_e32 v193, 0x4f800000, v80
	v_mov_b32_e32 v201, v160
	v_cndmask_b32_e32 v80, v80, v193, vcc
	v_sqrt_f32_e32 v193, v80
	v_mov_b32_e32 v203, v178
	v_mov_b32_e32 v160, v157
	v_mov_b32_e32 v178, v177
	v_mov_b32_e32 v200, v156
	v_mov_b32_e32 v202, v176
	s_waitcnt vmcnt(1)
	v_pk_add_f32 v[132:133], v[2:3], 1.0 op_sel_hi:[1,0]
	v_pk_add_f32 v[134:135], v[0:1], 1.0 op_sel_hi:[1,0]
	s_waitcnt vmcnt(0)
	v_pk_add_f32 v[128:129], v[6:7], 1.0 op_sel_hi:[1,0]
	v_pk_add_f32 v[130:131], v[4:5], 1.0 op_sel_hi:[1,0]
	global_load_dwordx4 v[0:3], v[120:121], off offset:2064
	global_load_dwordx4 v[4:7], v[120:121], off offset:2048
	global_load_dwordx4 v[194:197], v[122:123], off offset:2064
	s_nop 0
	global_load_dwordx4 v[120:123], v[122:123], off offset:2048
	s_waitcnt vmcnt(0)
; __device__ __forceinline__ unsigned pk2(float lo, float hi) { return pg8::cvt_pk_bf16(lo, hi); }
; __device__ __forceinline__ void unpack8(const u32x4 w, f32x4& a, f32x4& c) { a = (f32x4){bf_lo(w.x), bf_hi(w.x), bf_lo(w.y), bf_hi(w.y)}; c = (f32x4){bf_lo(w.z), bf_hi(w.z), bf_lo(w.w), bf_hi(w.w)}; }
; template <bool X_F32> __device__ __forceinline__ void phase_norm_mod(const Ctx& C, const void* xin, const float* modl, int shift_idx, int scale_idx) {
;     ...
; #pragma unroll
;             for (int r = 0; r < NR; ++r) { const float rs = 1.0f / sqrtf(s[r] * (1.f / DM) + EPS);
; #pragma unroll
;                 for (int j = 0; j < 2; ++j) { f32x4 t0, t1; unpack8(raw[r][j], t0, t1);
;                     const f32x4 y0 = t0 * rs * g[2 * j] + a[2 * j], y1 = t1 * rs * g[2 * j + 1] + a[2 * j + 1];
;                     u32x4 w; w.x = pk2(y0.x, y0.y); w.y = pk2(y0.z, y0.w); w.z = pk2(y1.x, y1.y); w.w = pk2(y1.z, y1.w);
;                     ((u32x4*)(H + (size_t)(m0 + r) * DM + 512 * j))[lane] = w; } }
	v_pk_add_f32 v[124:125], v[122:123], 1.0 op_sel_hi:[1,0]
	v_pk_add_f32 v[122:123], v[194:195], 1.0 op_sel_hi:[1,0]
	v_add_u32_e32 v194, -1, v193
	v_fma_f32 v195, -v194, v193, v80
	v_cmp_ge_f32_e64 s[36:37], 0, v195
	v_add_u32_e32 v195, 1, v193
	v_pk_add_f32 v[126:127], v[120:121], 1.0 op_sel_hi:[1,0]
	v_cndmask_b32_e64 v194, v193, v194, s[36:37]
	v_fma_f32 v193, -v195, v193, v80
	v_cmp_lt_f32_e64 s[36:37], 0, v193
	v_pk_add_f32 v[120:121], v[196:197], 1.0 op_sel_hi:[1,0]
	s_nop 0
	v_cndmask_b32_e64 v193, v194, v195, s[36:37]
	v_mul_f32_e32 v194, 0x37800000, v193
	v_cndmask_b32_e32 v193, v193, v194, vcc
	v_cmp_class_f32_e32 vcc, v80, v215
	s_nop 1
	v_cndmask_b32_e32 v80, v193, v80, vcc
	v_div_scale_f32 v193, s[2:3], v80, v80, 1.0
	v_rcp_f32_e32 v194, v193
	s_nop 0
	v_fma_f32 v195, -v193, v194, 1.0
	v_fmac_f32_e32 v194, v195, v194
	v_div_scale_f32 v195, vcc, 1.0, v80, 1.0
	v_mul_f32_e32 v196, v195, v194
	v_fma_f32 v197, -v193, v196, v195
	v_fmac_f32_e32 v196, v197, v194
	v_fma_f32 v193, -v193, v196, v195
	v_div_fmas_f32 v193, v193, v194, v196
	v_div_fixup_f32 v80, v193, v80, 1.0
	v_mov_b32_e32 v195, v154
	v_mov_b32_e32 v197, v174
	v_mov_b32_e32 v154, v153
	v_mov_b32_e32 v174, v159
	v_mov_b32_e32 v194, v152
	v_mov_b32_e32 v196, v158
	v_pk_mul_f32 v[152:153], v[80:81], v[154:155] op_sel_hi:[0,1]
	v_pk_mul_f32 v[154:155], v[80:81], v[174:175] op_sel_hi:[0,1]
	v_pk_mul_f32 v[156:157], v[80:81], v[160:161] op_sel_hi:[0,1]
	v_pk_mul_f32 v[158:159], v[80:81], v[178:179] op_sel_hi:[0,1]
	v_pk_fma_f32 v[154:155], v[154:155], v[124:125], v[6:7]
	v_pk_fma_f32 v[152:153], v[152:153], v[126:127], v[4:5]
	v_pk_fma_f32 v[158:159], v[158:159], v[120:121], v[2:3]
	v_pk_fma_f32 v[156:157], v[156:157], v[122:123], v[0:1]
	v_pk_mul_f32 v[194:195], v[80:81], v[194:195] op_sel_hi:[0,1]
	v_pk_mul_f32 v[196:197], v[80:81], v[196:197] op_sel_hi:[0,1]
	v_pk_mul_f32 v[200:201], v[80:81], v[200:201] op_sel_hi:[0,1]
	v_pk_mul_f32 v[202:203], v[80:81], v[202:203] op_sel_hi:[0,1]
	v_cvt_pk_bf16_f32 v152, v152, v153
	v_cvt_pk_bf16_f32 v153, v154, v155
	v_cvt_pk_bf16_f32 v154, v156, v157
	v_cvt_pk_bf16_f32 v155, v158, v159
	v_fmamk_f32 v80, v192, 0x3a800000, v214
	flat_store_dwordx4 v[198:199], v[152:155] offset:1024 sc0 sc1
	v_cmp_gt_f32_e32 vcc, s19, v80
	v_mov_b32_e32 v159, v144
	v_mul_f32_e32 v152, 0x4f800000, v80
	v_cndmask_b32_e32 v80, v80, v152, vcc
	v_sqrt_f32_e32 v152, v80
	v_mov_b32_e32 v161, v150
	v_mov_b32_e32 v144, v141
	v_mov_b32_e32 v150, v149
	v_add_u32_e32 v153, -1, v152
	v_fma_f32 v154, -v153, v152, v80
	v_cmp_ge_f32_e64 s[36:37], 0, v154
	v_add_u32_e32 v154, 1, v152
	v_mov_b32_e32 v158, v140
	v_cndmask_b32_e64 v153, v152, v153, s[36:37]
	v_fma_f32 v152, -v154, v152, v80
	v_cmp_lt_f32_e64 s[36:37], 0, v152
	v_mov_b32_e32 v160, v148
	v_pk_fma_f32 v[196:197], v[196:197], v[132:133], v[14:15]
	v_cndmask_b32_e64 v152, v153, v154, s[36:37]
	v_mul_f32_e32 v153, 0x37800000, v152
	v_cndmask_b32_e32 v152, v152, v153, vcc
	v_cmp_class_f32_e32 vcc, v80, v215
	v_pk_fma_f32 v[194:195], v[194:195], v[134:135], v[12:13]
	v_pk_fma_f32 v[202:203], v[202:203], v[128:129], v[10:11]
	v_cndmask_b32_e32 v80, v152, v80, vcc
	v_div_scale_f32 v152, s[2:3], v80, v80, 1.0
	v_rcp_f32_e32 v153, v152
	v_pk_fma_f32 v[200:201], v[200:201], v[130:131], v[8:9]
	v_cvt_pk_bf16_f32 v194, v194, v195
	v_cvt_pk_bf16_f32 v195, v196, v197
	v_fma_f32 v154, -v152, v153, 1.0
	v_fmac_f32_e32 v153, v154, v153
	v_div_scale_f32 v154, vcc, 1.0, v80, 1.0
	v_mul_f32_e32 v155, v154, v153
	v_fma_f32 v156, -v152, v155, v154
	v_fmac_f32_e32 v155, v156, v153
	v_fma_f32 v152, -v152, v155, v154
	v_div_fmas_f32 v152, v152, v153, v155
	v_div_fixup_f32 v80, v152, v80, 1.0
	v_mov_b32_e32 v153, v138
	v_mov_b32_e32 v155, v146
	v_mov_b32_e32 v138, v137
	v_mov_b32_e32 v146, v143
	v_mov_b32_e32 v152, v136
	v_mov_b32_e32 v154, v142
	v_pk_mul_f32 v[136:137], v[80:81], v[138:139] op_sel_hi:[0,1]
	v_pk_mul_f32 v[138:139], v[80:81], v[146:147] op_sel_hi:[0,1]
	v_pk_mul_f32 v[140:141], v[80:81], v[144:145] op_sel_hi:[0,1]
	v_pk_mul_f32 v[142:143], v[80:81], v[150:151] op_sel_hi:[0,1]
	v_pk_fma_f32 v[138:139], v[138:139], v[124:125], v[6:7]
	v_pk_fma_f32 v[136:137], v[136:137], v[126:127], v[4:5]
	v_pk_fma_f32 v[142:143], v[142:143], v[120:121], v[2:3]
	v_pk_fma_f32 v[140:141], v[140:141], v[122:123], v[0:1]
	v_lshl_add_u64 v[156:157], v[20:21], 0, s[14:15]
	v_pk_mul_f32 v[152:153], v[80:81], v[152:153] op_sel_hi:[0,1]
	v_pk_mul_f32 v[154:155], v[80:81], v[154:155] op_sel_hi:[0,1]
	v_pk_mul_f32 v[158:159], v[80:81], v[158:159] op_sel_hi:[0,1]
	v_pk_mul_f32 v[160:161], v[80:81], v[160:161] op_sel_hi:[0,1]
	v_cvt_pk_bf16_f32 v136, v136, v137
	v_cvt_pk_bf16_f32 v137, v138, v139
	v_cvt_pk_bf16_f32 v138, v140, v141
	v_cvt_pk_bf16_f32 v139, v142, v143
	v_fmamk_f32 v80, v191, 0x3a800000, v214
	flat_store_dwordx4 v[156:157], v[136:139] offset:1024 sc0 sc1
	v_cmp_gt_f32_e32 vcc, s19, v80
	v_mov_b32_e32 v143, v112
	v_mul_f32_e32 v136, 0x4f800000, v80
	v_cndmask_b32_e32 v80, v80, v136, vcc
	v_sqrt_f32_e32 v136, v80
	v_mov_b32_e32 v145, v118
	v_mov_b32_e32 v112, v109
	v_mov_b32_e32 v118, v117
	v_add_u32_e32 v137, -1, v136
	v_fma_f32 v138, -v137, v136, v80
	v_cmp_ge_f32_e64 s[36:37], 0, v138
	v_add_u32_e32 v138, 1, v136
	v_mov_b32_e32 v142, v108
	v_cndmask_b32_e64 v137, v136, v137, s[36:37]
	v_fma_f32 v136, -v138, v136, v80
	v_cmp_lt_f32_e64 s[36:37], 0, v136
	v_mov_b32_e32 v144, v116
	v_pk_fma_f32 v[154:155], v[132:133], v[154:155], v[14:15]
	v_cndmask_b32_e64 v136, v137, v138, s[36:37]
	v_mul_f32_e32 v137, 0x37800000, v136
	v_cndmask_b32_e32 v136, v136, v137, vcc
	v_cmp_class_f32_e32 vcc, v80, v215
	v_pk_fma_f32 v[152:153], v[134:135], v[152:153], v[12:13]
; __device__ __forceinline__ unsigned pk2(float lo, float hi) { return pg8::cvt_pk_bf16(lo, hi); }
; __device__ __forceinline__ void unpack8(const u32x4 w, f32x4& a, f32x4& c) { a = (f32x4){bf_lo(w.x), bf_hi(w.x), bf_lo(w.y), bf_hi(w.y)}; c = (f32x4){bf_lo(w.z), bf_hi(w.z), bf_lo(w.w), bf_hi(w.w)}; }
; template <bool X_F32> __device__ __forceinline__ void phase_norm_mod(const Ctx& C, const void* xin, const float* modl, int shift_idx, int scale_idx) {
;     ...
; #pragma unroll
;             for (int r = 0; r < NR; ++r) { const float rs = 1.0f / sqrtf(s[r] * (1.f / DM) + EPS);
; #pragma unroll
;                 for (int j = 0; j < 2; ++j) { f32x4 t0, t1; unpack8(raw[r][j], t0, t1);
;                     const f32x4 y0 = t0 * rs * g[2 * j] + a[2 * j], y1 = t1 * rs * g[2 * j + 1] + a[2 * j + 1];
;                     u32x4 w; w.x = pk2(y0.x, y0.y); w.y = pk2(y0.z, y0.w); w.z = pk2(y1.x, y1.y); w.w = pk2(y1.z, y1.w);
;                     ((u32x4*)(H + (size_t)(m0 + r) * DM + 512 * j))[lane] = w; } }
	v_pk_fma_f32 v[160:161], v[160:161], v[128:129], v[10:11]
	v_cndmask_b32_e32 v80, v136, v80, vcc
	v_div_scale_f32 v136, s[2:3], v80, v80, 1.0
	v_rcp_f32_e32 v137, v136
	v_pk_fma_f32 v[158:159], v[158:159], v[130:131], v[8:9]
	v_cvt_pk_bf16_f32 v196, v200, v201
	v_cvt_pk_bf16_f32 v197, v202, v203
	v_fma_f32 v138, -v136, v137, 1.0
	v_fmac_f32_e32 v137, v138, v137
	v_div_scale_f32 v138, vcc, 1.0, v80, 1.0
	v_mul_f32_e32 v139, v138, v137
	v_fma_f32 v140, -v136, v139, v138
	v_fmac_f32_e32 v139, v140, v137
	v_fma_f32 v136, -v136, v139, v138
	v_div_fmas_f32 v136, v136, v137, v139
	v_div_fixup_f32 v80, v136, v80, 1.0
	v_mov_b32_e32 v137, v106
	v_mov_b32_e32 v139, v114
	v_mov_b32_e32 v106, v105
	v_mov_b32_e32 v114, v111
	v_mov_b32_e32 v136, v104
	v_mov_b32_e32 v138, v110
	v_pk_mul_f32 v[104:105], v[80:81], v[106:107] op_sel_hi:[0,1]
	v_pk_mul_f32 v[106:107], v[80:81], v[114:115] op_sel_hi:[0,1]
	v_pk_mul_f32 v[108:109], v[80:81], v[112:113] op_sel_hi:[0,1]
	v_pk_mul_f32 v[110:111], v[80:81], v[118:119] op_sel_hi:[0,1]
	v_pk_fma_f32 v[106:107], v[106:107], v[124:125], v[6:7]
	v_pk_fma_f32 v[104:105], v[104:105], v[126:127], v[4:5]
	v_pk_fma_f32 v[110:111], v[110:111], v[120:121], v[2:3]
	v_pk_fma_f32 v[108:109], v[108:109], v[122:123], v[0:1]
	v_lshl_add_u64 v[140:141], v[20:21], 0, s[4:5]
	v_pk_mul_f32 v[136:137], v[80:81], v[136:137] op_sel_hi:[0,1]
	v_pk_mul_f32 v[138:139], v[80:81], v[138:139] op_sel_hi:[0,1]
	v_pk_mul_f32 v[142:143], v[80:81], v[142:143] op_sel_hi:[0,1]
	v_pk_mul_f32 v[144:145], v[80:81], v[144:145] op_sel_hi:[0,1]
	v_cvt_pk_bf16_f32 v104, v104, v105
	v_cvt_pk_bf16_f32 v105, v106, v107
	v_cvt_pk_bf16_f32 v106, v108, v109
	v_cvt_pk_bf16_f32 v107, v110, v111
	v_fmamk_f32 v80, v190, 0x3a800000, v214
	flat_store_dwordx4 v[140:141], v[104:107] offset:1024 sc0 sc1
	v_cmp_gt_f32_e32 vcc, s19, v80
	v_mov_b32_e32 v111, v96
	v_mul_f32_e32 v104, 0x4f800000, v80
	v_cndmask_b32_e32 v80, v80, v104, vcc
	v_sqrt_f32_e32 v104, v80
	v_mov_b32_e32 v113, v102
	v_mov_b32_e32 v96, v93
	v_mov_b32_e32 v102, v101
	v_add_u32_e32 v105, -1, v104
	v_fma_f32 v106, -v105, v104, v80
	v_cmp_ge_f32_e64 s[36:37], 0, v106
	v_add_u32_e32 v106, 1, v104
	v_mov_b32_e32 v110, v92
	v_cndmask_b32_e64 v105, v104, v105, s[36:37]
	v_fma_f32 v104, -v106, v104, v80
	v_cmp_lt_f32_e64 s[36:37], 0, v104
	v_mov_b32_e32 v112, v100
	v_pk_fma_f32 v[138:139], v[132:133], v[138:139], v[14:15]
	v_cndmask_b32_e64 v104, v105, v106, s[36:37]
	v_mul_f32_e32 v105, 0x37800000, v104
	v_cndmask_b32_e32 v104, v104, v105, vcc
	v_cmp_class_f32_e32 vcc, v80, v215
	v_pk_fma_f32 v[136:137], v[134:135], v[136:137], v[12:13]
	v_pk_fma_f32 v[144:145], v[144:145], v[128:129], v[10:11]
	v_cndmask_b32_e32 v80, v104, v80, vcc
	v_div_scale_f32 v104, s[2:3], v80, v80, 1.0
	v_rcp_f32_e32 v105, v104
	v_pk_fma_f32 v[142:143], v[142:143], v[130:131], v[8:9]
	v_cvt_pk_bf16_f32 v152, v152, v153
	v_cvt_pk_bf16_f32 v153, v154, v155
	v_fma_f32 v106, -v104, v105, 1.0
	v_fmac_f32_e32 v105, v106, v105
	v_div_scale_f32 v106, vcc, 1.0, v80, 1.0
	v_mul_f32_e32 v107, v106, v105
	v_fma_f32 v108, -v104, v107, v106
	v_fmac_f32_e32 v107, v108, v105
	v_fma_f32 v104, -v104, v107, v106
	v_div_fmas_f32 v104, v104, v105, v107
	v_div_fixup_f32 v80, v104, v80, 1.0
	v_mov_b32_e32 v105, v90
	v_mov_b32_e32 v107, v98
	v_mov_b32_e32 v90, v89
	v_mov_b32_e32 v98, v95
	v_mov_b32_e32 v104, v88
	v_mov_b32_e32 v106, v94
	v_pk_mul_f32 v[88:89], v[80:81], v[90:91] op_sel_hi:[0,1]
	v_pk_mul_f32 v[90:91], v[80:81], v[98:99] op_sel_hi:[0,1]
	v_pk_mul_f32 v[92:93], v[80:81], v[96:97] op_sel_hi:[0,1]
	v_pk_mul_f32 v[94:95], v[80:81], v[102:103] op_sel_hi:[0,1]
	v_pk_fma_f32 v[90:91], v[90:91], v[124:125], v[6:7]
	v_pk_fma_f32 v[88:89], v[88:89], v[126:127], v[4:5]
	v_pk_fma_f32 v[94:95], v[94:95], v[120:121], v[2:3]
	v_pk_fma_f32 v[92:93], v[92:93], v[122:123], v[0:1]
	v_lshl_add_u64 v[108:109], v[20:21], 0, s[46:47]
	v_pk_mul_f32 v[104:105], v[80:81], v[104:105] op_sel_hi:[0,1]
	v_pk_mul_f32 v[106:107], v[80:81], v[106:107] op_sel_hi:[0,1]
	v_pk_mul_f32 v[110:111], v[80:81], v[110:111] op_sel_hi:[0,1]
	v_pk_mul_f32 v[112:113], v[80:81], v[112:113] op_sel_hi:[0,1]
	v_cvt_pk_bf16_f32 v88, v88, v89
	v_cvt_pk_bf16_f32 v89, v90, v91
	v_cvt_pk_bf16_f32 v90, v92, v93
	v_cvt_pk_bf16_f32 v91, v94, v95
	v_fmamk_f32 v80, v189, 0x3a800000, v214
	flat_store_dwordx4 v[108:109], v[88:91] offset:1024 sc0 sc1
	v_cmp_gt_f32_e32 vcc, s19, v80
	v_mov_b32_e32 v95, v78
	v_mul_f32_e32 v88, 0x4f800000, v80
	v_cndmask_b32_e32 v80, v80, v88, vcc
	v_sqrt_f32_e32 v88, v80
	v_mov_b32_e32 v97, v86
	v_mov_b32_e32 v78, v75
	v_mov_b32_e32 v86, v85
	v_add_u32_e32 v89, -1, v88
	v_fma_f32 v90, -v89, v88, v80
	v_cmp_ge_f32_e64 s[36:37], 0, v90
	v_add_u32_e32 v90, 1, v88
	v_mov_b32_e32 v94, v74
	v_cndmask_b32_e64 v89, v88, v89, s[36:37]
	v_fma_f32 v88, -v90, v88, v80
	v_cmp_lt_f32_e64 s[36:37], 0, v88
	v_pk_fma_f32 v[106:107], v[132:133], v[106:107], v[14:15]
	v_pk_fma_f32 v[104:105], v[134:135], v[104:105], v[12:13]
	v_cndmask_b32_e64 v88, v89, v90, s[36:37]
	v_mul_f32_e32 v89, 0x37800000, v88
	v_cndmask_b32_e32 v88, v88, v89, vcc
	v_cmp_class_f32_e32 vcc, v80, v215
	v_mov_b32_e32 v96, v84
	v_pk_fma_f32 v[112:113], v[128:129], v[112:113], v[10:11]
	v_cndmask_b32_e32 v80, v88, v80, vcc
	v_div_scale_f32 v88, s[2:3], v80, v80, 1.0
	v_rcp_f32_e32 v89, v88
	v_pk_fma_f32 v[110:111], v[130:131], v[110:111], v[8:9]
	v_cvt_pk_bf16_f32 v154, v158, v159
	v_cvt_pk_bf16_f32 v155, v160, v161
	v_fma_f32 v90, -v88, v89, 1.0
	v_fmac_f32_e32 v89, v90, v89
	v_div_scale_f32 v90, vcc, 1.0, v80, 1.0
	v_mul_f32_e32 v91, v90, v89
	v_fma_f32 v92, -v88, v91, v90
	v_fmac_f32_e32 v91, v92, v89
; __device__ __forceinline__ unsigned pk2(float lo, float hi) { return pg8::cvt_pk_bf16(lo, hi); }
; __device__ __forceinline__ void unpack8(const u32x4 w, f32x4& a, f32x4& c) { a = (f32x4){bf_lo(w.x), bf_hi(w.x), bf_lo(w.y), bf_hi(w.y)}; c = (f32x4){bf_lo(w.z), bf_hi(w.z), bf_lo(w.w), bf_hi(w.w)}; }
; template <bool X_F32> __device__ __forceinline__ void phase_norm_mod(const Ctx& C, const void* xin, const float* modl, int shift_idx, int scale_idx) {
;     ...
; #pragma unroll
;             for (int r = 0; r < NR; ++r) { const float rs = 1.0f / sqrtf(s[r] * (1.f / DM) + EPS);
; #pragma unroll
;                 for (int j = 0; j < 2; ++j) { f32x4 t0, t1; unpack8(raw[r][j], t0, t1);
;                     const f32x4 y0 = t0 * rs * g[2 * j] + a[2 * j], y1 = t1 * rs * g[2 * j + 1] + a[2 * j + 1];
;                     u32x4 w; w.x = pk2(y0.x, y0.y); w.y = pk2(y0.z, y0.w); w.z = pk2(y1.x, y1.y); w.w = pk2(y1.z, y1.w);
;                     ((u32x4*)(H + (size_t)(m0 + r) * DM + 512 * j))[lane] = w; } }
	v_fma_f32 v88, -v88, v91, v90
	v_div_fmas_f32 v88, v88, v89, v91
	v_div_fixup_f32 v80, v88, v80, 1.0
	v_mov_b32_e32 v89, v72
	v_mov_b32_e32 v91, v82
	v_mov_b32_e32 v72, v71
	v_mov_b32_e32 v82, v77
	v_mov_b32_e32 v88, v70
	v_mov_b32_e32 v90, v76
	v_pk_mul_f32 v[70:71], v[80:81], v[72:73] op_sel_hi:[0,1]
	v_pk_mul_f32 v[72:73], v[80:81], v[82:83] op_sel_hi:[0,1]
	v_pk_mul_f32 v[74:75], v[80:81], v[78:79] op_sel_hi:[0,1]
	v_pk_mul_f32 v[76:77], v[80:81], v[86:87] op_sel_hi:[0,1]
	v_pk_fma_f32 v[72:73], v[72:73], v[124:125], v[6:7]
	v_pk_fma_f32 v[70:71], v[70:71], v[126:127], v[4:5]
	v_pk_fma_f32 v[76:77], v[76:77], v[120:121], v[2:3]
	v_pk_fma_f32 v[74:75], v[74:75], v[122:123], v[0:1]
	v_lshl_add_u64 v[92:93], v[20:21], 0, s[44:45]
	v_cvt_pk_bf16_f32 v70, v70, v71
	v_cvt_pk_bf16_f32 v71, v72, v73
	v_cvt_pk_bf16_f32 v72, v74, v75
	v_cvt_pk_bf16_f32 v73, v76, v77
	flat_store_dwordx4 v[92:93], v[70:73] offset:1024 sc0 sc1
	v_mov_b32_e32 v79, v62
	v_mov_b32_e32 v83, v68
	v_fmamk_f32 v70, v188, 0x3a800000, v214
	v_cmp_gt_f32_e32 vcc, s19, v70
	v_mul_f32_e32 v71, 0x4f800000, v70
	v_mov_b32_e32 v62, v59
	v_cndmask_b32_e32 v70, v70, v71, vcc
	v_sqrt_f32_e32 v71, v70
	v_mov_b32_e32 v68, v67
	v_mov_b32_e32 v78, v58
	v_lshl_add_u64 v[76:77], v[20:21], 0, s[42:43]
	v_add_u32_e32 v72, -1, v71
	v_fma_f32 v73, -v72, v71, v70
	v_cmp_ge_f32_e64 s[36:37], 0, v73
	v_add_u32_e32 v73, 1, v71
	v_pk_mul_f32 v[88:89], v[80:81], v[88:89] op_sel_hi:[0,1]
	v_cndmask_b32_e64 v72, v71, v72, s[36:37]
	v_fma_f32 v71, -v73, v71, v70
	v_cmp_lt_f32_e64 s[36:37], 0, v71
	v_pk_mul_f32 v[90:91], v[80:81], v[90:91] op_sel_hi:[0,1]
	v_pk_fma_f32 v[90:91], v[132:133], v[90:91], v[14:15]
	v_cndmask_b32_e64 v71, v72, v73, s[36:37]
	v_mul_f32_e32 v72, 0x37800000, v71
	v_cndmask_b32_e32 v71, v71, v72, vcc
	v_cmp_class_f32_e32 vcc, v70, v215
	v_pk_fma_f32 v[88:89], v[134:135], v[88:89], v[12:13]
	v_mov_b32_e32 v82, v66
	v_cndmask_b32_e32 v70, v71, v70, vcc
	v_div_scale_f32 v71, s[2:3], v70, v70, 1.0
	v_rcp_f32_e32 v72, v71
	v_pk_mul_f32 v[96:97], v[80:81], v[96:97] op_sel_hi:[0,1]
	v_pk_mul_f32 v[94:95], v[80:81], v[94:95] op_sel_hi:[0,1]
	v_pk_fma_f32 v[96:97], v[128:129], v[96:97], v[10:11]
	v_fma_f32 v73, -v71, v72, 1.0
	v_fmac_f32_e32 v72, v73, v72
	v_div_scale_f32 v73, vcc, 1.0, v70, 1.0
	v_mul_f32_e32 v74, v73, v72
	v_fma_f32 v75, -v71, v74, v73
	v_fmac_f32_e32 v74, v75, v72
	v_fma_f32 v71, -v71, v74, v73
	v_div_fmas_f32 v71, v71, v72, v74
	v_div_fixup_f32 v70, v71, v70, 1.0
	v_mov_b32_e32 v73, v56
	v_mov_b32_e32 v75, v64
	v_mov_b32_e32 v56, v55
	v_mov_b32_e32 v64, v61
	v_mov_b32_e32 v72, v54
	v_mov_b32_e32 v74, v60
	v_pk_mul_f32 v[54:55], v[70:71], v[56:57] op_sel_hi:[0,1]
	v_pk_mul_f32 v[56:57], v[70:71], v[64:65] op_sel_hi:[0,1]
	v_pk_mul_f32 v[58:59], v[70:71], v[62:63] op_sel_hi:[0,1]
	v_pk_mul_f32 v[60:61], v[70:71], v[68:69] op_sel_hi:[0,1]
	v_pk_fma_f32 v[56:57], v[124:125], v[56:57], v[6:7]
	v_pk_fma_f32 v[54:55], v[126:127], v[54:55], v[4:5]
	v_pk_fma_f32 v[60:61], v[60:61], v[120:121], v[2:3]
	v_pk_fma_f32 v[58:59], v[58:59], v[122:123], v[0:1]
	v_cvt_pk_bf16_f32 v54, v54, v55
	v_cvt_pk_bf16_f32 v55, v56, v57
	v_cvt_pk_bf16_f32 v56, v58, v59
	v_cvt_pk_bf16_f32 v57, v60, v61
	flat_store_dwordx4 v[76:77], v[54:57] offset:1024 sc0 sc1
	v_mov_b32_e32 v63, v46
	v_mov_b32_e32 v65, v52
	v_fmamk_f32 v54, v187, 0x3a800000, v214
	v_cmp_gt_f32_e32 vcc, s19, v54
	v_mul_f32_e32 v55, 0x4f800000, v54
	v_mov_b32_e32 v46, v43
	v_cndmask_b32_e32 v54, v54, v55, vcc
	v_sqrt_f32_e32 v55, v54
	v_mov_b32_e32 v52, v51
	v_mov_b32_e32 v62, v42
	v_lshl_add_u64 v[60:61], v[20:21], 0, s[40:41]
	v_add_u32_e32 v56, -1, v55
	v_fma_f32 v57, -v56, v55, v54
	v_cmp_ge_f32_e64 s[36:37], 0, v57
	v_add_u32_e32 v57, 1, v55
	v_pk_mul_f32 v[72:73], v[70:71], v[72:73] op_sel_hi:[0,1]
	v_cndmask_b32_e64 v56, v55, v56, s[36:37]
	v_fma_f32 v55, -v57, v55, v54
	v_cmp_lt_f32_e64 s[36:37], 0, v55
	v_pk_mul_f32 v[74:75], v[70:71], v[74:75] op_sel_hi:[0,1]
	v_pk_fma_f32 v[74:75], v[132:133], v[74:75], v[14:15]
	v_cndmask_b32_e64 v55, v56, v57, s[36:37]
	v_mul_f32_e32 v56, 0x37800000, v55
	v_cndmask_b32_e32 v55, v55, v56, vcc
	v_cmp_class_f32_e32 vcc, v54, v215
	v_pk_fma_f32 v[72:73], v[134:135], v[72:73], v[12:13]
	v_mov_b32_e32 v64, v50
	v_cndmask_b32_e32 v54, v55, v54, vcc
	v_div_scale_f32 v55, s[2:3], v54, v54, 1.0
	v_rcp_f32_e32 v56, v55
	v_pk_mul_f32 v[82:83], v[70:71], v[82:83] op_sel_hi:[0,1]
	v_pk_mul_f32 v[78:79], v[70:71], v[78:79] op_sel_hi:[0,1]
	v_pk_fma_f32 v[82:83], v[128:129], v[82:83], v[10:11]
	v_fma_f32 v57, -v55, v56, 1.0
	v_fmac_f32_e32 v56, v57, v56
	v_div_scale_f32 v57, vcc, 1.0, v54, 1.0
	v_mul_f32_e32 v58, v57, v56
	v_fma_f32 v59, -v55, v58, v57
	v_fmac_f32_e32 v58, v59, v56
	v_fma_f32 v55, -v55, v58, v57
	v_div_fmas_f32 v55, v55, v56, v58
	v_div_fixup_f32 v54, v55, v54, 1.0
	v_mov_b32_e32 v57, v40
	v_mov_b32_e32 v59, v48
	v_mov_b32_e32 v40, v39
	v_mov_b32_e32 v48, v45
; __device__ __forceinline__ unsigned pk2(float lo, float hi) { return pg8::cvt_pk_bf16(lo, hi); }
; __device__ __forceinline__ void unpack8(const u32x4 w, f32x4& a, f32x4& c) { a = (f32x4){bf_lo(w.x), bf_hi(w.x), bf_lo(w.y), bf_hi(w.y)}; c = (f32x4){bf_lo(w.z), bf_hi(w.z), bf_lo(w.w), bf_hi(w.w)}; }
; template <bool X_F32> __device__ __forceinline__ void phase_norm_mod(const Ctx& C, const void* xin, const float* modl, int shift_idx, int scale_idx) {
;     ...
; #pragma unroll
;             for (int r = 0; r < NR; ++r) { const float rs = 1.0f / sqrtf(s[r] * (1.f / DM) + EPS);
; #pragma unroll
;                 for (int j = 0; j < 2; ++j) { f32x4 t0, t1; unpack8(raw[r][j], t0, t1);
;                     const f32x4 y0 = t0 * rs * g[2 * j] + a[2 * j], y1 = t1 * rs * g[2 * j + 1] + a[2 * j + 1];
;                     u32x4 w; w.x = pk2(y0.x, y0.y); w.y = pk2(y0.z, y0.w); w.z = pk2(y1.x, y1.y); w.w = pk2(y1.z, y1.w);
;                     ((u32x4*)(H + (size_t)(m0 + r) * DM + 512 * j))[lane] = w; } }
	v_mov_b32_e32 v56, v38
	v_mov_b32_e32 v58, v44
	v_pk_mul_f32 v[38:39], v[54:55], v[40:41] op_sel_hi:[0,1]
	v_pk_mul_f32 v[40:41], v[54:55], v[48:49] op_sel_hi:[0,1]
	v_pk_mul_f32 v[42:43], v[54:55], v[46:47] op_sel_hi:[0,1]
	v_pk_mul_f32 v[44:45], v[54:55], v[52:53] op_sel_hi:[0,1]
	v_pk_fma_f32 v[40:41], v[124:125], v[40:41], v[6:7]
	v_pk_fma_f32 v[38:39], v[126:127], v[38:39], v[4:5]
	v_pk_fma_f32 v[44:45], v[44:45], v[120:121], v[2:3]
	v_pk_fma_f32 v[42:43], v[42:43], v[122:123], v[0:1]
	v_cvt_pk_bf16_f32 v38, v38, v39
	v_cvt_pk_bf16_f32 v39, v40, v41
	v_cvt_pk_bf16_f32 v40, v42, v43
	v_cvt_pk_bf16_f32 v41, v44, v45
	flat_store_dwordx4 v[60:61], v[38:41] offset:1024 sc0 sc1
	v_mov_b32_e32 v44, v28
	v_mov_b32_e32 v45, v32
	v_fmamk_f32 v38, v186, 0x3a800000, v214
	v_cmp_gt_f32_e32 vcc, s19, v38
	v_mul_f32_e32 v39, 0x4f800000, v38
	v_pk_mul_f32 v[56:57], v[54:55], v[56:57] op_sel_hi:[0,1]
	v_cndmask_b32_e32 v38, v38, v39, vcc
	v_sqrt_f32_e32 v39, v38
	v_pk_mul_f32 v[58:59], v[54:55], v[58:59] op_sel_hi:[0,1]
	v_pk_fma_f32 v[58:59], v[132:133], v[58:59], v[14:15]
	v_pk_fma_f32 v[56:57], v[134:135], v[56:57], v[12:13]
	v_add_u32_e32 v40, -1, v39
	v_fma_f32 v41, -v40, v39, v38
	v_cmp_ge_f32_e64 s[36:37], 0, v41
	v_add_u32_e32 v41, 1, v39
	v_pk_mul_f32 v[64:65], v[54:55], v[64:65] op_sel_hi:[0,1]
	v_cndmask_b32_e64 v40, v39, v40, s[36:37]
	v_fma_f32 v39, -v41, v39, v38
	v_cmp_lt_f32_e64 s[36:37], 0, v39
	v_pk_mul_f32 v[62:63], v[54:55], v[62:63] op_sel_hi:[0,1]
	v_pk_fma_f32 v[64:65], v[128:129], v[64:65], v[10:11]
	v_cndmask_b32_e64 v39, v40, v41, s[36:37]
	v_mul_f32_e32 v40, 0x37800000, v39
	v_cndmask_b32_e32 v39, v39, v40, vcc
	v_cmp_class_f32_e32 vcc, v38, v215
	v_pk_fma_f32 v[94:95], v[130:131], v[94:95], v[8:9]
	v_pk_fma_f32 v[78:79], v[130:131], v[78:79], v[8:9]
	v_cndmask_b32_e32 v38, v39, v38, vcc
	v_div_scale_f32 v39, s[2:3], v38, v38, 1.0
	v_rcp_f32_e32 v40, v39
	v_pk_fma_f32 v[62:63], v[130:131], v[62:63], v[8:9]
	v_mov_b32_e32 v32, v29
	s_add_i32 s2, s20, s21
	v_fma_f32 v41, -v39, v40, 1.0
	v_fmac_f32_e32 v40, v41, v40
	v_div_scale_f32 v41, vcc, 1.0, v38, 1.0
	v_mul_f32_e32 v42, v41, v40
	v_fma_f32 v43, -v39, v42, v41
	v_fmac_f32_e32 v42, v43, v40
	v_fma_f32 v39, -v39, v42, v41
	v_div_fmas_f32 v39, v39, v40, v42
	v_div_fixup_f32 v38, v39, v38, 1.0
	v_mov_b32_e32 v42, v22
	v_mov_b32_e32 v43, v24
	v_pk_mul_f32 v[42:43], v[38:39], v[42:43] op_sel_hi:[0,1]
	v_pk_mul_f32 v[44:45], v[38:39], v[44:45] op_sel_hi:[0,1]
	v_pk_fma_f32 v[14:15], v[132:133], v[44:45], v[14:15]
	v_pk_fma_f32 v[12:13], v[134:135], v[42:43], v[12:13]
	v_mov_b32_e32 v42, v26
	v_mov_b32_e32 v43, v30
	v_mov_b32_e32 v44, v34
	v_mov_b32_e32 v45, v36
	v_pk_mul_f32 v[42:43], v[38:39], v[42:43] op_sel_hi:[0,1]
	v_pk_mul_f32 v[44:45], v[38:39], v[44:45] op_sel_hi:[0,1]
	v_pk_fma_f32 v[44:45], v[128:129], v[44:45], v[10:11]
	v_pk_fma_f32 v[10:11], v[130:131], v[42:43], v[8:9]
	v_lshl_add_u64 v[40:41], v[20:21], 0, s[38:39]
	v_cvt_pk_bf16_f32 v8, v12, v13
	v_cvt_pk_bf16_f32 v9, v14, v15
	v_cvt_pk_bf16_f32 v10, v10, v11
	v_cvt_pk_bf16_f32 v11, v44, v45
	v_mov_b32_e32 v24, v23
	flat_store_dwordx4 v[40:41], v[8:11] sc0 sc1
	v_mov_b32_e32 v30, v27
	v_mov_b32_e32 v36, v35
	v_pk_mul_f32 v[8:9], v[38:39], v[24:25] op_sel_hi:[0,1]
	v_pk_mul_f32 v[10:11], v[38:39], v[32:33] op_sel_hi:[0,1]
	v_pk_fma_f32 v[6:7], v[124:125], v[10:11], v[6:7]
	v_pk_fma_f32 v[4:5], v[126:127], v[8:9], v[4:5]
	v_pk_mul_f32 v[8:9], v[38:39], v[30:31] op_sel_hi:[0,1]
	v_pk_mul_f32 v[10:11], v[38:39], v[36:37] op_sel_hi:[0,1]
	v_pk_fma_f32 v[10:11], v[120:121], v[10:11], v[2:3]
	v_pk_fma_f32 v[2:3], v[122:123], v[8:9], v[0:1]
	v_cvt_pk_bf16_f32 v136, v136, v137
	v_cvt_pk_bf16_f32 v137, v138, v139
	v_cvt_pk_bf16_f32 v138, v142, v143
	v_cvt_pk_bf16_f32 v139, v144, v145
	v_cvt_pk_bf16_f32 v104, v104, v105
	v_cvt_pk_bf16_f32 v105, v106, v107
	v_cvt_pk_bf16_f32 v106, v110, v111
	v_cvt_pk_bf16_f32 v107, v112, v113
	v_cvt_pk_bf16_f32 v88, v88, v89
	v_cvt_pk_bf16_f32 v89, v90, v91
	v_cvt_pk_bf16_f32 v90, v94, v95
	v_cvt_pk_bf16_f32 v91, v96, v97
	v_cvt_pk_bf16_f32 v72, v72, v73
	v_cvt_pk_bf16_f32 v73, v74, v75
	v_cvt_pk_bf16_f32 v74, v78, v79
	v_cvt_pk_bf16_f32 v75, v82, v83
	v_cvt_pk_bf16_f32 v56, v56, v57
	v_cvt_pk_bf16_f32 v57, v58, v59
	v_cvt_pk_bf16_f32 v58, v62, v63
	v_cvt_pk_bf16_f32 v59, v64, v65
	v_cvt_pk_bf16_f32 v0, v4, v5
	v_cvt_pk_bf16_f32 v1, v6, v7
	v_cvt_pk_bf16_f32 v2, v2, v3
	v_cvt_pk_bf16_f32 v3, v10, v11
	s_cmpk_lt_i32 s2, 0x1000
	flat_store_dwordx4 v[198:199], v[194:197] sc0 sc1
	flat_store_dwordx4 v[156:157], v[152:155] sc0 sc1
	flat_store_dwordx4 v[140:141], v[136:139] sc0 sc1
	flat_store_dwordx4 v[108:109], v[104:107] sc0 sc1
	flat_store_dwordx4 v[92:93], v[88:91] sc0 sc1
	flat_store_dwordx4 v[76:77], v[72:75] sc0 sc1
	flat_store_dwordx4 v[60:61], v[56:59] sc0 sc1
	flat_store_dwordx4 v[40:41], v[0:3] offset:1024 sc0 sc1
	s_cbranch_scc1 .LBB0_499

; __device__ __forceinline__ unsigned cvt_pk_bf16(float lo, float hi) { f32x2_cv v = {lo, hi}; bf16x2_cv b = __builtin_convertvector(v, bf16x2_cv); return __builtin_bit_cast(unsigned, b); }
;     __device__ __forceinline__ void operator()(const f32x4 (&acc)[2][2][4][2], const Unit& u, int wr, int wc, int fr_, int fq_) const {
;     ...
;         for (int ai = 0; ai < 2; ++ai) {
;             const int grp = (rowu + ai * HALF) >> 6;
; #pragma unroll
;             for (int mm = 0; mm < 2; ++mm) { const int m = mm * 3;
;                 const bool is_edge = mm == 0 ? (fr < 2) : (fr >= 14);
;                 if (is_edge) { const unsigned e = (unsigned)(mm == 0 ? fr : fr - 12);
;                     bf16_t* eb = edge + (size_t)grp * 4 * 5632;
; #pragma unroll
;                     for (int bj = 0; bj < 2; ++bj) { const f32x4 v0 = acc[ai][bj][m][0], v1 = acc[ai][bj][m][1];
;                         u32x4 w; w.x = cvt_pk_bf16(v0[0], v0[1]); w.y = cvt_pk_bf16(v0[2], v0[3]); w.z = cvt_pk_bf16(v1[0], v1[1]); w.w = cvt_pk_bf16(v1[2], v1[3]);
;                         *(u32x4*)(eb + (e * 5632u + ecol + (unsigned)(bj * HALF))) = w; } } }
.LBB0_562:
	s_lshl_b32 s63, s20, 8
	v_readlane_b32 s3, v255, 44
	v_mov_b32_e32 v189, v187
	v_mov_b32_e32 v80, v219
	s_add_i32 s63, s63, s3
	s_lshl_b32 s3, s4, 8
	s_or_b32 s3, s3, s92
	v_lshlrev_b32_e32 v130, 3, v80
	s_ashr_i32 s5, s63, 6
	v_add_u32_e32 v186, s3, v130
	v_cmp_lt_i32_e64 s[40:41], 1, v189
	v_cmp_gt_i32_e32 vcc, 2, v189
	s_mul_hi_i32 s3, s5, 0xb000
	s_mul_i32 s5, s5, 0xb000
	s_and_saveexec_b64 s[12:13], vcc
	s_cbranch_execz .LBB0_564
	s_movk_i32 s38, 0x1600
	s_add_u32 s20, s94, s5
	v_readlane_b32 s21, v255, 43
	v_mad_u64_u32 v[136:137], s[38:39], v189, s38, v[186:187]
	s_addc_u32 s21, s21, s3
	v_mov_b32_e32 v137, v81
	v_cvt_pk_bf16_f32 v132, v126, v127
	v_cvt_pk_bf16_f32 v133, v128, v129
	v_cvt_pk_bf16_f32 v134, v94, v95
	v_cvt_pk_bf16_f32 v135, v96, v97
	v_lshl_add_u64 v[138:139], v[136:137], 1, s[20:21]
	v_add_u32_e32 v80, 0x80, v136
	global_store_dwordx4 v[138:139], v[132:135], off sc0 sc1
	v_lshl_add_u64 v[136:137], v[80:81], 1, s[20:21]
	s_nop 0
	v_cvt_pk_bf16_f32 v132, v122, v123
	v_cvt_pk_bf16_f32 v133, v124, v125
	v_cvt_pk_bf16_f32 v134, v90, v91
	v_cvt_pk_bf16_f32 v135, v92, v93
	global_store_dwordx4 v[136:137], v[132:135], off sc0 sc1
.LBB0_564:
	s_or_b64 exec, exec, s[12:13]
	v_cmp_lt_i32_e64 s[42:43], 13, v189
	v_add_u32_e32 v223, -12, v189
	s_and_saveexec_b64 s[12:13], s[42:43]
	s_cbranch_execz .LBB0_566
	s_add_u32 s20, s94, s5
	v_readlane_b32 s5, v255, 43
	s_addc_u32 s21, s5, s3
	s_movk_i32 s3, 0x1600
	v_mad_u64_u32 v[136:137], s[38:39], v223, s3, v[186:187]
	v_mov_b32_e32 v137, v81
	v_cvt_pk_bf16_f32 v132, v102, v103
	v_cvt_pk_bf16_f32 v133, v104, v105
	v_cvt_pk_bf16_f32 v134, v68, v69
	v_cvt_pk_bf16_f32 v135, v70, v71
	v_lshl_add_u64 v[138:139], v[136:137], 1, s[20:21]
	v_add_u32_e32 v80, 0x80, v136
	global_store_dwordx4 v[138:139], v[132:135], off sc0 sc1
	v_lshl_add_u64 v[136:137], v[80:81], 1, s[20:21]
	s_nop 0
	v_cvt_pk_bf16_f32 v132, v98, v99
	v_cvt_pk_bf16_f32 v133, v100, v101
	v_cvt_pk_bf16_f32 v134, v64, v65
	v_cvt_pk_bf16_f32 v135, v66, v67
	global_store_dwordx4 v[136:137], v[132:135], off sc0 sc1

; __device__ __forceinline__ unsigned cvt_pk_bf16(float lo, float hi) { f32x2_cv v = {lo, hi}; bf16x2_cv b = __builtin_convertvector(v, bf16x2_cv); return __builtin_bit_cast(unsigned, b); }
;     __device__ __forceinline__ void operator()(const f32x4 (&acc)[2][2][4][2], const Unit& u, int wr, int wc, int fr_, int fq_) const {
;     ...
; #pragma unroll
;             for (int n = 0; n < 2; ++n) {
;                 int jl = jbase + 4 * n; asm volatile("" : "+v"(jl) :: "memory");
;                 const unsigned j = (unsigned)jl;
;                 const f32x4 wg0 = *(const f32x4*)(cw + j), wg1 = *(const f32x4*)(cw + 5632 + j), wg2 = *(const f32x4*)(cw + 2 * 5632 + j), bg = *(const f32x4*)(cb + j);
;                 const f32x4 wv0 = *(const f32x4*)(cw + 2816 + j), wv1 = *(const f32x4*)(cw + 5632 + 2816 + j), wv2 = *(const f32x4*)(cw + 2 * 5632 + 2816 + j), bv = *(const f32x4*)(cb + 2816 + j);
;                 const unsigned loff = (unsigned)fr * 2816u + j;
;                 const bool c1 = fr == 0, c2 = fr < 2;
;                 f32x4 g1p = (f32x4){0.f, 0.f, 0.f, 0.f}, g2p = g1p, v1p = g1p, v2p = g1p;
; #pragma unroll
;                 for (int m = 0; m < 4; ++m) {
;                     const f32x4 xg = acc[ai][0][m][n], xv = acc[ai][1][m][n];
;                     f32x4 g1, g2, v1, v2;
; #pragma unroll
;                     for (int i = 0; i < 4; ++i) { g1[i] = dpp_ror1(xg[i]); g2[i] = dpp_ror2(xg[i]); v1[i] = dpp_ror1(xv[i]); v2[i] = dpp_ror2(xv[i]); }
;                     f32x4 pg1, pg2, pv1, pv2;
; #pragma unroll
;                     for (int i = 0; i < 4; ++i) { pg1[i] = c1 ? g1p[i] : g1[i]; pg2[i] = c2 ? g2p[i] : g2[i]; pv1[i] = c1 ? v1p[i] : v1[i]; pv2[i] = c2 ? v2p[i] : v2[i]; }
;                     const f32x4 G = wg0 * pg2 + wg1 * pg1 + wg2 * xg + bg;
;                     const f32x4 V = wv0 * pv2 + wv1 * pv1 + wv2 * xv + bv;
;                     f32x4 r;
; #pragma unroll
;                     for (int i = 0; i < 4; ++i) r[i] = G[i] * __builtin_amdgcn_rcpf(1.0f + __builtin_amdgcn_exp2f(-1.4426950408889634f * G[i])) * V[i];
;                     u32x2 w; w.x = cvt_pk_bf16(r[0], r[1]); w.y = cvt_pk_bf16(r[2], r[3]);
;                     if (m > 0 || !c2) *(u32x2*)(ACT + (size_t)(rowu + ai * HALF + m * 16) * 2816 + loff) = w;
;                     g1p = g1; g2p = g2; v1p = v1; v2p = v2;
.LBB0_570:
	s_andn2_saveexec_b64 s[70:71], s[70:71]
	s_or_b64 exec, exec, s[70:71]
	v_mov_b32_dpp v97, v86 row_ror:2 row_mask:0xf bank_mask:0xf
	v_mov_b32_dpp v150, v87 row_ror:2 row_mask:0xf bank_mask:0xf
	v_mov_b32_dpp v96, v86 row_ror:1 row_mask:0xf bank_mask:0xf
	v_mov_b32_dpp v149, v87 row_ror:1 row_mask:0xf bank_mask:0xf
	v_cndmask_b32_e32 v91, v150, v147, vcc
	v_cndmask_b32_e32 v90, v97, v146, vcc
	s_waitcnt lgkmcnt(0)
	v_pk_mul_f32 v[90:91], v[126:127], v[90:91]
	v_cndmask_b32_e64 v93, v149, v145, s[38:39]
	v_cndmask_b32_e64 v92, v96, v144, s[38:39]
	v_pk_fma_f32 v[90:91], v[118:119], v[92:93], v[90:91]
	v_mov_b32_dpp v148, v82 row_ror:2 row_mask:0xf bank_mask:0xf
	v_pk_fma_f32 v[86:87], v[86:87], v[114:115], v[90:91]
	v_mov_b32_dpp v152, v83 row_ror:2 row_mask:0xf bank_mask:0xf
	v_pk_add_f32 v[86:87], v[122:123], v[86:87]
	v_mov_b32_dpp v131, v82 row_ror:1 row_mask:0xf bank_mask:0xf
	v_mul_f32_e32 v90, 0xbfb8aa3b, v86
	v_mul_f32_e32 v91, 0xbfb8aa3b, v87
	v_exp_f32_e32 v90, v90
	v_exp_f32_e32 v91, v91
	v_mov_b32_dpp v151, v83 row_ror:1 row_mask:0xf bank_mask:0xf
	v_cndmask_b32_e32 v93, v152, v143, vcc
	v_cndmask_b32_e32 v92, v148, v142, vcc
	v_pk_mul_f32 v[92:93], v[110:111], v[92:93]
	v_cndmask_b32_e64 v95, v151, v139, s[38:39]
	v_cndmask_b32_e64 v94, v131, v138, s[38:39]
	v_mov_b32_dpp v154, v88 row_ror:2 row_mask:0xf bank_mask:0xf
	v_mov_b32_dpp v144, v89 row_ror:2 row_mask:0xf bank_mask:0xf
	v_add_f32_e32 v90, 1.0, v90
	v_pk_fma_f32 v[92:93], v[98:99], v[94:95], v[92:93]
	v_add_f32_e32 v91, 1.0, v91
	v_mov_b32_dpp v153, v88 row_ror:1 row_mask:0xf bank_mask:0xf
	v_mov_b32_dpp v157, v89 row_ror:1 row_mask:0xf bank_mask:0xf
	v_rcp_f32_e32 v90, v90
	v_pk_fma_f32 v[82:83], v[82:83], v[102:103], v[92:93]
	v_rcp_f32_e32 v91, v91
	v_cndmask_b32_e32 v93, v144, v141, vcc
	v_cndmask_b32_e32 v92, v154, v140, vcc
	v_pk_mul_f32 v[92:93], v[128:129], v[92:93]
	v_cndmask_b32_e64 v95, v157, v137, s[38:39]
	v_cndmask_b32_e64 v94, v153, v136, s[38:39]
	v_pk_fma_f32 v[92:93], v[120:121], v[94:95], v[92:93]
	v_pk_add_f32 v[82:83], v[106:107], v[82:83]
	v_pk_fma_f32 v[88:89], v[88:89], v[116:117], v[92:93]
	v_pk_mul_f32 v[86:87], v[86:87], v[90:91]
	v_pk_add_f32 v[88:89], v[124:125], v[88:89]
	v_pk_mul_f32 v[82:83], v[82:83], v[86:87]
	v_mul_f32_e32 v92, 0xbfb8aa3b, v88
	v_mul_f32_e32 v87, 0xbfb8aa3b, v89
	v_exp_f32_e32 v92, v92
	v_exp_f32_e32 v87, v87
	v_mov_b32_dpp v156, v84 row_ror:2 row_mask:0xf bank_mask:0xf
	v_mov_b32_dpp v146, v85 row_ror:2 row_mask:0xf bank_mask:0xf
	v_add_f32_e32 v86, 1.0, v92
	v_add_f32_e32 v87, 1.0, v87
	v_mov_b32_dpp v155, v84 row_ror:1 row_mask:0xf bank_mask:0xf
	v_mov_b32_dpp v145, v85 row_ror:1 row_mask:0xf bank_mask:0xf
	v_rcp_f32_e32 v86, v86
	v_cndmask_b32_e32 v91, v146, v135, vcc
	v_cndmask_b32_e32 v90, v156, v134, vcc
	v_rcp_f32_e32 v87, v87
	v_pk_mul_f32 v[90:91], v[112:113], v[90:91]
	v_cndmask_b32_e64 v93, v145, v133, s[38:39]
	v_cndmask_b32_e64 v92, v155, v132, s[38:39]
	v_pk_fma_f32 v[90:91], v[100:101], v[92:93], v[90:91]
	v_pk_mul_f32 v[86:87], v[88:89], v[86:87]
	v_pk_fma_f32 v[84:85], v[84:85], v[104:105], v[90:91]
	s_nop 0
	v_pk_add_f32 v[84:85], v[108:109], v[84:85]
	s_nop 0
	v_pk_mul_f32 v[84:85], v[84:85], v[86:87]
	s_nop 0
	v_cvt_pk_bf16_f32 v85, v84, v85
	v_cvt_pk_bf16_f32 v84, v82, v83
	v_lshlrev_b64 v[82:83], 1, v[80:81]
	v_lshl_add_u64 v[86:87], s[4:5], 0, v[82:83]
	global_store_dwordx2 v[86:87], v[84:85], off
	v_mov_b32_dpp v90, v76 row_ror:2 row_mask:0xf bank_mask:0xf
	v_mov_b32_dpp v94, v77 row_ror:2 row_mask:0xf bank_mask:0xf
	v_mov_b32_dpp v80, v76 row_ror:1 row_mask:0xf bank_mask:0xf
	v_mov_b32_dpp v93, v77 row_ror:1 row_mask:0xf bank_mask:0xf
	v_cndmask_b32_e32 v85, v94, v150, vcc
	v_cndmask_b32_e32 v84, v90, v97, vcc
	v_pk_mul_f32 v[84:85], v[126:127], v[84:85]
	v_cndmask_b32_e64 v87, v93, v149, s[38:39]
	v_cndmask_b32_e64 v86, v80, v96, s[38:39]
	v_pk_fma_f32 v[84:85], v[118:119], v[86:87], v[84:85]
	v_mov_b32_dpp v92, v72 row_ror:2 row_mask:0xf bank_mask:0xf
	v_pk_fma_f32 v[76:77], v[76:77], v[114:115], v[84:85]
	v_mov_b32_dpp v132, v73 row_ror:2 row_mask:0xf bank_mask:0xf
	v_pk_add_f32 v[76:77], v[122:123], v[76:77]
	v_mov_b32_dpp v91, v72 row_ror:1 row_mask:0xf bank_mask:0xf
	v_mul_f32_e32 v84, 0xbfb8aa3b, v76
	v_mul_f32_e32 v85, 0xbfb8aa3b, v77
	v_exp_f32_e32 v84, v84
	v_exp_f32_e32 v85, v85
	v_mov_b32_dpp v95, v73 row_ror:1 row_mask:0xf bank_mask:0xf
	v_cndmask_b32_e32 v87, v132, v152, vcc
	v_add_f32_e32 v84, 1.0, v84
	v_add_f32_e32 v85, 1.0, v85
	v_rcp_f32_e32 v84, v84
	v_cndmask_b32_e32 v86, v92, v148, vcc
	v_rcp_f32_e32 v85, v85
	v_pk_mul_f32 v[86:87], v[110:111], v[86:87]
	v_cndmask_b32_e64 v89, v95, v151, s[38:39]
	v_cndmask_b32_e64 v88, v91, v131, s[38:39]
	v_pk_fma_f32 v[86:87], v[98:99], v[88:89], v[86:87]
	v_mov_b32_dpp v134, v78 row_ror:2 row_mask:0xf bank_mask:0xf
	v_pk_fma_f32 v[72:73], v[72:73], v[102:103], v[86:87]
	v_mov_b32_dpp v138, v79 row_ror:2 row_mask:0xf bank_mask:0xf
	v_pk_add_f32 v[72:73], v[106:107], v[72:73]
	v_pk_mul_f32 v[76:77], v[76:77], v[84:85]
	v_mov_b32_dpp v133, v78 row_ror:1 row_mask:0xf bank_mask:0xf
	v_mov_b32_dpp v137, v79 row_ror:1 row_mask:0xf bank_mask:0xf
	v_pk_mul_f32 v[72:73], v[72:73], v[76:77]
	v_cndmask_b32_e32 v77, v138, v144, vcc
	v_cndmask_b32_e32 v76, v134, v154, vcc
	v_pk_mul_f32 v[76:77], v[128:129], v[76:77]
	v_cndmask_b32_e64 v85, v137, v157, s[38:39]
	v_cndmask_b32_e64 v84, v133, v153, s[38:39]
	v_pk_fma_f32 v[76:77], v[120:121], v[84:85], v[76:77]
	v_mov_b32_dpp v136, v74 row_ror:2 row_mask:0xf bank_mask:0xf
	v_pk_fma_f32 v[76:77], v[78:79], v[116:117], v[76:77]
	v_mov_b32_dpp v140, v75 row_ror:2 row_mask:0xf bank_mask:0xf
; __device__ __forceinline__ unsigned cvt_pk_bf16(float lo, float hi) { f32x2_cv v = {lo, hi}; bf16x2_cv b = __builtin_convertvector(v, bf16x2_cv); return __builtin_bit_cast(unsigned, b); }
;     __device__ __forceinline__ void operator()(const f32x4 (&acc)[2][2][4][2], const Unit& u, int wr, int wc, int fr_, int fq_) const {
;     ...
;         for (int ai = 0; ai < 2; ++ai) {
;             const int grp = (rowu + ai * HALF) >> 6;
; #pragma unroll
;             for (int mm = 0; mm < 2; ++mm) { const int m = mm * 3;
;                 const bool is_edge = mm == 0 ? (fr < 2) : (fr >= 14);
;                 if (is_edge) { const unsigned e = (unsigned)(mm == 0 ? fr : fr - 12);
;                     bf16_t* eb = edge + (size_t)grp * 4 * 5632;
; #pragma unroll
;                     for (int bj = 0; bj < 2; ++bj) { const f32x4 v0 = acc[ai][bj][m][0], v1 = acc[ai][bj][m][1];
;                         u32x4 w; w.x = cvt_pk_bf16(v0[0], v0[1]); w.y = cvt_pk_bf16(v0[2], v0[3]); w.z = cvt_pk_bf16(v1[0], v1[1]); w.w = cvt_pk_bf16(v1[2], v1[3]);
;                         *(u32x4*)(eb + (e * 5632u + ecol + (unsigned)(bj * HALF))) = w; } } }
;     ...
;                 for (int m = 0; m < 4; ++m) {
;                     const f32x4 xg = acc[ai][0][m][n], xv = acc[ai][1][m][n];
;                     f32x4 g1, g2, v1, v2;
; #pragma unroll
;                     for (int i = 0; i < 4; ++i) { g1[i] = dpp_ror1(xg[i]); g2[i] = dpp_ror2(xg[i]); v1[i] = dpp_ror1(xv[i]); v2[i] = dpp_ror2(xv[i]); }
;                     f32x4 pg1, pg2, pv1, pv2;
; #pragma unroll
;                     for (int i = 0; i < 4; ++i) { pg1[i] = c1 ? g1p[i] : g1[i]; pg2[i] = c2 ? g2p[i] : g2[i]; pv1[i] = c1 ? v1p[i] : v1[i]; pv2[i] = c2 ? v2p[i] : v2[i]; }
;                     const f32x4 G = wg0 * pg2 + wg1 * pg1 + wg2 * xg + bg;
;                     const f32x4 V = wv0 * pv2 + wv1 * pv1 + wv2 * xv + bv;
;                     f32x4 r;
; #pragma unroll
;                     for (int i = 0; i < 4; ++i) r[i] = G[i] * __builtin_amdgcn_rcpf(1.0f + __builtin_amdgcn_exp2f(-1.4426950408889634f * G[i])) * V[i];
;                     u32x2 w; w.x = cvt_pk_bf16(r[0], r[1]); w.y = cvt_pk_bf16(r[2], r[3]);
;                     if (m > 0 || !c2) *(u32x2*)(ACT + (size_t)(rowu + ai * HALF + m * 16) * 2816 + loff) = w;
;                     g1p = g1; g2p = g2; v1p = v1; v2p = v2;
	v_pk_add_f32 v[76:77], v[124:125], v[76:77]
	v_mov_b32_dpp v135, v74 row_ror:1 row_mask:0xf bank_mask:0xf
	v_mul_f32_e32 v78, 0xbfb8aa3b, v76
	v_mul_f32_e32 v79, 0xbfb8aa3b, v77
	v_exp_f32_e32 v78, v78
	v_exp_f32_e32 v79, v79
	v_mov_b32_dpp v139, v75 row_ror:1 row_mask:0xf bank_mask:0xf
	v_cndmask_b32_e32 v85, v140, v146, vcc
	v_add_f32_e32 v78, 1.0, v78
	v_add_f32_e32 v79, 1.0, v79
	v_rcp_f32_e32 v78, v78
	v_cndmask_b32_e32 v84, v136, v156, vcc
	v_rcp_f32_e32 v79, v79
	v_pk_mul_f32 v[84:85], v[112:113], v[84:85]
	v_cndmask_b32_e64 v87, v139, v145, s[38:39]
	v_cndmask_b32_e64 v86, v135, v155, s[38:39]
	v_pk_fma_f32 v[84:85], v[100:101], v[86:87], v[84:85]
	v_pk_mul_f32 v[76:77], v[76:77], v[78:79]
	v_pk_fma_f32 v[74:75], v[74:75], v[104:105], v[84:85]
	s_nop 0
	v_pk_add_f32 v[74:75], v[108:109], v[74:75]
	s_nop 0
	v_pk_mul_f32 v[74:75], v[74:75], v[76:77]
	s_nop 0
	v_cvt_pk_bf16_f32 v75, v74, v75
	v_cvt_pk_bf16_f32 v74, v72, v73
	v_lshl_add_u64 v[72:73], s[12:13], 0, v[82:83]
	global_store_dwordx2 v[72:73], v[74:75], off
	s_nop 0
	v_mov_b32_dpp v72, v68 row_ror:2 row_mask:0xf bank_mask:0xf
	v_mov_b32_dpp v73, v69 row_ror:2 row_mask:0xf bank_mask:0xf
	v_mov_b32_dpp v74, v68 row_ror:1 row_mask:0xf bank_mask:0xf
	v_mov_b32_dpp v75, v69 row_ror:1 row_mask:0xf bank_mask:0xf
	v_cndmask_b32_e32 v73, v73, v94, vcc
	v_cndmask_b32_e32 v72, v72, v90, vcc
	v_pk_mul_f32 v[72:73], v[126:127], v[72:73]
	v_cndmask_b32_e64 v75, v75, v93, s[38:39]
	v_cndmask_b32_e64 v74, v74, v80, s[38:39]
	v_pk_fma_f32 v[72:73], v[118:119], v[74:75], v[72:73]
	v_mov_b32_dpp v77, v64 row_ror:2 row_mask:0xf bank_mask:0xf
	v_pk_fma_f32 v[68:69], v[68:69], v[114:115], v[72:73]
	v_mov_b32_dpp v79, v65 row_ror:2 row_mask:0xf bank_mask:0xf
	v_pk_add_f32 v[68:69], v[122:123], v[68:69]
	v_mov_b32_dpp v76, v64 row_ror:1 row_mask:0xf bank_mask:0xf
	v_mul_f32_e32 v72, 0xbfb8aa3b, v68
	v_mul_f32_e32 v73, 0xbfb8aa3b, v69
	v_exp_f32_e32 v72, v72
	v_exp_f32_e32 v73, v73
	v_mov_b32_dpp v78, v65 row_ror:1 row_mask:0xf bank_mask:0xf
	v_cndmask_b32_e32 v75, v79, v132, vcc
	v_cndmask_b32_e32 v74, v77, v92, vcc
	v_pk_mul_f32 v[74:75], v[110:111], v[74:75]
	v_cndmask_b32_e64 v77, v78, v95, s[38:39]
	v_cndmask_b32_e64 v76, v76, v91, s[38:39]
	v_mov_b32_dpp v85, v70 row_ror:2 row_mask:0xf bank_mask:0xf
	v_mov_b32_dpp v80, v71 row_ror:2 row_mask:0xf bank_mask:0xf
	v_add_f32_e32 v72, 1.0, v72
	v_pk_fma_f32 v[74:75], v[98:99], v[76:77], v[74:75]
	v_add_f32_e32 v73, 1.0, v73
	v_mov_b32_dpp v84, v70 row_ror:1 row_mask:0xf bank_mask:0xf
	v_mov_b32_dpp v88, v71 row_ror:1 row_mask:0xf bank_mask:0xf
	v_rcp_f32_e32 v72, v72
	v_pk_fma_f32 v[64:65], v[64:65], v[102:103], v[74:75]
	v_rcp_f32_e32 v73, v73
	v_cndmask_b32_e32 v75, v80, v138, vcc
	v_cndmask_b32_e32 v74, v85, v134, vcc
	v_pk_mul_f32 v[74:75], v[128:129], v[74:75]
	v_cndmask_b32_e64 v77, v88, v137, s[38:39]
	v_cndmask_b32_e64 v76, v84, v133, s[38:39]
	v_pk_fma_f32 v[74:75], v[120:121], v[76:77], v[74:75]
	v_pk_add_f32 v[64:65], v[106:107], v[64:65]
	v_pk_fma_f32 v[70:71], v[70:71], v[116:117], v[74:75]
	v_pk_mul_f32 v[68:69], v[68:69], v[72:73]
	v_pk_add_f32 v[70:71], v[124:125], v[70:71]
	v_pk_mul_f32 v[64:65], v[64:65], v[68:69]
	v_mul_f32_e32 v74, 0xbfb8aa3b, v70
	v_mul_f32_e32 v69, 0xbfb8aa3b, v71
	v_exp_f32_e32 v74, v74
	v_exp_f32_e32 v69, v69
	v_mov_b32_dpp v87, v66 row_ror:2 row_mask:0xf bank_mask:0xf
	v_mov_b32_dpp v90, v67 row_ror:2 row_mask:0xf bank_mask:0xf
	v_add_f32_e32 v68, 1.0, v74
	v_add_f32_e32 v69, 1.0, v69
	v_mov_b32_dpp v86, v66 row_ror:1 row_mask:0xf bank_mask:0xf
	v_mov_b32_dpp v89, v67 row_ror:1 row_mask:0xf bank_mask:0xf
	v_rcp_f32_e32 v68, v68
	v_cndmask_b32_e32 v73, v90, v140, vcc
	v_cndmask_b32_e32 v72, v87, v136, vcc
	v_rcp_f32_e32 v69, v69
	v_pk_mul_f32 v[72:73], v[112:113], v[72:73]
	v_cndmask_b32_e64 v75, v89, v139, s[38:39]
	v_cndmask_b32_e64 v74, v86, v135, s[38:39]
	v_pk_fma_f32 v[72:73], v[100:101], v[74:75], v[72:73]
	v_pk_mul_f32 v[68:69], v[70:71], v[68:69]
	v_pk_fma_f32 v[66:67], v[66:67], v[104:105], v[72:73]
	s_nop 0
	v_pk_add_f32 v[66:67], v[108:109], v[66:67]
	s_nop 0
	v_pk_mul_f32 v[66:67], v[66:67], v[68:69]
	s_nop 0
	v_cvt_pk_bf16_f32 v67, v66, v67
	v_cvt_pk_bf16_f32 v66, v64, v65
	v_lshl_add_u64 v[64:65], s[20:21], 0, v[82:83]
	global_store_dwordx2 v[64:65], v[66:67], off
	s_add_i32 s70, s63, 0x80
	s_ashr_i32 s12, s70, 6
	s_mul_hi_i32 s3, s12, 0xb000
	s_mul_i32 s12, s12, 0xb000
	s_and_saveexec_b64 s[4:5], vcc
	s_cbranch_execz .LBB0_572
	s_add_u32 s20, s94, s12
	v_readlane_b32 s13, v255, 43
	s_addc_u32 s21, s13, s3
	s_movk_i32 s13, 0x1600
	v_mad_u64_u32 v[68:69], s[80:81], v189, s13, v[186:187]
	v_mov_b32_e32 v69, v81
	v_cvt_pk_bf16_f32 v64, v60, v61
	v_cvt_pk_bf16_f32 v65, v62, v63
	v_cvt_pk_bf16_f32 v66, v28, v29
	v_cvt_pk_bf16_f32 v67, v30, v31
	v_lshl_add_u64 v[70:71], v[68:69], 1, s[20:21]
	v_add_u32_e32 v80, 0x80, v68
	global_store_dwordx4 v[70:71], v[64:67], off sc0 sc1
	v_lshl_add_u64 v[68:69], v[80:81], 1, s[20:21]
	s_nop 0
	v_cvt_pk_bf16_f32 v64, v56, v57
	v_cvt_pk_bf16_f32 v65, v58, v59
	v_cvt_pk_bf16_f32 v66, v24, v25
	v_cvt_pk_bf16_f32 v67, v26, v27
	global_store_dwordx4 v[68:69], v[64:67], off sc0 sc1
.LBB0_572:
	s_or_b64 exec, exec, s[4:5]
	s_and_saveexec_b64 s[4:5], s[42:43]
	s_cbranch_execz .LBB0_574
	s_add_u32 s12, s94, s12
	v_readlane_b32 s13, v255, 43
	s_addc_u32 s13, s13, s3
	s_movk_i32 s3, 0x1600
	v_mad_u64_u32 v[68:69], s[20:21], v223, s3, v[186:187]
	v_mov_b32_e32 v69, v81
	v_cvt_pk_bf16_f32 v64, v36, v37
	v_cvt_pk_bf16_f32 v65, v38, v39
	v_cvt_pk_bf16_f32 v66, v4, v5
	v_cvt_pk_bf16_f32 v67, v6, v7
	v_lshl_add_u64 v[70:71], v[68:69], 1, s[12:13]
	v_add_u32_e32 v80, 0x80, v68
	global_store_dwordx4 v[70:71], v[64:67], off sc0 sc1
	v_lshl_add_u64 v[68:69], v[80:81], 1, s[12:13]
	s_nop 0
	v_cvt_pk_bf16_f32 v64, v32, v33
	v_cvt_pk_bf16_f32 v65, v34, v35
	v_cvt_pk_bf16_f32 v66, v0, v1
	v_cvt_pk_bf16_f32 v67, v2, v3
	global_store_dwordx4 v[68:69], v[64:67], off sc0 sc1

; __device__ __forceinline__ unsigned cvt_pk_bf16(float lo, float hi) { f32x2_cv v = {lo, hi}; bf16x2_cv b = __builtin_convertvector(v, bf16x2_cv); return __builtin_bit_cast(unsigned, b); }
;     __device__ __forceinline__ void operator()(const f32x4 (&acc)[2][2][4][2], const Unit& u, int wr, int wc, int fr, int fq) const {
;         const int row0 = u.pm * BM + wr * 64 + fr; const int col0 = u.pn * BM + wc * 32 + 8 * fq;
;         const int b = (u.pm * BM) >> 12;
;         f32x4 gv[2][2];
; #pragma unroll
;         for (int bj = 0; bj < 2; ++bj)
; #pragma unroll
;             for (int n = 0; n < 2; ++n) gv[bj][n] = *(const f32x4*)(gate + (size_t)b * gate_ld + col0 + bj * HALF + n * 4);
;         f32x4 xv[2][2][2];
;         load_x(xv[0], (size_t)row0 * 1024 + col0);
; #pragma unroll
;         for (int g = 0; g < 8; ++g) { const int ai = g >> 2, m = g & 3; const size_t off = (size_t)(row0 + ai * HALF + m * 16) * 1024 + col0;
;             if (g + 1 < 8) { const int ai2 = (g + 1) >> 2, m2 = (g + 1) & 3; load_x(xv[(g + 1) & 1], (size_t)(row0 + ai2 * HALF + m2 * 16) * 1024 + col0); }
;             float rs_ = 1.0f; if constexpr (ROWSCALE) rs_ = tab[((u.pm == pm0 ? 0 : 256) + ai * HALF + wr * 64 + m * 16 + fr) * 2 + 1];
; #pragma unroll
;             for (int bj = 0; bj < 2; ++bj) { const f32x4 v0 = xv[g & 1][bj][0] + gv[bj][0] * (acc[ai][bj][m][0] * rs_), v1 = xv[g & 1][bj][1] + gv[bj][1] * (acc[ai][bj][m][1] * rs_);
;                 u32x4 w; w.x = cvt_pk_bf16(v0[0], v0[1]); w.y = cvt_pk_bf16(v0[2], v0[3]); w.z = cvt_pk_bf16(v1[0], v1[1]); w.w = cvt_pk_bf16(v1[2], v1[3]);
;                 *(u32x4*)(out + off + bj * HALF) = w; } }
.LBB0_708:
	s_ashr_i32 s3, s65, 4
	s_mul_hi_i32 s5, s3, 0x6000
	s_mulk_i32 s3, 0x6000
	s_add_u32 s4, s57, s3
	s_addc_u32 s5, s58, s5
	v_lshl_or_b32 v213, s66, 8, v194
	v_lshlrev_b32_e32 v220, 2, v213
	global_load_dwordx4 v[60:63], v220, s[4:5]
	global_load_dwordx4 v[56:59], v220, s[4:5] offset:16
	global_load_dwordx4 v[52:55], v220, s[4:5] offset:512
	global_load_dwordx4 v[48:51], v220, s[4:5] offset:528
	v_lshlrev_b32_e32 v212, 11, v192
	v_lshl_add_u32 v212, v213, 1, v212
	s_lshl_b32 s3, s65, 19
	s_add_u32 s98, s40, s3
	s_addc_u32 s99, s41, 0
	s_mov_b64 s[100:101], s[98:99]
	global_load_dwordx4 v[156:159], v212, s[98:99]
	global_load_dwordx4 v[176:179], v212, s[98:99] offset:256
	s_add_u32 s98, s98, 0x8000
	s_addc_u32 s99, s99, 0
	global_load_dwordx4 v[180:183], v212, s[98:99]
	global_load_dwordx4 v[184:187], v212, s[98:99] offset:256
	s_add_u32 s98, s98, 0x8000
	s_addc_u32 s99, s99, 0
	global_load_dwordx4 v[188:191], v212, s[98:99]
	global_load_dwordx4 v[196:199], v212, s[98:99] offset:256
	s_add_u32 s98, s98, 0x8000
	s_addc_u32 s99, s99, 0
	global_load_dwordx4 v[200:203], v212, s[98:99]
	global_load_dwordx4 v[224:227], v212, s[98:99] offset:256
	s_add_u32 s98, s98, 0x28000
	s_addc_u32 s99, s99, 0
	global_load_dwordx4 v[228:231], v212, s[98:99]
	global_load_dwordx4 v[232:235], v212, s[98:99] offset:256
	s_add_u32 s98, s98, 0x8000
	s_addc_u32 s99, s99, 0
	s_waitcnt vmcnt(8)
	v_lshlrev_b32_e32 v160, 16, v156
	v_and_b32_e32 v161, 0xffff0000, v156
	v_lshlrev_b32_e32 v174, 16, v157
	v_and_b32_e32 v175, 0xffff0000, v157
	v_lshlrev_b32_e32 v204, 16, v158
	v_and_b32_e32 v205, 0xffff0000, v158
	v_lshlrev_b32_e32 v210, 16, v159
	v_and_b32_e32 v211, 0xffff0000, v159
	v_pk_fma_f32 v[142:143], v[142:143], v[60:61], v[160:161]
	v_pk_fma_f32 v[144:145], v[144:145], v[62:63], v[174:175]
	v_pk_fma_f32 v[138:139], v[138:139], v[56:57], v[204:205]
	v_pk_fma_f32 v[140:141], v[140:141], v[58:59], v[210:211]
	v_cvt_pk_bf16_f32 v156, v142, v143
	v_cvt_pk_bf16_f32 v157, v144, v145
	v_cvt_pk_bf16_f32 v158, v138, v139
	v_cvt_pk_bf16_f32 v159, v140, v141
	global_store_dwordx4 v212, v[156:159], s[100:101] sc0 sc1
	v_lshlrev_b32_e32 v160, 16, v176
	v_and_b32_e32 v161, 0xffff0000, v176
	v_lshlrev_b32_e32 v174, 16, v177
	v_and_b32_e32 v175, 0xffff0000, v177
	v_lshlrev_b32_e32 v204, 16, v178
	v_and_b32_e32 v205, 0xffff0000, v178
	v_lshlrev_b32_e32 v210, 16, v179
	v_and_b32_e32 v211, 0xffff0000, v179
	v_pk_fma_f32 v[134:135], v[134:135], v[52:53], v[160:161]
	v_pk_fma_f32 v[136:137], v[136:137], v[54:55], v[174:175]
	v_pk_fma_f32 v[130:131], v[130:131], v[48:49], v[204:205]
	v_pk_fma_f32 v[132:133], v[132:133], v[50:51], v[210:211]
	v_cvt_pk_bf16_f32 v176, v134, v135
	v_cvt_pk_bf16_f32 v177, v136, v137
	v_cvt_pk_bf16_f32 v178, v130, v131
	v_cvt_pk_bf16_f32 v179, v132, v133
	global_store_dwordx4 v212, v[176:179], s[100:101] offset:256 sc0 sc1
	s_add_u32 s100, s100, 0x8000
	s_addc_u32 s101, s101, 0
	global_load_dwordx4 v[156:159], v212, s[98:99]
	global_load_dwordx4 v[176:179], v212, s[98:99] offset:256
	s_add_u32 s98, s98, 0x8000
	s_addc_u32 s99, s99, 0
	s_waitcnt vmcnt(10)
	v_lshlrev_b32_e32 v160, 16, v180
	v_and_b32_e32 v161, 0xffff0000, v180
	v_lshlrev_b32_e32 v174, 16, v181
	v_and_b32_e32 v175, 0xffff0000, v181
	v_lshlrev_b32_e32 v204, 16, v182
	v_and_b32_e32 v205, 0xffff0000, v182
	v_lshlrev_b32_e32 v210, 16, v183
	v_and_b32_e32 v211, 0xffff0000, v183
	v_pk_fma_f32 v[126:127], v[126:127], v[60:61], v[160:161]
	v_pk_fma_f32 v[128:129], v[128:129], v[62:63], v[174:175]
	v_pk_fma_f32 v[122:123], v[122:123], v[56:57], v[204:205]
	v_pk_fma_f32 v[124:125], v[124:125], v[58:59], v[210:211]
	v_cvt_pk_bf16_f32 v180, v126, v127
	v_cvt_pk_bf16_f32 v181, v128, v129
	v_cvt_pk_bf16_f32 v182, v122, v123
	v_cvt_pk_bf16_f32 v183, v124, v125
	global_store_dwordx4 v212, v[180:183], s[100:101] sc0 sc1
	v_lshlrev_b32_e32 v160, 16, v184
	v_and_b32_e32 v161, 0xffff0000, v184
	v_lshlrev_b32_e32 v174, 16, v185
	v_and_b32_e32 v175, 0xffff0000, v185
	v_lshlrev_b32_e32 v204, 16, v186
	v_and_b32_e32 v205, 0xffff0000, v186
	v_lshlrev_b32_e32 v210, 16, v187
	v_and_b32_e32 v211, 0xffff0000, v187
	v_pk_fma_f32 v[118:119], v[118:119], v[52:53], v[160:161]
	v_pk_fma_f32 v[120:121], v[120:121], v[54:55], v[174:175]
	v_pk_fma_f32 v[114:115], v[114:115], v[48:49], v[204:205]
	v_pk_fma_f32 v[116:117], v[116:117], v[50:51], v[210:211]
	v_cvt_pk_bf16_f32 v184, v118, v119
	v_cvt_pk_bf16_f32 v185, v120, v121
	v_cvt_pk_bf16_f32 v186, v114, v115
	v_cvt_pk_bf16_f32 v187, v116, v117
	global_store_dwordx4 v212, v[184:187], s[100:101] offset:256 sc0 sc1
	s_add_u32 s100, s100, 0x8000
	s_addc_u32 s101, s101, 0
	global_load_dwordx4 v[180:183], v212, s[98:99]
	global_load_dwordx4 v[184:187], v212, s[98:99] offset:256
	s_add_u32 s98, s98, 0x8000
	s_addc_u32 s99, s99, 0
	s_waitcnt vmcnt(12)
; __device__ __forceinline__ unsigned cvt_pk_bf16(float lo, float hi) { f32x2_cv v = {lo, hi}; bf16x2_cv b = __builtin_convertvector(v, bf16x2_cv); return __builtin_bit_cast(unsigned, b); }
;     __device__ __forceinline__ void load_x(f32x4 (&x)[2][2], size_t off) const {
;     ...
;             else { const u32x4 w = *(const u32x4*)((const bf16_t*)xin + off + bj * HALF);
;                 x[bj][0] = (f32x4){__builtin_bit_cast(float, w.x << 16), __builtin_bit_cast(float, w.x & 0xffff0000u), __builtin_bit_cast(float, w.y << 16), __builtin_bit_cast(float, w.y & 0xffff0000u)};
;                 x[bj][1] = (f32x4){__builtin_bit_cast(float, w.z << 16), __builtin_bit_cast(float, w.z & 0xffff0000u), __builtin_bit_cast(float, w.w << 16), __builtin_bit_cast(float, w.w & 0xffff0000u)}; } }
;     }
;     __device__ __forceinline__ void operator()(const f32x4 (&acc)[2][2][4][2], const Unit& u, int wr, int wc, int fr, int fq) const {
;         const int row0 = u.pm * BM + wr * 64 + fr; const int col0 = u.pn * BM + wc * 32 + 8 * fq;
;         const int b = (u.pm * BM) >> 12;
;         f32x4 gv[2][2];
; #pragma unroll
;         for (int bj = 0; bj < 2; ++bj)
; #pragma unroll
;             for (int n = 0; n < 2; ++n) gv[bj][n] = *(const f32x4*)(gate + (size_t)b * gate_ld + col0 + bj * HALF + n * 4);
;         f32x4 xv[2][2][2];
;         load_x(xv[0], (size_t)row0 * 1024 + col0);
; #pragma unroll
;         for (int g = 0; g < 8; ++g) { const int ai = g >> 2, m = g & 3; const size_t off = (size_t)(row0 + ai * HALF + m * 16) * 1024 + col0;
;             if (g + 1 < 8) { const int ai2 = (g + 1) >> 2, m2 = (g + 1) & 3; load_x(xv[(g + 1) & 1], (size_t)(row0 + ai2 * HALF + m2 * 16) * 1024 + col0); }
;             float rs_ = 1.0f; if constexpr (ROWSCALE) rs_ = tab[((u.pm == pm0 ? 0 : 256) + ai * HALF + wr * 64 + m * 16 + fr) * 2 + 1];
; #pragma unroll
;             for (int bj = 0; bj < 2; ++bj) { const f32x4 v0 = xv[g & 1][bj][0] + gv[bj][0] * (acc[ai][bj][m][0] * rs_), v1 = xv[g & 1][bj][1] + gv[bj][1] * (acc[ai][bj][m][1] * rs_);
;                 u32x4 w; w.x = cvt_pk_bf16(v0[0], v0[1]); w.y = cvt_pk_bf16(v0[2], v0[3]); w.z = cvt_pk_bf16(v1[0], v1[1]); w.w = cvt_pk_bf16(v1[2], v1[3]);
;                 *(u32x4*)(out + off + bj * HALF) = w; } }
	v_lshlrev_b32_e32 v160, 16, v188
	v_and_b32_e32 v161, 0xffff0000, v188
	v_lshlrev_b32_e32 v174, 16, v189
	v_and_b32_e32 v175, 0xffff0000, v189
	v_lshlrev_b32_e32 v204, 16, v190
	v_and_b32_e32 v205, 0xffff0000, v190
	v_lshlrev_b32_e32 v210, 16, v191
	v_and_b32_e32 v211, 0xffff0000, v191
	v_pk_fma_f32 v[110:111], v[110:111], v[60:61], v[160:161]
	v_pk_fma_f32 v[112:113], v[112:113], v[62:63], v[174:175]
	v_pk_fma_f32 v[106:107], v[106:107], v[56:57], v[204:205]
	v_pk_fma_f32 v[108:109], v[108:109], v[58:59], v[210:211]
	v_cvt_pk_bf16_f32 v188, v110, v111
	v_cvt_pk_bf16_f32 v189, v112, v113
	v_cvt_pk_bf16_f32 v190, v106, v107
	v_cvt_pk_bf16_f32 v191, v108, v109
	global_store_dwordx4 v212, v[188:191], s[100:101] sc0 sc1
	v_lshlrev_b32_e32 v160, 16, v196
	v_and_b32_e32 v161, 0xffff0000, v196
	v_lshlrev_b32_e32 v174, 16, v197
	v_and_b32_e32 v175, 0xffff0000, v197
	v_lshlrev_b32_e32 v204, 16, v198
	v_and_b32_e32 v205, 0xffff0000, v198
	v_lshlrev_b32_e32 v210, 16, v199
	v_and_b32_e32 v211, 0xffff0000, v199
	v_pk_fma_f32 v[102:103], v[102:103], v[52:53], v[160:161]
	v_pk_fma_f32 v[104:105], v[104:105], v[54:55], v[174:175]
	v_pk_fma_f32 v[98:99], v[98:99], v[48:49], v[204:205]
	v_pk_fma_f32 v[100:101], v[100:101], v[50:51], v[210:211]
	v_cvt_pk_bf16_f32 v196, v102, v103
	v_cvt_pk_bf16_f32 v197, v104, v105
	v_cvt_pk_bf16_f32 v198, v98, v99
	v_cvt_pk_bf16_f32 v199, v100, v101
	global_store_dwordx4 v212, v[196:199], s[100:101] offset:256 sc0 sc1
	s_add_u32 s100, s100, 0x8000
	s_addc_u32 s101, s101, 0
	global_load_dwordx4 v[188:191], v212, s[98:99]
	global_load_dwordx4 v[196:199], v212, s[98:99] offset:256
	s_add_u32 s98, s98, 0x8000
	s_addc_u32 s99, s99, 0
	s_waitcnt vmcnt(14)
	v_lshlrev_b32_e32 v160, 16, v200
	v_and_b32_e32 v161, 0xffff0000, v200
	v_lshlrev_b32_e32 v174, 16, v201
	v_and_b32_e32 v175, 0xffff0000, v201
	v_lshlrev_b32_e32 v204, 16, v202
	v_and_b32_e32 v205, 0xffff0000, v202
	v_lshlrev_b32_e32 v210, 16, v203
	v_and_b32_e32 v211, 0xffff0000, v203
	v_pk_fma_f32 v[94:95], v[94:95], v[60:61], v[160:161]
	v_pk_fma_f32 v[96:97], v[96:97], v[62:63], v[174:175]
	v_pk_fma_f32 v[90:91], v[90:91], v[56:57], v[204:205]
	v_pk_fma_f32 v[92:93], v[92:93], v[58:59], v[210:211]
	v_cvt_pk_bf16_f32 v200, v94, v95
	v_cvt_pk_bf16_f32 v201, v96, v97
	v_cvt_pk_bf16_f32 v202, v90, v91
	v_cvt_pk_bf16_f32 v203, v92, v93
	global_store_dwordx4 v212, v[200:203], s[100:101] sc0 sc1
	v_lshlrev_b32_e32 v160, 16, v224
	v_and_b32_e32 v161, 0xffff0000, v224
	v_lshlrev_b32_e32 v174, 16, v225
	v_and_b32_e32 v175, 0xffff0000, v225
	v_lshlrev_b32_e32 v204, 16, v226
	v_and_b32_e32 v205, 0xffff0000, v226
	v_lshlrev_b32_e32 v210, 16, v227
	v_and_b32_e32 v211, 0xffff0000, v227
	v_pk_fma_f32 v[86:87], v[86:87], v[52:53], v[160:161]
	v_pk_fma_f32 v[88:89], v[88:89], v[54:55], v[174:175]
	v_pk_fma_f32 v[82:83], v[82:83], v[48:49], v[204:205]
	v_pk_fma_f32 v[84:85], v[84:85], v[50:51], v[210:211]
	v_cvt_pk_bf16_f32 v224, v86, v87
	v_cvt_pk_bf16_f32 v225, v88, v89
	v_cvt_pk_bf16_f32 v226, v82, v83
	v_cvt_pk_bf16_f32 v227, v84, v85
	global_store_dwordx4 v212, v[224:227], s[100:101] offset:256 sc0 sc1
	s_add_u32 s100, s100, 0x28000
	s_addc_u32 s101, s101, 0
	s_waitcnt vmcnt(14)
	v_lshlrev_b32_e32 v160, 16, v228
	v_and_b32_e32 v161, 0xffff0000, v228
	v_lshlrev_b32_e32 v174, 16, v229
	v_and_b32_e32 v175, 0xffff0000, v229
	v_lshlrev_b32_e32 v204, 16, v230
	v_and_b32_e32 v205, 0xffff0000, v230
	v_lshlrev_b32_e32 v210, 16, v231
	v_and_b32_e32 v211, 0xffff0000, v231
	v_pk_fma_f32 v[76:77], v[76:77], v[60:61], v[160:161]
	v_pk_fma_f32 v[78:79], v[78:79], v[62:63], v[174:175]
	v_pk_fma_f32 v[72:73], v[72:73], v[56:57], v[204:205]
	v_pk_fma_f32 v[74:75], v[74:75], v[58:59], v[210:211]
	v_cvt_pk_bf16_f32 v228, v76, v77
	v_cvt_pk_bf16_f32 v229, v78, v79
	v_cvt_pk_bf16_f32 v230, v72, v73
	v_cvt_pk_bf16_f32 v231, v74, v75
	global_store_dwordx4 v212, v[228:231], s[100:101] sc0 sc1
	v_lshlrev_b32_e32 v160, 16, v232
	v_and_b32_e32 v161, 0xffff0000, v232
	v_lshlrev_b32_e32 v174, 16, v233
	v_and_b32_e32 v175, 0xffff0000, v233
	v_lshlrev_b32_e32 v204, 16, v234
	v_and_b32_e32 v205, 0xffff0000, v234
	v_lshlrev_b32_e32 v210, 16, v235
	v_and_b32_e32 v211, 0xffff0000, v235
	v_pk_fma_f32 v[68:69], v[68:69], v[52:53], v[160:161]
	v_pk_fma_f32 v[70:71], v[70:71], v[54:55], v[174:175]
	v_pk_fma_f32 v[64:65], v[64:65], v[48:49], v[204:205]
	v_pk_fma_f32 v[66:67], v[66:67], v[50:51], v[210:211]
	v_cvt_pk_bf16_f32 v232, v68, v69
	v_cvt_pk_bf16_f32 v233, v70, v71
	v_cvt_pk_bf16_f32 v234, v64, v65
	v_cvt_pk_bf16_f32 v235, v66, v67
	global_store_dwordx4 v212, v[232:235], s[100:101] offset:256 sc0 sc1
	s_add_u32 s100, s100, 0x8000
	s_addc_u32 s101, s101, 0
	s_waitcnt vmcnt(12)
; __device__ __forceinline__ unsigned cvt_pk_bf16(float lo, float hi) { f32x2_cv v = {lo, hi}; bf16x2_cv b = __builtin_convertvector(v, bf16x2_cv); return __builtin_bit_cast(unsigned, b); }
; #define PG8_BAR __builtin_amdgcn_s_barrier()
;     __device__ __forceinline__ void operator()(const f32x4 (&acc)[2][2][4][2], const Unit& u, int wr, int wc, int fr, int fq) const {
;     ...
;         for (int g = 0; g < 8; ++g) { const int ai = g >> 2, m = g & 3; const size_t off = (size_t)(row0 + ai * HALF + m * 16) * 1024 + col0;
;             if (g + 1 < 8) { const int ai2 = (g + 1) >> 2, m2 = (g + 1) & 3; load_x(xv[(g + 1) & 1], (size_t)(row0 + ai2 * HALF + m2 * 16) * 1024 + col0); }
;             float rs_ = 1.0f; if constexpr (ROWSCALE) rs_ = tab[((u.pm == pm0 ? 0 : 256) + ai * HALF + wr * 64 + m * 16 + fr) * 2 + 1];
; #pragma unroll
;             for (int bj = 0; bj < 2; ++bj) { const f32x4 v0 = xv[g & 1][bj][0] + gv[bj][0] * (acc[ai][bj][m][0] * rs_), v1 = xv[g & 1][bj][1] + gv[bj][1] * (acc[ai][bj][m][1] * rs_);
;                 u32x4 w; w.x = cvt_pk_bf16(v0[0], v0[1]); w.y = cvt_pk_bf16(v0[2], v0[3]); w.z = cvt_pk_bf16(v1[0], v1[1]); w.w = cvt_pk_bf16(v1[2], v1[3]);
;                 *(u32x4*)(out + off + bj * HALF) = w; } }
; template <class Epi, class Sched, bool ALIGN_EPI = false, bool SP2 = false, bool MID = false>
; __device__ __forceinline__ void gemm_phase(PG8_LAS unsigned char* lds, const Gemm g, const Sched& S, const Epi& E, const PG8_LAS float* mid = nullptr) {
;     ...
;         if constexpr (ALIGN_EPI) { if (wr == 0) PG8_BAR; }
;         if constexpr (!Epi::AFTER_DRAIN) { E(acc, cur, wr, wc, fr, fq); S.done(cur); }
;         if (!has_next) break;
; #pragma unroll
;         for (int a = 0; a < 2; ++a)
; #pragma unroll
;             for (int b = 0; b < 2; ++b)
; #pragma unroll
;                 for (int m = 0; m < 4; ++m)
; #pragma unroll
;                     for (int n = 0; n < 2; ++n) acc[a][b][m][n] = (f32x4){0.f, 0.f, 0.f, 0.f};
;         cur = nxt; cA = nA; cB = nB; ++ui;
;         if constexpr (ALIGN_EPI) { if (wr == 1) PG8_BAR; }
	v_lshlrev_b32_e32 v160, 16, v156
	v_and_b32_e32 v161, 0xffff0000, v156
	v_lshlrev_b32_e32 v174, 16, v157
	v_and_b32_e32 v175, 0xffff0000, v157
	v_lshlrev_b32_e32 v204, 16, v158
	v_and_b32_e32 v205, 0xffff0000, v158
	v_lshlrev_b32_e32 v210, 16, v159
	v_and_b32_e32 v211, 0xffff0000, v159
	v_pk_fma_f32 v[44:45], v[44:45], v[60:61], v[160:161]
	v_pk_fma_f32 v[46:47], v[46:47], v[62:63], v[174:175]
	v_pk_fma_f32 v[40:41], v[40:41], v[56:57], v[204:205]
	v_pk_fma_f32 v[42:43], v[42:43], v[58:59], v[210:211]
	v_cvt_pk_bf16_f32 v156, v44, v45
	v_cvt_pk_bf16_f32 v157, v46, v47
	v_cvt_pk_bf16_f32 v158, v40, v41
	v_cvt_pk_bf16_f32 v159, v42, v43
	global_store_dwordx4 v212, v[156:159], s[100:101] sc0 sc1
	v_lshlrev_b32_e32 v160, 16, v176
	v_and_b32_e32 v161, 0xffff0000, v176
	v_lshlrev_b32_e32 v174, 16, v177
	v_and_b32_e32 v175, 0xffff0000, v177
	v_lshlrev_b32_e32 v204, 16, v178
	v_and_b32_e32 v205, 0xffff0000, v178
	v_lshlrev_b32_e32 v210, 16, v179
	v_and_b32_e32 v211, 0xffff0000, v179
	v_pk_fma_f32 v[36:37], v[36:37], v[52:53], v[160:161]
	v_pk_fma_f32 v[38:39], v[38:39], v[54:55], v[174:175]
	v_pk_fma_f32 v[32:33], v[32:33], v[48:49], v[204:205]
	v_pk_fma_f32 v[34:35], v[34:35], v[50:51], v[210:211]
	v_cvt_pk_bf16_f32 v176, v36, v37
	v_cvt_pk_bf16_f32 v177, v38, v39
	v_cvt_pk_bf16_f32 v178, v32, v33
	v_cvt_pk_bf16_f32 v179, v34, v35
	global_store_dwordx4 v212, v[176:179], s[100:101] offset:256 sc0 sc1
	s_add_u32 s100, s100, 0x8000
	s_addc_u32 s101, s101, 0
	s_waitcnt vmcnt(10)
	v_lshlrev_b32_e32 v160, 16, v180
	v_and_b32_e32 v161, 0xffff0000, v180
	v_lshlrev_b32_e32 v174, 16, v181
	v_and_b32_e32 v175, 0xffff0000, v181
	v_lshlrev_b32_e32 v204, 16, v182
	v_and_b32_e32 v205, 0xffff0000, v182
	v_lshlrev_b32_e32 v210, 16, v183
	v_and_b32_e32 v211, 0xffff0000, v183
	v_pk_fma_f32 v[28:29], v[28:29], v[60:61], v[160:161]
	v_pk_fma_f32 v[30:31], v[30:31], v[62:63], v[174:175]
	v_pk_fma_f32 v[24:25], v[24:25], v[56:57], v[204:205]
	v_pk_fma_f32 v[26:27], v[26:27], v[58:59], v[210:211]
	v_cvt_pk_bf16_f32 v180, v28, v29
	v_cvt_pk_bf16_f32 v181, v30, v31
	v_cvt_pk_bf16_f32 v182, v24, v25
	v_cvt_pk_bf16_f32 v183, v26, v27
	global_store_dwordx4 v212, v[180:183], s[100:101] sc0 sc1
	v_lshlrev_b32_e32 v160, 16, v184
	v_and_b32_e32 v161, 0xffff0000, v184
	v_lshlrev_b32_e32 v174, 16, v185
	v_and_b32_e32 v175, 0xffff0000, v185
	v_lshlrev_b32_e32 v204, 16, v186
	v_and_b32_e32 v205, 0xffff0000, v186
	v_lshlrev_b32_e32 v210, 16, v187
	v_and_b32_e32 v211, 0xffff0000, v187
	v_pk_fma_f32 v[20:21], v[20:21], v[52:53], v[160:161]
	v_pk_fma_f32 v[22:23], v[22:23], v[54:55], v[174:175]
	v_pk_fma_f32 v[16:17], v[16:17], v[48:49], v[204:205]
	v_pk_fma_f32 v[18:19], v[18:19], v[50:51], v[210:211]
	v_cvt_pk_bf16_f32 v184, v20, v21
	v_cvt_pk_bf16_f32 v185, v22, v23
	v_cvt_pk_bf16_f32 v186, v16, v17
	v_cvt_pk_bf16_f32 v187, v18, v19
	global_store_dwordx4 v212, v[184:187], s[100:101] offset:256 sc0 sc1
	s_add_u32 s100, s100, 0x8000
	s_addc_u32 s101, s101, 0
	s_waitcnt vmcnt(8)
	v_lshlrev_b32_e32 v160, 16, v188
	v_and_b32_e32 v161, 0xffff0000, v188
	v_lshlrev_b32_e32 v174, 16, v189
	v_and_b32_e32 v175, 0xffff0000, v189
	v_lshlrev_b32_e32 v204, 16, v190
	v_and_b32_e32 v205, 0xffff0000, v190
	v_lshlrev_b32_e32 v210, 16, v191
	v_and_b32_e32 v211, 0xffff0000, v191
	v_pk_fma_f32 v[12:13], v[12:13], v[60:61], v[160:161]
	v_pk_fma_f32 v[14:15], v[14:15], v[62:63], v[174:175]
	v_pk_fma_f32 v[8:9], v[8:9], v[56:57], v[204:205]
	v_pk_fma_f32 v[10:11], v[10:11], v[58:59], v[210:211]
	v_cvt_pk_bf16_f32 v188, v12, v13
	v_cvt_pk_bf16_f32 v189, v14, v15
	v_cvt_pk_bf16_f32 v190, v8, v9
	v_cvt_pk_bf16_f32 v191, v10, v11
	global_store_dwordx4 v212, v[188:191], s[100:101] sc0 sc1
	v_lshlrev_b32_e32 v160, 16, v196
	v_and_b32_e32 v161, 0xffff0000, v196
	v_lshlrev_b32_e32 v174, 16, v197
	v_and_b32_e32 v175, 0xffff0000, v197
	v_lshlrev_b32_e32 v204, 16, v198
	v_and_b32_e32 v205, 0xffff0000, v198
	v_lshlrev_b32_e32 v210, 16, v199
	v_and_b32_e32 v211, 0xffff0000, v199
	v_pk_fma_f32 v[4:5], v[4:5], v[52:53], v[160:161]
	v_pk_fma_f32 v[6:7], v[6:7], v[54:55], v[174:175]
	v_pk_fma_f32 v[0:1], v[0:1], v[48:49], v[204:205]
	v_pk_fma_f32 v[2:3], v[2:3], v[50:51], v[210:211]
	v_cvt_pk_bf16_f32 v196, v4, v5
	v_cvt_pk_bf16_f32 v197, v6, v7
	v_cvt_pk_bf16_f32 v198, v0, v1
	v_cvt_pk_bf16_f32 v199, v2, v3
	global_store_dwordx4 v212, v[196:199], s[100:101] offset:256 sc0 sc1
	s_add_u32 s100, s100, 0x8000
	s_addc_u32 s101, s101, 0
	s_mov_b64 s[4:5], -1
	s_and_b64 vcc, exec, s[36:37]
	s_cbranch_vccnz .LBB0_693
	s_andn2_b64 vcc, exec, s[14:15]
	s_cbranch_vccnz .LBB0_692
	s_barrier
	s_branch .LBB0_692
